# S3: S1 + K-loop load segments VALU-free: loop-invariant LDS read-address v_add_u32 pairs replaced by one per-unit v250=base+0x10000 and immediate offsets (42 adds removed, 168 ds_reads retargeted)
# baseline (speedup 1.0000x reference)
.Ldefbar_skip_0:
	v_add_u32_e32 v250, 0x10000, v141
	s_add_i32 s69, s8, 2
	s_add_u32 s0, s52, 0xfff80080
	s_addc_u32 s1, s53, -1
	s_add_i32 s70, 0, 0x10000
	s_cmp_eq_u32 s66, s8
	s_cselect_b32 s59, s41, s1
	s_cselect_b32 s58, s45, s0
	s_cselect_b32 s9, s43, s68
	s_cselect_b32 s8, s65, s67
	s_add_i32 s0, 0, 0x14000
	ds_read_b128 v[144:147], v250
	ds_read_b128 v[148:151], v250 offset:1024
	ds_read_b128 v[152:155], v250 offset:2048
	ds_read_b128 v[156:159], v250 offset:3072
	ds_read_b128 v[160:163], v250 offset:16384
	ds_read_b128 v[164:167], v250 offset:17408
	ds_read_b128 v[168:171], v250 offset:18432
	ds_read_b128 v[172:175], v250 offset:19456
	s_add_i32 m0, s27, 0xc000
	ds_read_b128 v[176:179], v143
	ds_read_b128 v[180:183], v143 offset:1024
	ds_read_b128 v[184:187], v143 offset:2048
	ds_read_b128 v[188:191], v143 offset:3072
	ds_read_b128 v[192:195], v143 offset:4096
	ds_read_b128 v[202:205], v143 offset:5120
	ds_read_b128 v[206:209], v143 offset:6144
	ds_read_b128 v[210:213], v143 offset:7168
	global_load_lds_dwordx4 v138, s[52:53]
	s_add_i32 m0, s27, 0xe000
	s_nop 0
	global_load_lds_dwordx4 v136, s[52:53]
	s_waitcnt vmcnt(8)
	s_waitcnt lgkmcnt(0)
	s_setprio 1
	s_barrier
	v_mfma_f32_16x16x32_bf16 v[126:129], v[144:147], v[176:179], 0
	v_mfma_f32_16x16x32_bf16 v[118:121], v[152:155], v[176:179], 0
	v_mfma_f32_16x16x32_bf16 v[110:113], v[144:147], v[184:187], 0
	v_mfma_f32_16x16x32_bf16 v[102:105], v[152:155], v[184:187], 0
	v_mfma_f32_16x16x32_bf16 v[94:97], v[144:147], v[192:195], 0
	v_mfma_f32_16x16x32_bf16 v[86:89], v[152:155], v[192:195], 0
	v_mfma_f32_16x16x32_bf16 v[78:81], v[144:147], v[206:209], 0
	v_mfma_f32_16x16x32_bf16 v[70:73], v[152:155], v[206:209], 0
	v_mfma_f32_16x16x32_bf16 v[126:129], v[148:151], v[180:183], v[126:129]
	v_mfma_f32_16x16x32_bf16 v[118:121], v[156:159], v[180:183], v[118:121]
	v_mfma_f32_16x16x32_bf16 v[110:113], v[148:151], v[188:191], v[110:113]
	v_mfma_f32_16x16x32_bf16 v[102:105], v[156:159], v[188:191], v[102:105]
	v_mfma_f32_16x16x32_bf16 v[94:97], v[148:151], v[202:205], v[94:97]
	v_mfma_f32_16x16x32_bf16 v[86:89], v[156:159], v[202:205], v[86:89]
	v_mfma_f32_16x16x32_bf16 v[78:81], v[148:151], v[210:213], v[78:81]
	v_mfma_f32_16x16x32_bf16 v[70:73], v[156:159], v[210:213], v[70:73]
	v_mfma_f32_16x16x32_bf16 v[122:125], v[160:163], v[176:179], 0
	v_mfma_f32_16x16x32_bf16 v[114:117], v[168:171], v[176:179], 0
	v_mfma_f32_16x16x32_bf16 v[106:109], v[160:163], v[184:187], 0
	v_mfma_f32_16x16x32_bf16 v[98:101], v[168:171], v[184:187], 0
	v_mfma_f32_16x16x32_bf16 v[90:93], v[160:163], v[192:195], 0
	v_mfma_f32_16x16x32_bf16 v[82:85], v[168:171], v[192:195], 0
	v_mfma_f32_16x16x32_bf16 v[74:77], v[160:163], v[206:209], 0
	v_mfma_f32_16x16x32_bf16 v[66:69], v[168:171], v[206:209], 0
	v_mfma_f32_16x16x32_bf16 v[122:125], v[164:167], v[180:183], v[122:125]
	v_mfma_f32_16x16x32_bf16 v[114:117], v[172:175], v[180:183], v[114:117]
	v_mfma_f32_16x16x32_bf16 v[106:109], v[164:167], v[188:191], v[106:109]
	v_mfma_f32_16x16x32_bf16 v[98:101], v[172:175], v[188:191], v[98:101]
	v_mfma_f32_16x16x32_bf16 v[90:93], v[164:167], v[202:205], v[90:93]
	v_mfma_f32_16x16x32_bf16 v[82:85], v[172:175], v[202:205], v[82:85]
	v_mfma_f32_16x16x32_bf16 v[74:77], v[164:167], v[210:213], v[74:77]
	v_mfma_f32_16x16x32_bf16 v[66:69], v[172:175], v[210:213], v[66:69]
	s_barrier
	s_setprio 0
	s_add_i32 s1, s70, s26
	s_add_u32 s98, s8, s16
	s_addc_u32 s99, s9, s17
	s_mov_b32 m0, s1
	ds_read_b128 v[176:179], v143 offset:16384
	ds_read_b128 v[180:183], v143 offset:17408
	ds_read_b128 v[184:187], v143 offset:18432
	ds_read_b128 v[188:191], v143 offset:19456
	ds_read_b128 v[192:195], v143 offset:20480
	ds_read_b128 v[202:205], v143 offset:21504
	ds_read_b128 v[206:209], v143 offset:22528
	ds_read_b128 v[210:213], v143 offset:23552
	global_load_lds_dwordx4 v196, s[8:9]
	s_add_i32 m0, s1, 0x2000
	s_add_u32 s70, s8, 0x80000
	s_addc_u32 s71, s9, 0
	s_add_i32 s0, s0, s26
	global_load_lds_dwordx4 v130, s[8:9]
	s_mov_b32 m0, s0
	s_nop 0
	global_load_lds_dwordx4 v196, s[70:71]
	s_add_i32 m0, s0, 0x2000
	s_nop 0
	global_load_lds_dwordx4 v130, s[70:71]
	s_add_u32 s78, s58, s16
	s_addc_u32 s79, s59, s17
	s_mov_b32 m0, s27
	s_nop 0
	global_load_lds_dwordx4 v134, s[58:59]
	s_mov_b32 m0, s28
	s_nop 0
	global_load_lds_dwordx4 v132, s[58:59]
	s_waitcnt vmcnt(8)
	s_waitcnt lgkmcnt(0)
	s_setprio 1
	s_barrier
	v_mfma_f32_16x16x32_bf16 v[62:65], v[144:147], v[176:179], 0
	v_mfma_f32_16x16x32_bf16 v[54:57], v[152:155], v[176:179], 0
	v_mfma_f32_16x16x32_bf16 v[46:49], v[144:147], v[184:187], 0
	v_mfma_f32_16x16x32_bf16 v[38:41], v[152:155], v[184:187], 0
	v_mfma_f32_16x16x32_bf16 v[30:33], v[144:147], v[192:195], 0
	v_mfma_f32_16x16x32_bf16 v[22:25], v[152:155], v[192:195], 0
	v_mfma_f32_16x16x32_bf16 v[14:17], v[144:147], v[206:209], 0
	v_mfma_f32_16x16x32_bf16 v[6:9], v[152:155], v[206:209], 0
	v_mfma_f32_16x16x32_bf16 v[62:65], v[148:151], v[180:183], v[62:65]
	v_mfma_f32_16x16x32_bf16 v[54:57], v[156:159], v[180:183], v[54:57]
	v_mfma_f32_16x16x32_bf16 v[46:49], v[148:151], v[188:191], v[46:49]
	v_mfma_f32_16x16x32_bf16 v[38:41], v[156:159], v[188:191], v[38:41]
	v_mfma_f32_16x16x32_bf16 v[30:33], v[148:151], v[202:205], v[30:33]
	v_mfma_f32_16x16x32_bf16 v[22:25], v[156:159], v[202:205], v[22:25]
	v_mfma_f32_16x16x32_bf16 v[14:17], v[148:151], v[210:213], v[14:17]
	v_mfma_f32_16x16x32_bf16 v[6:9], v[156:159], v[210:213], v[6:9]
	v_mfma_f32_16x16x32_bf16 v[58:61], v[160:163], v[176:179], 0
	v_mfma_f32_16x16x32_bf16 v[50:53], v[168:171], v[176:179], 0
	v_mfma_f32_16x16x32_bf16 v[42:45], v[160:163], v[184:187], 0
	v_mfma_f32_16x16x32_bf16 v[34:37], v[168:171], v[184:187], 0
	v_mfma_f32_16x16x32_bf16 v[26:29], v[160:163], v[192:195], 0
	v_mfma_f32_16x16x32_bf16 v[18:21], v[168:171], v[192:195], 0
	v_mfma_f32_16x16x32_bf16 v[10:13], v[160:163], v[206:209], 0
	v_mfma_f32_16x16x32_bf16 v[2:5], v[168:171], v[206:209], 0
	v_mfma_f32_16x16x32_bf16 v[58:61], v[164:167], v[180:183], v[58:61]
	v_mfma_f32_16x16x32_bf16 v[50:53], v[172:175], v[180:183], v[50:53]
	v_mfma_f32_16x16x32_bf16 v[42:45], v[164:167], v[188:191], v[42:45]
	v_mfma_f32_16x16x32_bf16 v[34:37], v[172:175], v[188:191], v[34:37]
	v_mfma_f32_16x16x32_bf16 v[26:29], v[164:167], v[202:205], v[26:29]
	v_mfma_f32_16x16x32_bf16 v[18:21], v[172:175], v[202:205], v[18:21]
	v_mfma_f32_16x16x32_bf16 v[10:13], v[164:167], v[210:213], v[10:13]
	v_mfma_f32_16x16x32_bf16 v[2:5], v[172:175], v[210:213], v[2:5]
	s_barrier
	s_setprio 0
	s_branch .Lkmid_0
.LBB0_904:
	s_add_i32 s69, s8, 2
	s_add_u32 s0, s52, 0xfff80080
	s_addc_u32 s1, s53, -1
	s_add_i32 s70, 0, 0x10000
	s_cmp_eq_u32 s66, s8
	s_cselect_b32 s59, s41, s1
	s_cselect_b32 s58, s45, s0
	s_cselect_b32 s9, s43, s68
	s_cselect_b32 s8, s65, s67
	s_add_i32 s0, 0, 0x14000
	ds_read_b128 v[144:147], v250
	ds_read_b128 v[148:151], v250 offset:1024
	ds_read_b128 v[152:155], v250 offset:2048
	ds_read_b128 v[156:159], v250 offset:3072
	ds_read_b128 v[160:163], v250 offset:16384
	ds_read_b128 v[164:167], v250 offset:17408
	ds_read_b128 v[168:171], v250 offset:18432
	ds_read_b128 v[172:175], v250 offset:19456
	s_add_i32 m0, s27, 0xc000
	ds_read_b128 v[176:179], v143
	ds_read_b128 v[180:183], v143 offset:1024
	ds_read_b128 v[184:187], v143 offset:2048
	ds_read_b128 v[188:191], v143 offset:3072
	ds_read_b128 v[192:195], v143 offset:4096
	ds_read_b128 v[202:205], v143 offset:5120
	ds_read_b128 v[206:209], v143 offset:6144
	ds_read_b128 v[210:213], v143 offset:7168
	global_load_lds_dwordx4 v138, s[52:53]
	s_add_i32 m0, s27, 0xe000
	s_nop 0
	global_load_lds_dwordx4 v136, s[52:53]
	s_waitcnt vmcnt(8)
	s_waitcnt lgkmcnt(0)
	s_setprio 1
	s_barrier
	v_mfma_f32_16x16x32_bf16 v[126:129], v[144:147], v[176:179], v[126:129]
	v_mfma_f32_16x16x32_bf16 v[118:121], v[152:155], v[176:179], v[118:121]
	v_mfma_f32_16x16x32_bf16 v[110:113], v[144:147], v[184:187], v[110:113]
	v_mfma_f32_16x16x32_bf16 v[102:105], v[152:155], v[184:187], v[102:105]
	v_mfma_f32_16x16x32_bf16 v[94:97], v[144:147], v[192:195], v[94:97]
	v_mfma_f32_16x16x32_bf16 v[86:89], v[152:155], v[192:195], v[86:89]
	v_mfma_f32_16x16x32_bf16 v[78:81], v[144:147], v[206:209], v[78:81]
	v_mfma_f32_16x16x32_bf16 v[70:73], v[152:155], v[206:209], v[70:73]
	v_mfma_f32_16x16x32_bf16 v[126:129], v[148:151], v[180:183], v[126:129]
	v_mfma_f32_16x16x32_bf16 v[118:121], v[156:159], v[180:183], v[118:121]
	v_mfma_f32_16x16x32_bf16 v[110:113], v[148:151], v[188:191], v[110:113]
	v_mfma_f32_16x16x32_bf16 v[102:105], v[156:159], v[188:191], v[102:105]
	v_mfma_f32_16x16x32_bf16 v[94:97], v[148:151], v[202:205], v[94:97]
	v_mfma_f32_16x16x32_bf16 v[86:89], v[156:159], v[202:205], v[86:89]
	v_mfma_f32_16x16x32_bf16 v[78:81], v[148:151], v[210:213], v[78:81]
	v_mfma_f32_16x16x32_bf16 v[70:73], v[156:159], v[210:213], v[70:73]
	v_mfma_f32_16x16x32_bf16 v[122:125], v[160:163], v[176:179], v[122:125]
	v_mfma_f32_16x16x32_bf16 v[114:117], v[168:171], v[176:179], v[114:117]
	v_mfma_f32_16x16x32_bf16 v[106:109], v[160:163], v[184:187], v[106:109]
	v_mfma_f32_16x16x32_bf16 v[98:101], v[168:171], v[184:187], v[98:101]
	v_mfma_f32_16x16x32_bf16 v[90:93], v[160:163], v[192:195], v[90:93]
	v_mfma_f32_16x16x32_bf16 v[82:85], v[168:171], v[192:195], v[82:85]
	v_mfma_f32_16x16x32_bf16 v[74:77], v[160:163], v[206:209], v[74:77]
	v_mfma_f32_16x16x32_bf16 v[66:69], v[168:171], v[206:209], v[66:69]
	v_mfma_f32_16x16x32_bf16 v[122:125], v[164:167], v[180:183], v[122:125]
	v_mfma_f32_16x16x32_bf16 v[114:117], v[172:175], v[180:183], v[114:117]
	v_mfma_f32_16x16x32_bf16 v[106:109], v[164:167], v[188:191], v[106:109]
	v_mfma_f32_16x16x32_bf16 v[98:101], v[172:175], v[188:191], v[98:101]
	v_mfma_f32_16x16x32_bf16 v[90:93], v[164:167], v[202:205], v[90:93]
	v_mfma_f32_16x16x32_bf16 v[82:85], v[172:175], v[202:205], v[82:85]
	v_mfma_f32_16x16x32_bf16 v[74:77], v[164:167], v[210:213], v[74:77]
	v_mfma_f32_16x16x32_bf16 v[66:69], v[172:175], v[210:213], v[66:69]
	s_barrier
	s_setprio 0
	s_add_i32 s1, s70, s26
	s_add_u32 s98, s8, s16
	s_addc_u32 s99, s9, s17
	s_mov_b32 m0, s1
	ds_read_b128 v[176:179], v143 offset:16384
	ds_read_b128 v[180:183], v143 offset:17408
	ds_read_b128 v[184:187], v143 offset:18432
	ds_read_b128 v[188:191], v143 offset:19456
	ds_read_b128 v[192:195], v143 offset:20480
	ds_read_b128 v[202:205], v143 offset:21504
	ds_read_b128 v[206:209], v143 offset:22528
	ds_read_b128 v[210:213], v143 offset:23552
	global_load_lds_dwordx4 v196, s[8:9]
	s_add_i32 m0, s1, 0x2000
	s_add_u32 s70, s8, 0x80000
	s_addc_u32 s71, s9, 0
	s_add_i32 s0, s0, s26
	global_load_lds_dwordx4 v130, s[8:9]
	s_mov_b32 m0, s0
	s_nop 0
	global_load_lds_dwordx4 v196, s[70:71]
	s_add_i32 m0, s0, 0x2000
	s_nop 0
	global_load_lds_dwordx4 v130, s[70:71]
	s_add_u32 s78, s58, s16
	s_addc_u32 s79, s59, s17
	s_mov_b32 m0, s27
	s_nop 0
	global_load_lds_dwordx4 v134, s[58:59]
	s_mov_b32 m0, s28
	s_nop 0
	global_load_lds_dwordx4 v132, s[58:59]
	s_waitcnt vmcnt(8)
	s_waitcnt lgkmcnt(0)
	s_setprio 1
	s_barrier
	v_mfma_f32_16x16x32_bf16 v[62:65], v[144:147], v[176:179], v[62:65]
	v_mfma_f32_16x16x32_bf16 v[54:57], v[152:155], v[176:179], v[54:57]
	v_mfma_f32_16x16x32_bf16 v[46:49], v[144:147], v[184:187], v[46:49]
	v_mfma_f32_16x16x32_bf16 v[38:41], v[152:155], v[184:187], v[38:41]
	v_mfma_f32_16x16x32_bf16 v[30:33], v[144:147], v[192:195], v[30:33]
	v_mfma_f32_16x16x32_bf16 v[22:25], v[152:155], v[192:195], v[22:25]
	v_mfma_f32_16x16x32_bf16 v[14:17], v[144:147], v[206:209], v[14:17]
	v_mfma_f32_16x16x32_bf16 v[6:9], v[152:155], v[206:209], v[6:9]
	v_mfma_f32_16x16x32_bf16 v[62:65], v[148:151], v[180:183], v[62:65]
	v_mfma_f32_16x16x32_bf16 v[54:57], v[156:159], v[180:183], v[54:57]
	v_mfma_f32_16x16x32_bf16 v[46:49], v[148:151], v[188:191], v[46:49]
	v_mfma_f32_16x16x32_bf16 v[38:41], v[156:159], v[188:191], v[38:41]
	v_mfma_f32_16x16x32_bf16 v[30:33], v[148:151], v[202:205], v[30:33]
	v_mfma_f32_16x16x32_bf16 v[22:25], v[156:159], v[202:205], v[22:25]
	v_mfma_f32_16x16x32_bf16 v[14:17], v[148:151], v[210:213], v[14:17]
	v_mfma_f32_16x16x32_bf16 v[6:9], v[156:159], v[210:213], v[6:9]
	v_mfma_f32_16x16x32_bf16 v[58:61], v[160:163], v[176:179], v[58:61]
	v_mfma_f32_16x16x32_bf16 v[50:53], v[168:171], v[176:179], v[50:53]
	v_mfma_f32_16x16x32_bf16 v[42:45], v[160:163], v[184:187], v[42:45]
	v_mfma_f32_16x16x32_bf16 v[34:37], v[168:171], v[184:187], v[34:37]
	v_mfma_f32_16x16x32_bf16 v[26:29], v[160:163], v[192:195], v[26:29]
	v_mfma_f32_16x16x32_bf16 v[18:21], v[168:171], v[192:195], v[18:21]
	v_mfma_f32_16x16x32_bf16 v[10:13], v[160:163], v[206:209], v[10:13]
	v_mfma_f32_16x16x32_bf16 v[2:5], v[168:171], v[206:209], v[2:5]
	v_mfma_f32_16x16x32_bf16 v[58:61], v[164:167], v[180:183], v[58:61]
	v_mfma_f32_16x16x32_bf16 v[50:53], v[172:175], v[180:183], v[50:53]
	v_mfma_f32_16x16x32_bf16 v[42:45], v[164:167], v[188:191], v[42:45]
	v_mfma_f32_16x16x32_bf16 v[34:37], v[172:175], v[188:191], v[34:37]
	v_mfma_f32_16x16x32_bf16 v[26:29], v[164:167], v[202:205], v[26:29]
	v_mfma_f32_16x16x32_bf16 v[18:21], v[172:175], v[202:205], v[18:21]
	v_mfma_f32_16x16x32_bf16 v[10:13], v[164:167], v[210:213], v[10:13]
	v_mfma_f32_16x16x32_bf16 v[2:5], v[172:175], v[210:213], v[2:5]
	s_barrier
	s_setprio 0
.Lkmid_0:
	s_add_i32 s0, 0, 0x18000
	s_add_i32 s1, 0, 0x1c000
	ds_read_b128 v[144:147], v250 offset:32768
	ds_read_b128 v[148:151], v250 offset:33792
	ds_read_b128 v[152:155], v250 offset:34816
	ds_read_b128 v[156:159], v250 offset:35840
	ds_read_b128 v[160:163], v250 offset:49152
	ds_read_b128 v[164:167], v250 offset:50176
	ds_read_b128 v[168:171], v250 offset:51200
	ds_read_b128 v[172:175], v250 offset:52224
	s_add_u32 s58, s58, 0x80000
	s_addc_u32 s59, s59, 0
	s_mov_b32 m0, s29
	ds_read_b128 v[176:179], v143 offset:32768
	ds_read_b128 v[180:183], v143 offset:33792
	ds_read_b128 v[184:187], v143 offset:34816
	ds_read_b128 v[188:191], v143 offset:35840
	ds_read_b128 v[192:195], v143 offset:36864
	ds_read_b128 v[202:205], v143 offset:37888
	ds_read_b128 v[206:209], v143 offset:38912
	ds_read_b128 v[210:213], v143 offset:39936
	global_load_lds_dwordx4 v134, s[58:59]
	s_mov_b32 m0, s30
	s_nop 0
	global_load_lds_dwordx4 v132, s[58:59]
	s_waitcnt vmcnt(8)
	s_waitcnt lgkmcnt(0)
	s_setprio 1
	s_barrier
	v_mfma_f32_16x16x32_bf16 v[126:129], v[144:147], v[176:179], v[126:129]
	v_mfma_f32_16x16x32_bf16 v[118:121], v[152:155], v[176:179], v[118:121]
	v_mfma_f32_16x16x32_bf16 v[110:113], v[144:147], v[184:187], v[110:113]
	v_mfma_f32_16x16x32_bf16 v[102:105], v[152:155], v[184:187], v[102:105]
	v_mfma_f32_16x16x32_bf16 v[94:97], v[144:147], v[192:195], v[94:97]
	v_mfma_f32_16x16x32_bf16 v[86:89], v[152:155], v[192:195], v[86:89]
	v_mfma_f32_16x16x32_bf16 v[78:81], v[144:147], v[206:209], v[78:81]
	v_mfma_f32_16x16x32_bf16 v[70:73], v[152:155], v[206:209], v[70:73]
	v_mfma_f32_16x16x32_bf16 v[126:129], v[148:151], v[180:183], v[126:129]
	v_mfma_f32_16x16x32_bf16 v[118:121], v[156:159], v[180:183], v[118:121]
	v_mfma_f32_16x16x32_bf16 v[110:113], v[148:151], v[188:191], v[110:113]
	v_mfma_f32_16x16x32_bf16 v[102:105], v[156:159], v[188:191], v[102:105]
	v_mfma_f32_16x16x32_bf16 v[94:97], v[148:151], v[202:205], v[94:97]
	v_mfma_f32_16x16x32_bf16 v[86:89], v[156:159], v[202:205], v[86:89]
	v_mfma_f32_16x16x32_bf16 v[78:81], v[148:151], v[210:213], v[78:81]
	v_mfma_f32_16x16x32_bf16 v[70:73], v[156:159], v[210:213], v[70:73]
	v_mfma_f32_16x16x32_bf16 v[122:125], v[160:163], v[176:179], v[122:125]
	v_mfma_f32_16x16x32_bf16 v[114:117], v[168:171], v[176:179], v[114:117]
	v_mfma_f32_16x16x32_bf16 v[106:109], v[160:163], v[184:187], v[106:109]
	v_mfma_f32_16x16x32_bf16 v[98:101], v[168:171], v[184:187], v[98:101]
	v_mfma_f32_16x16x32_bf16 v[90:93], v[160:163], v[192:195], v[90:93]
	v_mfma_f32_16x16x32_bf16 v[82:85], v[168:171], v[192:195], v[82:85]
	v_mfma_f32_16x16x32_bf16 v[74:77], v[160:163], v[206:209], v[74:77]
	v_mfma_f32_16x16x32_bf16 v[66:69], v[168:171], v[206:209], v[66:69]
	v_mfma_f32_16x16x32_bf16 v[122:125], v[164:167], v[180:183], v[122:125]
	v_mfma_f32_16x16x32_bf16 v[114:117], v[172:175], v[180:183], v[114:117]
	v_mfma_f32_16x16x32_bf16 v[106:109], v[164:167], v[188:191], v[106:109]
	v_mfma_f32_16x16x32_bf16 v[98:101], v[172:175], v[188:191], v[98:101]
	v_mfma_f32_16x16x32_bf16 v[90:93], v[164:167], v[202:205], v[90:93]
	v_mfma_f32_16x16x32_bf16 v[82:85], v[172:175], v[202:205], v[82:85]
	v_mfma_f32_16x16x32_bf16 v[74:77], v[164:167], v[210:213], v[74:77]
	v_mfma_f32_16x16x32_bf16 v[66:69], v[172:175], v[210:213], v[66:69]
	s_barrier
	s_setprio 0
	s_add_i32 s0, s0, s26
	s_mov_b32 m0, s0
	ds_read_b128 v[176:179], v143 offset:49152
	ds_read_b128 v[180:183], v143 offset:50176
	ds_read_b128 v[184:187], v143 offset:51200
	ds_read_b128 v[188:191], v143 offset:52224
	ds_read_b128 v[192:195], v143 offset:53248
	ds_read_b128 v[202:205], v143 offset:54272
	ds_read_b128 v[206:209], v143 offset:55296
	ds_read_b128 v[210:213], v143 offset:56320
	global_load_lds_dwordx4 v196, s[98:99]
	s_add_i32 m0, s0, 0x2000
	s_add_u32 s8, s8, 0x80080
	s_addc_u32 s9, s9, 0
	s_add_i32 s0, s1, s26
	global_load_lds_dwordx4 v130, s[98:99]
	s_mov_b32 m0, s0
	s_nop 0
	global_load_lds_dwordx4 v196, s[8:9]
	s_add_i32 m0, s0, 0x2000
	s_nop 0
	global_load_lds_dwordx4 v130, s[8:9]
	s_mov_b32 m0, s31
	s_nop 0
	global_load_lds_dwordx4 v134, s[78:79]
	s_mov_b32 m0, s34
	s_nop 0
	global_load_lds_dwordx4 v132, s[78:79]
	s_waitcnt vmcnt(8)
	s_waitcnt lgkmcnt(0)
	s_setprio 1
	s_barrier
	v_mfma_f32_16x16x32_bf16 v[62:65], v[144:147], v[176:179], v[62:65]
	v_mfma_f32_16x16x32_bf16 v[54:57], v[152:155], v[176:179], v[54:57]
	v_mfma_f32_16x16x32_bf16 v[46:49], v[144:147], v[184:187], v[46:49]
	v_mfma_f32_16x16x32_bf16 v[38:41], v[152:155], v[184:187], v[38:41]
	v_mfma_f32_16x16x32_bf16 v[30:33], v[144:147], v[192:195], v[30:33]
	v_mfma_f32_16x16x32_bf16 v[22:25], v[152:155], v[192:195], v[22:25]
	v_mfma_f32_16x16x32_bf16 v[14:17], v[144:147], v[206:209], v[14:17]
	v_mfma_f32_16x16x32_bf16 v[6:9], v[152:155], v[206:209], v[6:9]
	v_mfma_f32_16x16x32_bf16 v[62:65], v[148:151], v[180:183], v[62:65]
	v_mfma_f32_16x16x32_bf16 v[54:57], v[156:159], v[180:183], v[54:57]
	v_mfma_f32_16x16x32_bf16 v[46:49], v[148:151], v[188:191], v[46:49]
	v_mfma_f32_16x16x32_bf16 v[38:41], v[156:159], v[188:191], v[38:41]
	v_mfma_f32_16x16x32_bf16 v[30:33], v[148:151], v[202:205], v[30:33]
	v_mfma_f32_16x16x32_bf16 v[22:25], v[156:159], v[202:205], v[22:25]
	v_mfma_f32_16x16x32_bf16 v[14:17], v[148:151], v[210:213], v[14:17]
	v_mfma_f32_16x16x32_bf16 v[6:9], v[156:159], v[210:213], v[6:9]
	v_mfma_f32_16x16x32_bf16 v[58:61], v[160:163], v[176:179], v[58:61]
	v_mfma_f32_16x16x32_bf16 v[50:53], v[168:171], v[176:179], v[50:53]
	v_mfma_f32_16x16x32_bf16 v[42:45], v[160:163], v[184:187], v[42:45]
	v_mfma_f32_16x16x32_bf16 v[34:37], v[168:171], v[184:187], v[34:37]
	v_mfma_f32_16x16x32_bf16 v[26:29], v[160:163], v[192:195], v[26:29]
	v_mfma_f32_16x16x32_bf16 v[18:21], v[168:171], v[192:195], v[18:21]
	v_mfma_f32_16x16x32_bf16 v[10:13], v[160:163], v[206:209], v[10:13]
	v_mfma_f32_16x16x32_bf16 v[2:5], v[168:171], v[206:209], v[2:5]
	v_mfma_f32_16x16x32_bf16 v[58:61], v[164:167], v[180:183], v[58:61]
	v_mfma_f32_16x16x32_bf16 v[50:53], v[172:175], v[180:183], v[50:53]
	v_mfma_f32_16x16x32_bf16 v[42:45], v[164:167], v[188:191], v[42:45]
	v_mfma_f32_16x16x32_bf16 v[34:37], v[172:175], v[188:191], v[34:37]
	v_mfma_f32_16x16x32_bf16 v[26:29], v[164:167], v[202:205], v[26:29]
	v_mfma_f32_16x16x32_bf16 v[18:21], v[172:175], v[202:205], v[18:21]
	v_mfma_f32_16x16x32_bf16 v[10:13], v[164:167], v[210:213], v[10:13]
	v_mfma_f32_16x16x32_bf16 v[2:5], v[172:175], v[210:213], v[2:5]
	s_barrier
	s_setprio 0
	s_add_u32 s67, s67, 0x100
	s_addc_u32 s68, s68, 0
	s_add_u32 s52, s52, 0x100
	s_addc_u32 s53, s53, 0
	s_cmp_ge_i32 s69, s62
	s_mov_b32 s8, s69
	s_cbranch_scc0 .LBB0_904
	s_and_b64 vcc, exec, s[38:39]
	s_cbranch_vccz .LBB0_907
	s_barrier

.Ldefbar_skip_1:
	v_add_u32_e32 v250, 0x10000, v188
	s_add_i32 s72, s50, 2
	s_add_u32 s8, s48, 0x100
	s_addc_u32 s9, s49, 0
	s_add_i32 s0, 0, 0x10000
	s_cmp_eq_u32 s41, s50
	s_cselect_b32 s53, s45, s9
	s_cselect_b32 s52, s44, s8
	s_cselect_b32 s51, s47, s71
	s_cselect_b32 s50, s46, s70
	s_add_i32 s1, 0, 0x14000
	ds_read_b128 v[130:133], v250
	ds_read_b128 v[134:137], v250 offset:1024
	ds_read_b128 v[138:141], v250 offset:2048
	ds_read_b128 v[142:145], v250 offset:3072
	ds_read_b128 v[146:149], v250 offset:16384
	ds_read_b128 v[164:167], v250 offset:17408
	ds_read_b128 v[168:171], v250 offset:18432
	ds_read_b128 v[172:175], v250 offset:19456
	v_lshl_add_u64 v[194:195], s[48:49], 0, v[162:163]
	s_add_i32 m0, s27, 0xc000
	ds_read_b128 v[176:179], v189
	ds_read_b128 v[180:183], v189 offset:1024
	ds_read_b128 v[184:187], v189 offset:2048
	ds_read_b128 v[190:193], v189 offset:3072
	ds_read_b128 v[202:205], v189 offset:4096
	ds_read_b128 v[206:209], v189 offset:5120
	ds_read_b128 v[210:213], v189 offset:6144
	ds_read_b128 v[214:217], v189 offset:7168
	global_load_lds_dwordx4 v[194:195], off
	v_lshl_add_u64 v[194:195], s[48:49], 0, v[160:161]
	s_add_i32 m0, s27, 0xe000
	s_nop 0
	global_load_lds_dwordx4 v[194:195], off
	s_waitcnt vmcnt(8)
	s_waitcnt lgkmcnt(0)
	s_setprio 1
	s_barrier
	v_mfma_f32_16x16x32_bf16 v[126:129], v[130:133], v[176:179], 0
	v_mfma_f32_16x16x32_bf16 v[122:125], v[138:141], v[176:179], 0
	v_mfma_f32_16x16x32_bf16 v[110:113], v[130:133], v[184:187], 0
	v_mfma_f32_16x16x32_bf16 v[106:109], v[138:141], v[184:187], 0
	v_mfma_f32_16x16x32_bf16 v[98:101], v[130:133], v[202:205], 0
	v_mfma_f32_16x16x32_bf16 v[90:93], v[138:141], v[202:205], 0
	v_mfma_f32_16x16x32_bf16 v[82:85], v[130:133], v[210:213], 0
	v_mfma_f32_16x16x32_bf16 v[74:77], v[138:141], v[210:213], 0
	v_mfma_f32_16x16x32_bf16 v[126:129], v[134:137], v[180:183], v[126:129]
	v_mfma_f32_16x16x32_bf16 v[122:125], v[142:145], v[180:183], v[122:125]
	v_mfma_f32_16x16x32_bf16 v[110:113], v[134:137], v[190:193], v[110:113]
	v_mfma_f32_16x16x32_bf16 v[106:109], v[142:145], v[190:193], v[106:109]
	v_mfma_f32_16x16x32_bf16 v[98:101], v[134:137], v[206:209], v[98:101]
	v_mfma_f32_16x16x32_bf16 v[90:93], v[142:145], v[206:209], v[90:93]
	v_mfma_f32_16x16x32_bf16 v[82:85], v[134:137], v[214:217], v[82:85]
	v_mfma_f32_16x16x32_bf16 v[74:77], v[142:145], v[214:217], v[74:77]
	v_mfma_f32_16x16x32_bf16 v[118:121], v[146:149], v[176:179], 0
	v_mfma_f32_16x16x32_bf16 v[114:117], v[168:171], v[176:179], 0
	v_mfma_f32_16x16x32_bf16 v[102:105], v[146:149], v[184:187], 0
	v_mfma_f32_16x16x32_bf16 v[94:97], v[168:171], v[184:187], 0
	v_mfma_f32_16x16x32_bf16 v[86:89], v[146:149], v[202:205], 0
	v_mfma_f32_16x16x32_bf16 v[78:81], v[168:171], v[202:205], 0
	v_mfma_f32_16x16x32_bf16 v[70:73], v[146:149], v[210:213], 0
	v_mfma_f32_16x16x32_bf16 v[66:69], v[168:171], v[210:213], 0
	v_mfma_f32_16x16x32_bf16 v[118:121], v[164:167], v[180:183], v[118:121]
	v_mfma_f32_16x16x32_bf16 v[114:117], v[172:175], v[180:183], v[114:117]
	v_mfma_f32_16x16x32_bf16 v[102:105], v[164:167], v[190:193], v[102:105]
	v_mfma_f32_16x16x32_bf16 v[94:97], v[172:175], v[190:193], v[94:97]
	v_mfma_f32_16x16x32_bf16 v[86:89], v[164:167], v[206:209], v[86:89]
	v_mfma_f32_16x16x32_bf16 v[78:81], v[172:175], v[206:209], v[78:81]
	v_mfma_f32_16x16x32_bf16 v[70:73], v[164:167], v[214:217], v[70:73]
	v_mfma_f32_16x16x32_bf16 v[66:69], v[172:175], v[214:217], v[66:69]
	s_barrier
	s_setprio 0
	s_add_i32 s0, s0, s26
	s_add_u32 s98, s50, s16
	s_addc_u32 s99, s51, s17
	s_mov_b32 m0, s0
	ds_read_b128 v[176:179], v189 offset:16384
	ds_read_b128 v[180:183], v189 offset:17408
	ds_read_b128 v[184:187], v189 offset:18432
	ds_read_b128 v[190:193], v189 offset:19456
	ds_read_b128 v[202:205], v189 offset:20480
	ds_read_b128 v[206:209], v189 offset:21504
	ds_read_b128 v[210:213], v189 offset:22528
	ds_read_b128 v[214:217], v189 offset:23552
	global_load_lds_dwordx4 v196, s[50:51]
	s_add_i32 m0, s0, 0x2000
	s_add_u32 s48, s50, 0x158000
	s_addc_u32 s49, s51, 0
	s_add_i32 s0, s1, s26
	global_load_lds_dwordx4 v154, s[50:51]
	s_mov_b32 m0, s0
	s_nop 0
	global_load_lds_dwordx4 v196, s[48:49]
	s_add_i32 m0, s0, 0x2000
	s_nop 0
	global_load_lds_dwordx4 v154, s[48:49]
	s_add_u32 s78, s52, s16
	s_addc_u32 s79, s53, s17
	s_mov_b32 m0, s27
	s_nop 0
	global_load_lds_dwordx4 v150, s[52:53]
	s_mov_b32 m0, s28
	s_nop 0
	global_load_lds_dwordx4 v152, s[52:53]
	s_waitcnt vmcnt(8)
	s_waitcnt lgkmcnt(0)
	s_setprio 1
	s_barrier
	v_mfma_f32_16x16x32_bf16 v[62:65], v[130:133], v[176:179], 0
	v_mfma_f32_16x16x32_bf16 v[58:61], v[138:141], v[176:179], 0
	v_mfma_f32_16x16x32_bf16 v[50:53], v[130:133], v[184:187], 0
	v_mfma_f32_16x16x32_bf16 v[42:45], v[138:141], v[184:187], 0
	v_mfma_f32_16x16x32_bf16 v[34:37], v[130:133], v[202:205], 0
	v_mfma_f32_16x16x32_bf16 v[26:29], v[138:141], v[202:205], 0
	v_mfma_f32_16x16x32_bf16 v[18:21], v[130:133], v[210:213], 0
	v_mfma_f32_16x16x32_bf16 v[10:13], v[138:141], v[210:213], 0
	v_mfma_f32_16x16x32_bf16 v[62:65], v[134:137], v[180:183], v[62:65]
	v_mfma_f32_16x16x32_bf16 v[58:61], v[142:145], v[180:183], v[58:61]
	v_mfma_f32_16x16x32_bf16 v[50:53], v[134:137], v[190:193], v[50:53]
	v_mfma_f32_16x16x32_bf16 v[42:45], v[142:145], v[190:193], v[42:45]
	v_mfma_f32_16x16x32_bf16 v[34:37], v[134:137], v[206:209], v[34:37]
	v_mfma_f32_16x16x32_bf16 v[26:29], v[142:145], v[206:209], v[26:29]
	v_mfma_f32_16x16x32_bf16 v[18:21], v[134:137], v[214:217], v[18:21]
	v_mfma_f32_16x16x32_bf16 v[10:13], v[142:145], v[214:217], v[10:13]
	v_mfma_f32_16x16x32_bf16 v[54:57], v[146:149], v[176:179], 0
	v_mfma_f32_16x16x32_bf16 v[46:49], v[168:171], v[176:179], 0
	v_mfma_f32_16x16x32_bf16 v[38:41], v[146:149], v[184:187], 0
	v_mfma_f32_16x16x32_bf16 v[30:33], v[168:171], v[184:187], 0
	v_mfma_f32_16x16x32_bf16 v[22:25], v[146:149], v[202:205], 0
	v_mfma_f32_16x16x32_bf16 v[14:17], v[168:171], v[202:205], 0
	v_mfma_f32_16x16x32_bf16 v[6:9], v[146:149], v[210:213], 0
	v_mfma_f32_16x16x32_bf16 v[2:5], v[168:171], v[210:213], 0
	v_mfma_f32_16x16x32_bf16 v[54:57], v[164:167], v[180:183], v[54:57]
	v_mfma_f32_16x16x32_bf16 v[46:49], v[172:175], v[180:183], v[46:49]
	v_mfma_f32_16x16x32_bf16 v[38:41], v[164:167], v[190:193], v[38:41]
	v_mfma_f32_16x16x32_bf16 v[30:33], v[172:175], v[190:193], v[30:33]
	v_mfma_f32_16x16x32_bf16 v[22:25], v[164:167], v[206:209], v[22:25]
	v_mfma_f32_16x16x32_bf16 v[14:17], v[172:175], v[206:209], v[14:17]
	v_mfma_f32_16x16x32_bf16 v[6:9], v[164:167], v[214:217], v[6:9]
	v_mfma_f32_16x16x32_bf16 v[2:5], v[172:175], v[214:217], v[2:5]
	s_barrier
	s_setprio 0
	s_branch .Lkmid_1
.LBB0_987:
	s_add_i32 s72, s50, 2
	s_add_u32 s8, s48, 0x100
	s_addc_u32 s9, s49, 0
	s_add_i32 s0, 0, 0x10000
	s_cmp_eq_u32 s41, s50
	s_cselect_b32 s53, s45, s9
	s_cselect_b32 s52, s44, s8
	s_cselect_b32 s51, s47, s71
	s_cselect_b32 s50, s46, s70
	s_add_i32 s1, 0, 0x14000
	ds_read_b128 v[130:133], v250
	ds_read_b128 v[134:137], v250 offset:1024
	ds_read_b128 v[138:141], v250 offset:2048
	ds_read_b128 v[142:145], v250 offset:3072
	ds_read_b128 v[146:149], v250 offset:16384
	ds_read_b128 v[164:167], v250 offset:17408
	ds_read_b128 v[168:171], v250 offset:18432
	ds_read_b128 v[172:175], v250 offset:19456
	v_lshl_add_u64 v[194:195], s[48:49], 0, v[162:163]
	s_add_i32 m0, s27, 0xc000
	ds_read_b128 v[176:179], v189
	ds_read_b128 v[180:183], v189 offset:1024
	ds_read_b128 v[184:187], v189 offset:2048
	ds_read_b128 v[190:193], v189 offset:3072
	ds_read_b128 v[202:205], v189 offset:4096
	ds_read_b128 v[206:209], v189 offset:5120
	ds_read_b128 v[210:213], v189 offset:6144
	ds_read_b128 v[214:217], v189 offset:7168
	global_load_lds_dwordx4 v[194:195], off
	v_lshl_add_u64 v[194:195], s[48:49], 0, v[160:161]
	s_add_i32 m0, s27, 0xe000
	s_nop 0
	global_load_lds_dwordx4 v[194:195], off
	s_waitcnt vmcnt(8)
	s_waitcnt lgkmcnt(0)
	s_setprio 1
	s_barrier
	v_mfma_f32_16x16x32_bf16 v[126:129], v[130:133], v[176:179], v[126:129]
	v_mfma_f32_16x16x32_bf16 v[122:125], v[138:141], v[176:179], v[122:125]
	v_mfma_f32_16x16x32_bf16 v[110:113], v[130:133], v[184:187], v[110:113]
	v_mfma_f32_16x16x32_bf16 v[106:109], v[138:141], v[184:187], v[106:109]
	v_mfma_f32_16x16x32_bf16 v[98:101], v[130:133], v[202:205], v[98:101]
	v_mfma_f32_16x16x32_bf16 v[90:93], v[138:141], v[202:205], v[90:93]
	v_mfma_f32_16x16x32_bf16 v[82:85], v[130:133], v[210:213], v[82:85]
	v_mfma_f32_16x16x32_bf16 v[74:77], v[138:141], v[210:213], v[74:77]
	v_mfma_f32_16x16x32_bf16 v[126:129], v[134:137], v[180:183], v[126:129]
	v_mfma_f32_16x16x32_bf16 v[122:125], v[142:145], v[180:183], v[122:125]
	v_mfma_f32_16x16x32_bf16 v[110:113], v[134:137], v[190:193], v[110:113]
	v_mfma_f32_16x16x32_bf16 v[106:109], v[142:145], v[190:193], v[106:109]
	v_mfma_f32_16x16x32_bf16 v[98:101], v[134:137], v[206:209], v[98:101]
	v_mfma_f32_16x16x32_bf16 v[90:93], v[142:145], v[206:209], v[90:93]
	v_mfma_f32_16x16x32_bf16 v[82:85], v[134:137], v[214:217], v[82:85]
	v_mfma_f32_16x16x32_bf16 v[74:77], v[142:145], v[214:217], v[74:77]
	v_mfma_f32_16x16x32_bf16 v[118:121], v[146:149], v[176:179], v[118:121]
	v_mfma_f32_16x16x32_bf16 v[114:117], v[168:171], v[176:179], v[114:117]
	v_mfma_f32_16x16x32_bf16 v[102:105], v[146:149], v[184:187], v[102:105]
	v_mfma_f32_16x16x32_bf16 v[94:97], v[168:171], v[184:187], v[94:97]
	v_mfma_f32_16x16x32_bf16 v[86:89], v[146:149], v[202:205], v[86:89]
	v_mfma_f32_16x16x32_bf16 v[78:81], v[168:171], v[202:205], v[78:81]
	v_mfma_f32_16x16x32_bf16 v[70:73], v[146:149], v[210:213], v[70:73]
	v_mfma_f32_16x16x32_bf16 v[66:69], v[168:171], v[210:213], v[66:69]
	v_mfma_f32_16x16x32_bf16 v[118:121], v[164:167], v[180:183], v[118:121]
	v_mfma_f32_16x16x32_bf16 v[114:117], v[172:175], v[180:183], v[114:117]
	v_mfma_f32_16x16x32_bf16 v[102:105], v[164:167], v[190:193], v[102:105]
	v_mfma_f32_16x16x32_bf16 v[94:97], v[172:175], v[190:193], v[94:97]
	v_mfma_f32_16x16x32_bf16 v[86:89], v[164:167], v[206:209], v[86:89]
	v_mfma_f32_16x16x32_bf16 v[78:81], v[172:175], v[206:209], v[78:81]
	v_mfma_f32_16x16x32_bf16 v[70:73], v[164:167], v[214:217], v[70:73]
	v_mfma_f32_16x16x32_bf16 v[66:69], v[172:175], v[214:217], v[66:69]
	s_barrier
	s_setprio 0
	s_add_i32 s0, s0, s26
	s_add_u32 s98, s50, s16
	s_addc_u32 s99, s51, s17
	s_mov_b32 m0, s0
	ds_read_b128 v[176:179], v189 offset:16384
	ds_read_b128 v[180:183], v189 offset:17408
	ds_read_b128 v[184:187], v189 offset:18432
	ds_read_b128 v[190:193], v189 offset:19456
	ds_read_b128 v[202:205], v189 offset:20480
	ds_read_b128 v[206:209], v189 offset:21504
	ds_read_b128 v[210:213], v189 offset:22528
	ds_read_b128 v[214:217], v189 offset:23552
	global_load_lds_dwordx4 v196, s[50:51]
	s_add_i32 m0, s0, 0x2000
	s_add_u32 s48, s50, 0x158000
	s_addc_u32 s49, s51, 0
	s_add_i32 s0, s1, s26
	global_load_lds_dwordx4 v154, s[50:51]
	s_mov_b32 m0, s0
	s_nop 0
	global_load_lds_dwordx4 v196, s[48:49]
	s_add_i32 m0, s0, 0x2000
	s_nop 0
	global_load_lds_dwordx4 v154, s[48:49]
	s_add_u32 s78, s52, s16
	s_addc_u32 s79, s53, s17
	s_mov_b32 m0, s27
	s_nop 0
	global_load_lds_dwordx4 v150, s[52:53]
	s_mov_b32 m0, s28
	s_nop 0
	global_load_lds_dwordx4 v152, s[52:53]
	s_waitcnt vmcnt(8)
	s_waitcnt lgkmcnt(0)
	s_setprio 1
	s_barrier
	v_mfma_f32_16x16x32_bf16 v[62:65], v[130:133], v[176:179], v[62:65]
	v_mfma_f32_16x16x32_bf16 v[58:61], v[138:141], v[176:179], v[58:61]
	v_mfma_f32_16x16x32_bf16 v[50:53], v[130:133], v[184:187], v[50:53]
	v_mfma_f32_16x16x32_bf16 v[42:45], v[138:141], v[184:187], v[42:45]
	v_mfma_f32_16x16x32_bf16 v[34:37], v[130:133], v[202:205], v[34:37]
	v_mfma_f32_16x16x32_bf16 v[26:29], v[138:141], v[202:205], v[26:29]
	v_mfma_f32_16x16x32_bf16 v[18:21], v[130:133], v[210:213], v[18:21]
	v_mfma_f32_16x16x32_bf16 v[10:13], v[138:141], v[210:213], v[10:13]
	v_mfma_f32_16x16x32_bf16 v[62:65], v[134:137], v[180:183], v[62:65]
	v_mfma_f32_16x16x32_bf16 v[58:61], v[142:145], v[180:183], v[58:61]
	v_mfma_f32_16x16x32_bf16 v[50:53], v[134:137], v[190:193], v[50:53]
	v_mfma_f32_16x16x32_bf16 v[42:45], v[142:145], v[190:193], v[42:45]
	v_mfma_f32_16x16x32_bf16 v[34:37], v[134:137], v[206:209], v[34:37]
	v_mfma_f32_16x16x32_bf16 v[26:29], v[142:145], v[206:209], v[26:29]
	v_mfma_f32_16x16x32_bf16 v[18:21], v[134:137], v[214:217], v[18:21]
	v_mfma_f32_16x16x32_bf16 v[10:13], v[142:145], v[214:217], v[10:13]
	v_mfma_f32_16x16x32_bf16 v[54:57], v[146:149], v[176:179], v[54:57]
	v_mfma_f32_16x16x32_bf16 v[46:49], v[168:171], v[176:179], v[46:49]
	v_mfma_f32_16x16x32_bf16 v[38:41], v[146:149], v[184:187], v[38:41]
	v_mfma_f32_16x16x32_bf16 v[30:33], v[168:171], v[184:187], v[30:33]
	v_mfma_f32_16x16x32_bf16 v[22:25], v[146:149], v[202:205], v[22:25]
	v_mfma_f32_16x16x32_bf16 v[14:17], v[168:171], v[202:205], v[14:17]
	v_mfma_f32_16x16x32_bf16 v[6:9], v[146:149], v[210:213], v[6:9]
	v_mfma_f32_16x16x32_bf16 v[2:5], v[168:171], v[210:213], v[2:5]
	v_mfma_f32_16x16x32_bf16 v[54:57], v[164:167], v[180:183], v[54:57]
	v_mfma_f32_16x16x32_bf16 v[46:49], v[172:175], v[180:183], v[46:49]
	v_mfma_f32_16x16x32_bf16 v[38:41], v[164:167], v[190:193], v[38:41]
	v_mfma_f32_16x16x32_bf16 v[30:33], v[172:175], v[190:193], v[30:33]
	v_mfma_f32_16x16x32_bf16 v[22:25], v[164:167], v[206:209], v[22:25]
	v_mfma_f32_16x16x32_bf16 v[14:17], v[172:175], v[206:209], v[14:17]
	v_mfma_f32_16x16x32_bf16 v[6:9], v[164:167], v[214:217], v[6:9]
	v_mfma_f32_16x16x32_bf16 v[2:5], v[172:175], v[214:217], v[2:5]
	s_barrier
	s_setprio 0
.Lkmid_1:
	s_add_i32 s0, 0, 0x18000
	s_add_i32 s1, 0, 0x1c000
	ds_read_b128 v[130:133], v250 offset:32768
	ds_read_b128 v[134:137], v250 offset:33792
	ds_read_b128 v[138:141], v250 offset:34816
	ds_read_b128 v[142:145], v250 offset:35840
	ds_read_b128 v[146:149], v250 offset:49152
	ds_read_b128 v[164:167], v250 offset:50176
	ds_read_b128 v[168:171], v250 offset:51200
	ds_read_b128 v[172:175], v250 offset:52224
	s_add_u32 s48, s52, 0x158000
	s_addc_u32 s49, s53, 0
	s_mov_b32 m0, s29
	ds_read_b128 v[176:179], v189 offset:32768
	ds_read_b128 v[180:183], v189 offset:33792
	ds_read_b128 v[184:187], v189 offset:34816
	ds_read_b128 v[190:193], v189 offset:35840
	ds_read_b128 v[202:205], v189 offset:36864
	ds_read_b128 v[206:209], v189 offset:37888
	ds_read_b128 v[210:213], v189 offset:38912
	ds_read_b128 v[214:217], v189 offset:39936
	global_load_lds_dwordx4 v150, s[48:49]
	s_mov_b32 m0, s30
	s_nop 0
	global_load_lds_dwordx4 v152, s[48:49]
	s_waitcnt vmcnt(8)
	s_waitcnt lgkmcnt(0)
	s_setprio 1
	s_barrier
	v_mfma_f32_16x16x32_bf16 v[126:129], v[130:133], v[176:179], v[126:129]
	v_mfma_f32_16x16x32_bf16 v[122:125], v[138:141], v[176:179], v[122:125]
	v_mfma_f32_16x16x32_bf16 v[110:113], v[130:133], v[184:187], v[110:113]
	v_mfma_f32_16x16x32_bf16 v[106:109], v[138:141], v[184:187], v[106:109]
	v_mfma_f32_16x16x32_bf16 v[98:101], v[130:133], v[202:205], v[98:101]
	v_mfma_f32_16x16x32_bf16 v[90:93], v[138:141], v[202:205], v[90:93]
	v_mfma_f32_16x16x32_bf16 v[82:85], v[130:133], v[210:213], v[82:85]
	v_mfma_f32_16x16x32_bf16 v[74:77], v[138:141], v[210:213], v[74:77]
	v_mfma_f32_16x16x32_bf16 v[126:129], v[134:137], v[180:183], v[126:129]
	v_mfma_f32_16x16x32_bf16 v[122:125], v[142:145], v[180:183], v[122:125]
	v_mfma_f32_16x16x32_bf16 v[110:113], v[134:137], v[190:193], v[110:113]
	v_mfma_f32_16x16x32_bf16 v[106:109], v[142:145], v[190:193], v[106:109]
	v_mfma_f32_16x16x32_bf16 v[98:101], v[134:137], v[206:209], v[98:101]
	v_mfma_f32_16x16x32_bf16 v[90:93], v[142:145], v[206:209], v[90:93]
	v_mfma_f32_16x16x32_bf16 v[82:85], v[134:137], v[214:217], v[82:85]
	v_mfma_f32_16x16x32_bf16 v[74:77], v[142:145], v[214:217], v[74:77]
	v_mfma_f32_16x16x32_bf16 v[118:121], v[146:149], v[176:179], v[118:121]
	v_mfma_f32_16x16x32_bf16 v[114:117], v[168:171], v[176:179], v[114:117]
	v_mfma_f32_16x16x32_bf16 v[102:105], v[146:149], v[184:187], v[102:105]
	v_mfma_f32_16x16x32_bf16 v[94:97], v[168:171], v[184:187], v[94:97]
	v_mfma_f32_16x16x32_bf16 v[86:89], v[146:149], v[202:205], v[86:89]
	v_mfma_f32_16x16x32_bf16 v[78:81], v[168:171], v[202:205], v[78:81]
	v_mfma_f32_16x16x32_bf16 v[70:73], v[146:149], v[210:213], v[70:73]
	v_mfma_f32_16x16x32_bf16 v[66:69], v[168:171], v[210:213], v[66:69]
	v_mfma_f32_16x16x32_bf16 v[118:121], v[164:167], v[180:183], v[118:121]
	v_mfma_f32_16x16x32_bf16 v[114:117], v[172:175], v[180:183], v[114:117]
	v_mfma_f32_16x16x32_bf16 v[102:105], v[164:167], v[190:193], v[102:105]
	v_mfma_f32_16x16x32_bf16 v[94:97], v[172:175], v[190:193], v[94:97]
	v_mfma_f32_16x16x32_bf16 v[86:89], v[164:167], v[206:209], v[86:89]
	v_mfma_f32_16x16x32_bf16 v[78:81], v[172:175], v[206:209], v[78:81]
	v_mfma_f32_16x16x32_bf16 v[70:73], v[164:167], v[214:217], v[70:73]
	v_mfma_f32_16x16x32_bf16 v[66:69], v[172:175], v[214:217], v[66:69]
	s_barrier
	s_setprio 0
	s_add_i32 s0, s0, s26
	s_mov_b32 m0, s0
	ds_read_b128 v[176:179], v189 offset:49152
	ds_read_b128 v[180:183], v189 offset:50176
	ds_read_b128 v[184:187], v189 offset:51200
	ds_read_b128 v[190:193], v189 offset:52224
	ds_read_b128 v[202:205], v189 offset:53248
	ds_read_b128 v[206:209], v189 offset:54272
	ds_read_b128 v[210:213], v189 offset:55296
	ds_read_b128 v[214:217], v189 offset:56320
	global_load_lds_dwordx4 v196, s[98:99]
	s_add_i32 m0, s0, 0x2000
	s_add_u32 s48, s50, 0x158080
	s_addc_u32 s49, s51, 0
	s_add_i32 s0, s1, s26
	global_load_lds_dwordx4 v154, s[98:99]
	s_mov_b32 m0, s0
	s_nop 0
	global_load_lds_dwordx4 v196, s[48:49]
	s_add_i32 m0, s0, 0x2000
	s_nop 0
	global_load_lds_dwordx4 v154, s[48:49]
	s_mov_b32 m0, s35
	s_nop 0
	global_load_lds_dwordx4 v150, s[78:79]
	s_mov_b32 m0, s58
	s_nop 0
	global_load_lds_dwordx4 v152, s[78:79]
	s_waitcnt vmcnt(8)
	s_waitcnt lgkmcnt(0)
	s_setprio 1
	s_barrier
	v_mfma_f32_16x16x32_bf16 v[62:65], v[130:133], v[176:179], v[62:65]
	v_mfma_f32_16x16x32_bf16 v[58:61], v[138:141], v[176:179], v[58:61]
	v_mfma_f32_16x16x32_bf16 v[50:53], v[130:133], v[184:187], v[50:53]
	v_mfma_f32_16x16x32_bf16 v[42:45], v[138:141], v[184:187], v[42:45]
	v_mfma_f32_16x16x32_bf16 v[34:37], v[130:133], v[202:205], v[34:37]
	v_mfma_f32_16x16x32_bf16 v[26:29], v[138:141], v[202:205], v[26:29]
	v_mfma_f32_16x16x32_bf16 v[18:21], v[130:133], v[210:213], v[18:21]
	v_mfma_f32_16x16x32_bf16 v[10:13], v[138:141], v[210:213], v[10:13]
	v_mfma_f32_16x16x32_bf16 v[62:65], v[134:137], v[180:183], v[62:65]
	v_mfma_f32_16x16x32_bf16 v[58:61], v[142:145], v[180:183], v[58:61]
	v_mfma_f32_16x16x32_bf16 v[50:53], v[134:137], v[190:193], v[50:53]
	v_mfma_f32_16x16x32_bf16 v[42:45], v[142:145], v[190:193], v[42:45]
	v_mfma_f32_16x16x32_bf16 v[34:37], v[134:137], v[206:209], v[34:37]
	v_mfma_f32_16x16x32_bf16 v[26:29], v[142:145], v[206:209], v[26:29]
	v_mfma_f32_16x16x32_bf16 v[18:21], v[134:137], v[214:217], v[18:21]
	v_mfma_f32_16x16x32_bf16 v[10:13], v[142:145], v[214:217], v[10:13]
	v_mfma_f32_16x16x32_bf16 v[54:57], v[146:149], v[176:179], v[54:57]
	v_mfma_f32_16x16x32_bf16 v[46:49], v[168:171], v[176:179], v[46:49]
	v_mfma_f32_16x16x32_bf16 v[38:41], v[146:149], v[184:187], v[38:41]
	v_mfma_f32_16x16x32_bf16 v[30:33], v[168:171], v[184:187], v[30:33]
	v_mfma_f32_16x16x32_bf16 v[22:25], v[146:149], v[202:205], v[22:25]
	v_mfma_f32_16x16x32_bf16 v[14:17], v[168:171], v[202:205], v[14:17]
	v_mfma_f32_16x16x32_bf16 v[6:9], v[146:149], v[210:213], v[6:9]
	v_mfma_f32_16x16x32_bf16 v[2:5], v[168:171], v[210:213], v[2:5]
	v_mfma_f32_16x16x32_bf16 v[54:57], v[164:167], v[180:183], v[54:57]
	v_mfma_f32_16x16x32_bf16 v[46:49], v[172:175], v[180:183], v[46:49]
	v_mfma_f32_16x16x32_bf16 v[38:41], v[164:167], v[190:193], v[38:41]
	v_mfma_f32_16x16x32_bf16 v[30:33], v[172:175], v[190:193], v[30:33]
	v_mfma_f32_16x16x32_bf16 v[22:25], v[164:167], v[206:209], v[22:25]
	v_mfma_f32_16x16x32_bf16 v[14:17], v[172:175], v[206:209], v[14:17]
	v_mfma_f32_16x16x32_bf16 v[6:9], v[164:167], v[214:217], v[6:9]
	v_mfma_f32_16x16x32_bf16 v[2:5], v[172:175], v[214:217], v[2:5]
	s_barrier
	s_setprio 0
	s_add_u32 s70, s70, 0x100
	s_addc_u32 s71, s71, 0
	s_cmp_ge_i32 s72, s69
	s_mov_b64 s[48:49], s[8:9]
	s_mov_b32 s50, s72
	s_cbranch_scc0 .LBB0_987
	s_and_b64 vcc, exec, s[38:39]
	s_cbranch_vccz .LBB0_990
	s_barrier

.Ldefbar_skip_2:
	v_add_u32_e32 v250, 0x10000, v149
	s_add_i32 s71, s8, 2
	s_add_u32 s0, s58, 0xfff80080
	s_addc_u32 s1, s59, -1
	s_add_i32 s72, 0, 0x10000
	s_cmp_eq_u32 s68, s8
	s_cselect_b32 s63, s43, s1
	s_cselect_b32 s62, s47, s0
	s_cselect_b32 s9, s45, s70
	s_cselect_b32 s8, s67, s69
	s_add_i32 s0, 0, 0x14000
	ds_read_b128 v[142:145], v250
	ds_read_b128 v[152:155], v250 offset:1024
	ds_read_b128 v[156:159], v250 offset:2048
	ds_read_b128 v[160:163], v250 offset:3072
	ds_read_b128 v[164:167], v250 offset:16384
	ds_read_b128 v[168:171], v250 offset:17408
	ds_read_b128 v[172:175], v250 offset:18432
	ds_read_b128 v[176:179], v250 offset:19456
	s_add_i32 m0, s27, 0xc000
	ds_read_b128 v[180:183], v151
	ds_read_b128 v[184:187], v151 offset:1024
	ds_read_b128 v[188:191], v151 offset:2048
	ds_read_b128 v[192:195], v151 offset:3072
	ds_read_b128 v[202:205], v151 offset:4096
	ds_read_b128 v[206:209], v151 offset:5120
	ds_read_b128 v[210:213], v151 offset:6144
	ds_read_b128 v[214:217], v151 offset:7168
	global_load_lds_dwordx4 v140, s[58:59]
	s_add_i32 m0, s27, 0xe000
	s_nop 0
	global_load_lds_dwordx4 v138, s[58:59]
	s_waitcnt vmcnt(8)
	s_waitcnt lgkmcnt(0)
	s_setprio 1
	s_barrier
	v_mfma_f32_16x16x32_bf16 v[126:129], v[142:145], v[180:183], 0
	v_mfma_f32_16x16x32_bf16 v[122:125], v[156:159], v[180:183], 0
	v_mfma_f32_16x16x32_bf16 v[118:121], v[142:145], v[188:191], 0
	v_mfma_f32_16x16x32_bf16 v[110:113], v[156:159], v[188:191], 0
	v_mfma_f32_16x16x32_bf16 v[102:105], v[142:145], v[202:205], 0
	v_mfma_f32_16x16x32_bf16 v[94:97], v[156:159], v[202:205], 0
	v_mfma_f32_16x16x32_bf16 v[86:89], v[142:145], v[210:213], 0
	v_mfma_f32_16x16x32_bf16 v[78:81], v[156:159], v[210:213], 0
	v_mfma_f32_16x16x32_bf16 v[126:129], v[152:155], v[184:187], v[126:129]
	v_mfma_f32_16x16x32_bf16 v[122:125], v[160:163], v[184:187], v[122:125]
	v_mfma_f32_16x16x32_bf16 v[118:121], v[152:155], v[192:195], v[118:121]
	v_mfma_f32_16x16x32_bf16 v[110:113], v[160:163], v[192:195], v[110:113]
	v_mfma_f32_16x16x32_bf16 v[102:105], v[152:155], v[206:209], v[102:105]
	v_mfma_f32_16x16x32_bf16 v[94:97], v[160:163], v[206:209], v[94:97]
	v_mfma_f32_16x16x32_bf16 v[86:89], v[152:155], v[214:217], v[86:89]
	v_mfma_f32_16x16x32_bf16 v[78:81], v[160:163], v[214:217], v[78:81]
	v_mfma_f32_16x16x32_bf16 v[114:117], v[164:167], v[180:183], 0
	v_mfma_f32_16x16x32_bf16 v[106:109], v[172:175], v[180:183], 0
	v_mfma_f32_16x16x32_bf16 v[98:101], v[164:167], v[188:191], 0
	v_mfma_f32_16x16x32_bf16 v[90:93], v[172:175], v[188:191], 0
	v_mfma_f32_16x16x32_bf16 v[82:85], v[164:167], v[202:205], 0
	v_mfma_f32_16x16x32_bf16 v[74:77], v[172:175], v[202:205], 0
	v_mfma_f32_16x16x32_bf16 v[70:73], v[164:167], v[210:213], 0
	v_mfma_f32_16x16x32_bf16 v[66:69], v[172:175], v[210:213], 0
	v_mfma_f32_16x16x32_bf16 v[114:117], v[168:171], v[184:187], v[114:117]
	v_mfma_f32_16x16x32_bf16 v[106:109], v[176:179], v[184:187], v[106:109]
	v_mfma_f32_16x16x32_bf16 v[98:101], v[168:171], v[192:195], v[98:101]
	v_mfma_f32_16x16x32_bf16 v[90:93], v[176:179], v[192:195], v[90:93]
	v_mfma_f32_16x16x32_bf16 v[82:85], v[168:171], v[206:209], v[82:85]
	v_mfma_f32_16x16x32_bf16 v[74:77], v[176:179], v[206:209], v[74:77]
	v_mfma_f32_16x16x32_bf16 v[70:73], v[168:171], v[214:217], v[70:73]
	v_mfma_f32_16x16x32_bf16 v[66:69], v[176:179], v[214:217], v[66:69]
	s_barrier
	s_setprio 0
	s_add_i32 s1, s72, s26
	s_add_u32 s98, s8, s16
	s_addc_u32 s99, s9, s17
	s_mov_b32 m0, s1
	ds_read_b128 v[180:183], v151 offset:16384
	ds_read_b128 v[184:187], v151 offset:17408
	ds_read_b128 v[188:191], v151 offset:18432
	ds_read_b128 v[192:195], v151 offset:19456
	ds_read_b128 v[202:205], v151 offset:20480
	ds_read_b128 v[206:209], v151 offset:21504
	ds_read_b128 v[210:213], v151 offset:22528
	ds_read_b128 v[214:217], v151 offset:23552
	global_load_lds_dwordx4 v196, s[8:9]
	s_add_i32 m0, s1, 0x2000
	s_add_u32 s72, s8, 0x80000
	s_addc_u32 s73, s9, 0
	s_add_i32 s0, s0, s26
	global_load_lds_dwordx4 v130, s[8:9]
	s_mov_b32 m0, s0
	s_nop 0
	global_load_lds_dwordx4 v196, s[72:73]
	s_add_i32 m0, s0, 0x2000
	s_nop 0
	global_load_lds_dwordx4 v130, s[72:73]
	s_add_u32 s78, s62, s16
	s_addc_u32 s79, s63, s17
	s_mov_b32 m0, s27
	s_nop 0
	global_load_lds_dwordx4 v134, s[62:63]
	s_mov_b32 m0, s28
	s_nop 0
	global_load_lds_dwordx4 v132, s[62:63]
	s_waitcnt vmcnt(8)
	s_waitcnt lgkmcnt(0)
	s_setprio 1
	s_barrier
	v_mfma_f32_16x16x32_bf16 v[62:65], v[142:145], v[180:183], 0
	v_mfma_f32_16x16x32_bf16 v[58:61], v[156:159], v[180:183], 0
	v_mfma_f32_16x16x32_bf16 v[54:57], v[142:145], v[188:191], 0
	v_mfma_f32_16x16x32_bf16 v[46:49], v[156:159], v[188:191], 0
	v_mfma_f32_16x16x32_bf16 v[38:41], v[142:145], v[202:205], 0
	v_mfma_f32_16x16x32_bf16 v[30:33], v[156:159], v[202:205], 0
	v_mfma_f32_16x16x32_bf16 v[22:25], v[142:145], v[210:213], 0
	v_mfma_f32_16x16x32_bf16 v[14:17], v[156:159], v[210:213], 0
	v_mfma_f32_16x16x32_bf16 v[62:65], v[152:155], v[184:187], v[62:65]
	v_mfma_f32_16x16x32_bf16 v[58:61], v[160:163], v[184:187], v[58:61]
	v_mfma_f32_16x16x32_bf16 v[54:57], v[152:155], v[192:195], v[54:57]
	v_mfma_f32_16x16x32_bf16 v[46:49], v[160:163], v[192:195], v[46:49]
	v_mfma_f32_16x16x32_bf16 v[38:41], v[152:155], v[206:209], v[38:41]
	v_mfma_f32_16x16x32_bf16 v[30:33], v[160:163], v[206:209], v[30:33]
	v_mfma_f32_16x16x32_bf16 v[22:25], v[152:155], v[214:217], v[22:25]
	v_mfma_f32_16x16x32_bf16 v[14:17], v[160:163], v[214:217], v[14:17]
	v_mfma_f32_16x16x32_bf16 v[50:53], v[164:167], v[180:183], 0
	v_mfma_f32_16x16x32_bf16 v[42:45], v[172:175], v[180:183], 0
	v_mfma_f32_16x16x32_bf16 v[34:37], v[164:167], v[188:191], 0
	v_mfma_f32_16x16x32_bf16 v[26:29], v[172:175], v[188:191], 0
	v_mfma_f32_16x16x32_bf16 v[18:21], v[164:167], v[202:205], 0
	v_mfma_f32_16x16x32_bf16 v[10:13], v[172:175], v[202:205], 0
	v_mfma_f32_16x16x32_bf16 v[6:9], v[164:167], v[210:213], 0
	v_mfma_f32_16x16x32_bf16 v[2:5], v[172:175], v[210:213], 0
	v_mfma_f32_16x16x32_bf16 v[50:53], v[168:171], v[184:187], v[50:53]
	v_mfma_f32_16x16x32_bf16 v[42:45], v[176:179], v[184:187], v[42:45]
	v_mfma_f32_16x16x32_bf16 v[34:37], v[168:171], v[192:195], v[34:37]
	v_mfma_f32_16x16x32_bf16 v[26:29], v[176:179], v[192:195], v[26:29]
	v_mfma_f32_16x16x32_bf16 v[18:21], v[168:171], v[206:209], v[18:21]
	v_mfma_f32_16x16x32_bf16 v[10:13], v[176:179], v[206:209], v[10:13]
	v_mfma_f32_16x16x32_bf16 v[6:9], v[168:171], v[214:217], v[6:9]
	v_mfma_f32_16x16x32_bf16 v[2:5], v[176:179], v[214:217], v[2:5]
	s_barrier
	s_setprio 0
	s_branch .Lkmid_2
.LBB0_1135:
	s_add_i32 s71, s8, 2
	s_add_u32 s0, s58, 0xfff80080
	s_addc_u32 s1, s59, -1
	s_add_i32 s72, 0, 0x10000
	s_cmp_eq_u32 s68, s8
	s_cselect_b32 s63, s43, s1
	s_cselect_b32 s62, s47, s0
	s_cselect_b32 s9, s45, s70
	s_cselect_b32 s8, s67, s69
	s_add_i32 s0, 0, 0x14000
	ds_read_b128 v[142:145], v250
	ds_read_b128 v[152:155], v250 offset:1024
	ds_read_b128 v[156:159], v250 offset:2048
	ds_read_b128 v[160:163], v250 offset:3072
	ds_read_b128 v[164:167], v250 offset:16384
	ds_read_b128 v[168:171], v250 offset:17408
	ds_read_b128 v[172:175], v250 offset:18432
	ds_read_b128 v[176:179], v250 offset:19456
	s_add_i32 m0, s27, 0xc000
	ds_read_b128 v[180:183], v151
	ds_read_b128 v[184:187], v151 offset:1024
	ds_read_b128 v[188:191], v151 offset:2048
	ds_read_b128 v[192:195], v151 offset:3072
	ds_read_b128 v[202:205], v151 offset:4096
	ds_read_b128 v[206:209], v151 offset:5120
	ds_read_b128 v[210:213], v151 offset:6144
	ds_read_b128 v[214:217], v151 offset:7168
	global_load_lds_dwordx4 v140, s[58:59]
	s_add_i32 m0, s27, 0xe000
	s_nop 0
	global_load_lds_dwordx4 v138, s[58:59]
	s_waitcnt vmcnt(8)
	s_waitcnt lgkmcnt(0)
	s_setprio 1
	s_barrier
	v_mfma_f32_16x16x32_bf16 v[126:129], v[142:145], v[180:183], v[126:129]
	v_mfma_f32_16x16x32_bf16 v[122:125], v[156:159], v[180:183], v[122:125]
	v_mfma_f32_16x16x32_bf16 v[118:121], v[142:145], v[188:191], v[118:121]
	v_mfma_f32_16x16x32_bf16 v[110:113], v[156:159], v[188:191], v[110:113]
	v_mfma_f32_16x16x32_bf16 v[102:105], v[142:145], v[202:205], v[102:105]
	v_mfma_f32_16x16x32_bf16 v[94:97], v[156:159], v[202:205], v[94:97]
	v_mfma_f32_16x16x32_bf16 v[86:89], v[142:145], v[210:213], v[86:89]
	v_mfma_f32_16x16x32_bf16 v[78:81], v[156:159], v[210:213], v[78:81]
	v_mfma_f32_16x16x32_bf16 v[126:129], v[152:155], v[184:187], v[126:129]
	v_mfma_f32_16x16x32_bf16 v[122:125], v[160:163], v[184:187], v[122:125]
	v_mfma_f32_16x16x32_bf16 v[118:121], v[152:155], v[192:195], v[118:121]
	v_mfma_f32_16x16x32_bf16 v[110:113], v[160:163], v[192:195], v[110:113]
	v_mfma_f32_16x16x32_bf16 v[102:105], v[152:155], v[206:209], v[102:105]
	v_mfma_f32_16x16x32_bf16 v[94:97], v[160:163], v[206:209], v[94:97]
	v_mfma_f32_16x16x32_bf16 v[86:89], v[152:155], v[214:217], v[86:89]
	v_mfma_f32_16x16x32_bf16 v[78:81], v[160:163], v[214:217], v[78:81]
	v_mfma_f32_16x16x32_bf16 v[114:117], v[164:167], v[180:183], v[114:117]
	v_mfma_f32_16x16x32_bf16 v[106:109], v[172:175], v[180:183], v[106:109]
	v_mfma_f32_16x16x32_bf16 v[98:101], v[164:167], v[188:191], v[98:101]
	v_mfma_f32_16x16x32_bf16 v[90:93], v[172:175], v[188:191], v[90:93]
	v_mfma_f32_16x16x32_bf16 v[82:85], v[164:167], v[202:205], v[82:85]
	v_mfma_f32_16x16x32_bf16 v[74:77], v[172:175], v[202:205], v[74:77]
	v_mfma_f32_16x16x32_bf16 v[70:73], v[164:167], v[210:213], v[70:73]
	v_mfma_f32_16x16x32_bf16 v[66:69], v[172:175], v[210:213], v[66:69]
	v_mfma_f32_16x16x32_bf16 v[114:117], v[168:171], v[184:187], v[114:117]
	v_mfma_f32_16x16x32_bf16 v[106:109], v[176:179], v[184:187], v[106:109]
	v_mfma_f32_16x16x32_bf16 v[98:101], v[168:171], v[192:195], v[98:101]
	v_mfma_f32_16x16x32_bf16 v[90:93], v[176:179], v[192:195], v[90:93]
	v_mfma_f32_16x16x32_bf16 v[82:85], v[168:171], v[206:209], v[82:85]
	v_mfma_f32_16x16x32_bf16 v[74:77], v[176:179], v[206:209], v[74:77]
	v_mfma_f32_16x16x32_bf16 v[70:73], v[168:171], v[214:217], v[70:73]
	v_mfma_f32_16x16x32_bf16 v[66:69], v[176:179], v[214:217], v[66:69]
	s_barrier
	s_setprio 0
	s_add_i32 s1, s72, s26
	s_add_u32 s98, s8, s16
	s_addc_u32 s99, s9, s17
	s_mov_b32 m0, s1
	ds_read_b128 v[180:183], v151 offset:16384
	ds_read_b128 v[184:187], v151 offset:17408
	ds_read_b128 v[188:191], v151 offset:18432
	ds_read_b128 v[192:195], v151 offset:19456
	ds_read_b128 v[202:205], v151 offset:20480
	ds_read_b128 v[206:209], v151 offset:21504
	ds_read_b128 v[210:213], v151 offset:22528
	ds_read_b128 v[214:217], v151 offset:23552
	global_load_lds_dwordx4 v196, s[8:9]
	s_add_i32 m0, s1, 0x2000
	s_add_u32 s72, s8, 0x80000
	s_addc_u32 s73, s9, 0
	s_add_i32 s0, s0, s26
	global_load_lds_dwordx4 v130, s[8:9]
	s_mov_b32 m0, s0
	s_nop 0
	global_load_lds_dwordx4 v196, s[72:73]
	s_add_i32 m0, s0, 0x2000
	s_nop 0
	global_load_lds_dwordx4 v130, s[72:73]
	s_add_u32 s78, s62, s16
	s_addc_u32 s79, s63, s17
	s_mov_b32 m0, s27
	s_nop 0
	global_load_lds_dwordx4 v134, s[62:63]
	s_mov_b32 m0, s28
	s_nop 0
	global_load_lds_dwordx4 v132, s[62:63]
	s_waitcnt vmcnt(8)
	s_waitcnt lgkmcnt(0)
	s_setprio 1
	s_barrier
	v_mfma_f32_16x16x32_bf16 v[62:65], v[142:145], v[180:183], v[62:65]
	v_mfma_f32_16x16x32_bf16 v[58:61], v[156:159], v[180:183], v[58:61]
	v_mfma_f32_16x16x32_bf16 v[54:57], v[142:145], v[188:191], v[54:57]
	v_mfma_f32_16x16x32_bf16 v[46:49], v[156:159], v[188:191], v[46:49]
	v_mfma_f32_16x16x32_bf16 v[38:41], v[142:145], v[202:205], v[38:41]
	v_mfma_f32_16x16x32_bf16 v[30:33], v[156:159], v[202:205], v[30:33]
	v_mfma_f32_16x16x32_bf16 v[22:25], v[142:145], v[210:213], v[22:25]
	v_mfma_f32_16x16x32_bf16 v[14:17], v[156:159], v[210:213], v[14:17]
	v_mfma_f32_16x16x32_bf16 v[62:65], v[152:155], v[184:187], v[62:65]
	v_mfma_f32_16x16x32_bf16 v[58:61], v[160:163], v[184:187], v[58:61]
	v_mfma_f32_16x16x32_bf16 v[54:57], v[152:155], v[192:195], v[54:57]
	v_mfma_f32_16x16x32_bf16 v[46:49], v[160:163], v[192:195], v[46:49]
	v_mfma_f32_16x16x32_bf16 v[38:41], v[152:155], v[206:209], v[38:41]
	v_mfma_f32_16x16x32_bf16 v[30:33], v[160:163], v[206:209], v[30:33]
	v_mfma_f32_16x16x32_bf16 v[22:25], v[152:155], v[214:217], v[22:25]
	v_mfma_f32_16x16x32_bf16 v[14:17], v[160:163], v[214:217], v[14:17]
	v_mfma_f32_16x16x32_bf16 v[50:53], v[164:167], v[180:183], v[50:53]
	v_mfma_f32_16x16x32_bf16 v[42:45], v[172:175], v[180:183], v[42:45]
	v_mfma_f32_16x16x32_bf16 v[34:37], v[164:167], v[188:191], v[34:37]
	v_mfma_f32_16x16x32_bf16 v[26:29], v[172:175], v[188:191], v[26:29]
	v_mfma_f32_16x16x32_bf16 v[18:21], v[164:167], v[202:205], v[18:21]
	v_mfma_f32_16x16x32_bf16 v[10:13], v[172:175], v[202:205], v[10:13]
	v_mfma_f32_16x16x32_bf16 v[6:9], v[164:167], v[210:213], v[6:9]
	v_mfma_f32_16x16x32_bf16 v[2:5], v[172:175], v[210:213], v[2:5]
	v_mfma_f32_16x16x32_bf16 v[50:53], v[168:171], v[184:187], v[50:53]
	v_mfma_f32_16x16x32_bf16 v[42:45], v[176:179], v[184:187], v[42:45]
	v_mfma_f32_16x16x32_bf16 v[34:37], v[168:171], v[192:195], v[34:37]
	v_mfma_f32_16x16x32_bf16 v[26:29], v[176:179], v[192:195], v[26:29]
	v_mfma_f32_16x16x32_bf16 v[18:21], v[168:171], v[206:209], v[18:21]
	v_mfma_f32_16x16x32_bf16 v[10:13], v[176:179], v[206:209], v[10:13]
	v_mfma_f32_16x16x32_bf16 v[6:9], v[168:171], v[214:217], v[6:9]
	v_mfma_f32_16x16x32_bf16 v[2:5], v[176:179], v[214:217], v[2:5]
	s_barrier
	s_setprio 0
.Lkmid_2:
	s_add_i32 s0, 0, 0x18000
	s_add_i32 s1, 0, 0x1c000
	ds_read_b128 v[142:145], v250 offset:32768
	ds_read_b128 v[152:155], v250 offset:33792
	ds_read_b128 v[156:159], v250 offset:34816
	ds_read_b128 v[160:163], v250 offset:35840
	ds_read_b128 v[164:167], v250 offset:49152
	ds_read_b128 v[168:171], v250 offset:50176
	ds_read_b128 v[172:175], v250 offset:51200
	ds_read_b128 v[176:179], v250 offset:52224
	s_add_u32 s62, s62, 0x80000
	s_addc_u32 s63, s63, 0
	s_mov_b32 m0, s29
	ds_read_b128 v[180:183], v151 offset:32768
	ds_read_b128 v[184:187], v151 offset:33792
	ds_read_b128 v[188:191], v151 offset:34816
	ds_read_b128 v[192:195], v151 offset:35840
	ds_read_b128 v[202:205], v151 offset:36864
	ds_read_b128 v[206:209], v151 offset:37888
	ds_read_b128 v[210:213], v151 offset:38912
	ds_read_b128 v[214:217], v151 offset:39936
	global_load_lds_dwordx4 v134, s[62:63]
	s_mov_b32 m0, s30
	s_nop 0
	global_load_lds_dwordx4 v132, s[62:63]
	s_waitcnt vmcnt(8)
	s_waitcnt lgkmcnt(0)
	s_setprio 1
	s_barrier
	v_mfma_f32_16x16x32_bf16 v[126:129], v[142:145], v[180:183], v[126:129]
	v_mfma_f32_16x16x32_bf16 v[122:125], v[156:159], v[180:183], v[122:125]
	v_mfma_f32_16x16x32_bf16 v[118:121], v[142:145], v[188:191], v[118:121]
	v_mfma_f32_16x16x32_bf16 v[110:113], v[156:159], v[188:191], v[110:113]
	v_mfma_f32_16x16x32_bf16 v[102:105], v[142:145], v[202:205], v[102:105]
	v_mfma_f32_16x16x32_bf16 v[94:97], v[156:159], v[202:205], v[94:97]
	v_mfma_f32_16x16x32_bf16 v[86:89], v[142:145], v[210:213], v[86:89]
	v_mfma_f32_16x16x32_bf16 v[78:81], v[156:159], v[210:213], v[78:81]
	v_mfma_f32_16x16x32_bf16 v[126:129], v[152:155], v[184:187], v[126:129]
	v_mfma_f32_16x16x32_bf16 v[122:125], v[160:163], v[184:187], v[122:125]
	v_mfma_f32_16x16x32_bf16 v[118:121], v[152:155], v[192:195], v[118:121]
	v_mfma_f32_16x16x32_bf16 v[110:113], v[160:163], v[192:195], v[110:113]
	v_mfma_f32_16x16x32_bf16 v[102:105], v[152:155], v[206:209], v[102:105]
	v_mfma_f32_16x16x32_bf16 v[94:97], v[160:163], v[206:209], v[94:97]
	v_mfma_f32_16x16x32_bf16 v[86:89], v[152:155], v[214:217], v[86:89]
	v_mfma_f32_16x16x32_bf16 v[78:81], v[160:163], v[214:217], v[78:81]
	v_mfma_f32_16x16x32_bf16 v[114:117], v[164:167], v[180:183], v[114:117]
	v_mfma_f32_16x16x32_bf16 v[106:109], v[172:175], v[180:183], v[106:109]
	v_mfma_f32_16x16x32_bf16 v[98:101], v[164:167], v[188:191], v[98:101]
	v_mfma_f32_16x16x32_bf16 v[90:93], v[172:175], v[188:191], v[90:93]
	v_mfma_f32_16x16x32_bf16 v[82:85], v[164:167], v[202:205], v[82:85]
	v_mfma_f32_16x16x32_bf16 v[74:77], v[172:175], v[202:205], v[74:77]
	v_mfma_f32_16x16x32_bf16 v[70:73], v[164:167], v[210:213], v[70:73]
	v_mfma_f32_16x16x32_bf16 v[66:69], v[172:175], v[210:213], v[66:69]
	v_mfma_f32_16x16x32_bf16 v[114:117], v[168:171], v[184:187], v[114:117]
	v_mfma_f32_16x16x32_bf16 v[106:109], v[176:179], v[184:187], v[106:109]
	v_mfma_f32_16x16x32_bf16 v[98:101], v[168:171], v[192:195], v[98:101]
	v_mfma_f32_16x16x32_bf16 v[90:93], v[176:179], v[192:195], v[90:93]
	v_mfma_f32_16x16x32_bf16 v[82:85], v[168:171], v[206:209], v[82:85]
	v_mfma_f32_16x16x32_bf16 v[74:77], v[176:179], v[206:209], v[74:77]
	v_mfma_f32_16x16x32_bf16 v[70:73], v[168:171], v[214:217], v[70:73]
	v_mfma_f32_16x16x32_bf16 v[66:69], v[176:179], v[214:217], v[66:69]
	s_barrier
	s_setprio 0
	s_add_i32 s0, s0, s26
	s_mov_b32 m0, s0
	ds_read_b128 v[180:183], v151 offset:49152
	ds_read_b128 v[184:187], v151 offset:50176
	ds_read_b128 v[188:191], v151 offset:51200
	ds_read_b128 v[192:195], v151 offset:52224
	ds_read_b128 v[202:205], v151 offset:53248
	ds_read_b128 v[206:209], v151 offset:54272
	ds_read_b128 v[210:213], v151 offset:55296
	ds_read_b128 v[214:217], v151 offset:56320
	global_load_lds_dwordx4 v196, s[98:99]
	s_add_i32 m0, s0, 0x2000
	s_add_u32 s8, s8, 0x80080
	s_addc_u32 s9, s9, 0
	s_add_i32 s0, s1, s26
	global_load_lds_dwordx4 v130, s[98:99]
	s_mov_b32 m0, s0
	s_nop 0
	global_load_lds_dwordx4 v196, s[8:9]
	s_add_i32 m0, s0, 0x2000
	s_nop 0
	global_load_lds_dwordx4 v130, s[8:9]
	s_mov_b32 m0, s31
	s_nop 0
	global_load_lds_dwordx4 v134, s[78:79]
	s_mov_b32 m0, s34
	s_nop 0
	global_load_lds_dwordx4 v132, s[78:79]
	s_waitcnt vmcnt(8)
	s_waitcnt lgkmcnt(0)
	s_setprio 1
	s_barrier
	v_mfma_f32_16x16x32_bf16 v[62:65], v[142:145], v[180:183], v[62:65]
	v_mfma_f32_16x16x32_bf16 v[58:61], v[156:159], v[180:183], v[58:61]
	v_mfma_f32_16x16x32_bf16 v[54:57], v[142:145], v[188:191], v[54:57]
	v_mfma_f32_16x16x32_bf16 v[46:49], v[156:159], v[188:191], v[46:49]
	v_mfma_f32_16x16x32_bf16 v[38:41], v[142:145], v[202:205], v[38:41]
	v_mfma_f32_16x16x32_bf16 v[30:33], v[156:159], v[202:205], v[30:33]
	v_mfma_f32_16x16x32_bf16 v[22:25], v[142:145], v[210:213], v[22:25]
	v_mfma_f32_16x16x32_bf16 v[14:17], v[156:159], v[210:213], v[14:17]
	v_mfma_f32_16x16x32_bf16 v[62:65], v[152:155], v[184:187], v[62:65]
	v_mfma_f32_16x16x32_bf16 v[58:61], v[160:163], v[184:187], v[58:61]
	v_mfma_f32_16x16x32_bf16 v[54:57], v[152:155], v[192:195], v[54:57]
	v_mfma_f32_16x16x32_bf16 v[46:49], v[160:163], v[192:195], v[46:49]
	v_mfma_f32_16x16x32_bf16 v[38:41], v[152:155], v[206:209], v[38:41]
	v_mfma_f32_16x16x32_bf16 v[30:33], v[160:163], v[206:209], v[30:33]
	v_mfma_f32_16x16x32_bf16 v[22:25], v[152:155], v[214:217], v[22:25]
	v_mfma_f32_16x16x32_bf16 v[14:17], v[160:163], v[214:217], v[14:17]
	v_mfma_f32_16x16x32_bf16 v[50:53], v[164:167], v[180:183], v[50:53]
	v_mfma_f32_16x16x32_bf16 v[42:45], v[172:175], v[180:183], v[42:45]
	v_mfma_f32_16x16x32_bf16 v[34:37], v[164:167], v[188:191], v[34:37]
	v_mfma_f32_16x16x32_bf16 v[26:29], v[172:175], v[188:191], v[26:29]
	v_mfma_f32_16x16x32_bf16 v[18:21], v[164:167], v[202:205], v[18:21]
	v_mfma_f32_16x16x32_bf16 v[10:13], v[172:175], v[202:205], v[10:13]
	v_mfma_f32_16x16x32_bf16 v[6:9], v[164:167], v[210:213], v[6:9]
	v_mfma_f32_16x16x32_bf16 v[2:5], v[172:175], v[210:213], v[2:5]
	v_mfma_f32_16x16x32_bf16 v[50:53], v[168:171], v[184:187], v[50:53]
	v_mfma_f32_16x16x32_bf16 v[42:45], v[176:179], v[184:187], v[42:45]
	v_mfma_f32_16x16x32_bf16 v[34:37], v[168:171], v[192:195], v[34:37]
	v_mfma_f32_16x16x32_bf16 v[26:29], v[176:179], v[192:195], v[26:29]
	v_mfma_f32_16x16x32_bf16 v[18:21], v[168:171], v[206:209], v[18:21]
	v_mfma_f32_16x16x32_bf16 v[10:13], v[176:179], v[206:209], v[10:13]
	v_mfma_f32_16x16x32_bf16 v[6:9], v[168:171], v[214:217], v[6:9]
	v_mfma_f32_16x16x32_bf16 v[2:5], v[176:179], v[214:217], v[2:5]
	s_barrier
	s_setprio 0
	s_add_u32 s69, s69, 0x100
	s_addc_u32 s70, s70, 0
	s_add_u32 s58, s58, 0x100
	s_addc_u32 s59, s59, 0
	s_cmp_ge_i32 s71, s64
	s_mov_b32 s8, s71
	s_cbranch_scc0 .LBB0_1135
	s_and_b64 vcc, exec, s[38:39]
	s_cbranch_vccz .LBB0_1138
	s_barrier

.Ldefbar_skip_3:
	v_add_u32_e32 v250, 0x10000, v244
	s_add_i32 s73, s8, 2
	s_add_u32 s0, s44, 0xfff00080
	s_addc_u32 s1, s45, -1
	s_add_i32 s77, 0, 0x10000
	s_cmp_eq_u32 s70, s8
	s_cselect_b32 s67, s51, s1
	s_cselect_b32 s66, s53, s0
	s_cselect_b32 s9, s49, s72
	s_cselect_b32 s8, s69, s71
	s_add_i32 s78, 0, 0x14000
	ds_read_b128 v[130:133], v250
	ds_read_b128 v[134:137], v250 offset:1024
	ds_read_b128 v[138:141], v250 offset:2048
	ds_read_b128 v[142:145], v250 offset:3072
	ds_read_b128 v[146:149], v250 offset:16384
	ds_read_b128 v[150:153], v250 offset:17408
	ds_read_b128 v[154:157], v250 offset:18432
	ds_read_b128 v[158:161], v250 offset:19456
	s_add_i32 m0, s3, 0xc000
	ds_read_b128 v[162:165], v246
	ds_read_b128 v[166:169], v246 offset:1024
	ds_read_b128 v[170:173], v246 offset:2048
	ds_read_b128 v[174:177], v246 offset:3072
	ds_read_b128 v[178:181], v246 offset:4096
	ds_read_b128 v[182:185], v246 offset:5120
	ds_read_b128 v[186:189], v246 offset:6144
	ds_read_b128 v[190:193], v246 offset:7168
	global_load_lds_dwordx4 v210, s[44:45]
	s_add_i32 m0, s3, 0xe000
	s_nop 0
	global_load_lds_dwordx4 v208, s[44:45]
	s_waitcnt vmcnt(8)
	s_waitcnt lgkmcnt(0)
	s_setprio 1
	s_barrier
	v_mfma_f32_16x16x32_bf16 v[126:129], v[130:133], v[162:165], 0
	v_mfma_f32_16x16x32_bf16 v[122:125], v[138:141], v[162:165], 0
	v_mfma_f32_16x16x32_bf16 v[110:113], v[130:133], v[170:173], 0
	v_mfma_f32_16x16x32_bf16 v[106:109], v[138:141], v[170:173], 0
	v_mfma_f32_16x16x32_bf16 v[94:97], v[130:133], v[178:181], 0
	v_mfma_f32_16x16x32_bf16 v[90:93], v[138:141], v[178:181], 0
	v_mfma_f32_16x16x32_bf16 v[78:81], v[130:133], v[186:189], 0
	v_mfma_f32_16x16x32_bf16 v[74:77], v[138:141], v[186:189], 0
	v_mfma_f32_16x16x32_bf16 v[126:129], v[134:137], v[166:169], v[126:129]
	v_mfma_f32_16x16x32_bf16 v[122:125], v[142:145], v[166:169], v[122:125]
	v_mfma_f32_16x16x32_bf16 v[110:113], v[134:137], v[174:177], v[110:113]
	v_mfma_f32_16x16x32_bf16 v[106:109], v[142:145], v[174:177], v[106:109]
	v_mfma_f32_16x16x32_bf16 v[94:97], v[134:137], v[182:185], v[94:97]
	v_mfma_f32_16x16x32_bf16 v[90:93], v[142:145], v[182:185], v[90:93]
	v_mfma_f32_16x16x32_bf16 v[78:81], v[134:137], v[190:193], v[78:81]
	v_mfma_f32_16x16x32_bf16 v[74:77], v[142:145], v[190:193], v[74:77]
	v_mfma_f32_16x16x32_bf16 v[118:121], v[146:149], v[162:165], 0
	v_mfma_f32_16x16x32_bf16 v[114:117], v[154:157], v[162:165], 0
	v_mfma_f32_16x16x32_bf16 v[102:105], v[146:149], v[170:173], 0
	v_mfma_f32_16x16x32_bf16 v[98:101], v[154:157], v[170:173], 0
	v_mfma_f32_16x16x32_bf16 v[86:89], v[146:149], v[178:181], 0
	v_mfma_f32_16x16x32_bf16 v[82:85], v[154:157], v[178:181], 0
	v_mfma_f32_16x16x32_bf16 v[70:73], v[146:149], v[186:189], 0
	v_mfma_f32_16x16x32_bf16 v[66:69], v[154:157], v[186:189], 0
	v_mfma_f32_16x16x32_bf16 v[118:121], v[150:153], v[166:169], v[118:121]
	v_mfma_f32_16x16x32_bf16 v[114:117], v[158:161], v[166:169], v[114:117]
	v_mfma_f32_16x16x32_bf16 v[102:105], v[150:153], v[174:177], v[102:105]
	v_mfma_f32_16x16x32_bf16 v[98:101], v[158:161], v[174:177], v[98:101]
	v_mfma_f32_16x16x32_bf16 v[86:89], v[150:153], v[182:185], v[86:89]
	v_mfma_f32_16x16x32_bf16 v[82:85], v[158:161], v[182:185], v[82:85]
	v_mfma_f32_16x16x32_bf16 v[70:73], v[150:153], v[190:193], v[70:73]
	v_mfma_f32_16x16x32_bf16 v[66:69], v[158:161], v[190:193], v[66:69]
	s_barrier
	s_setprio 0
	s_add_i32 s0, s77, s2
	s_add_u32 s98, s8, s16
	s_addc_u32 s99, s9, s17
	s_mov_b32 m0, s0
	ds_read_b128 v[162:165], v246 offset:16384
	ds_read_b128 v[166:169], v246 offset:17408
	ds_read_b128 v[170:173], v246 offset:18432
	ds_read_b128 v[174:177], v246 offset:19456
	ds_read_b128 v[178:181], v246 offset:20480
	ds_read_b128 v[182:185], v246 offset:21504
	ds_read_b128 v[186:189], v246 offset:22528
	ds_read_b128 v[190:193], v246 offset:23552
	global_load_lds_dwordx4 v196, s[8:9]
	s_add_i32 m0, s0, 0x2000
	s_add_u32 s0, s8, 0x100000
	s_addc_u32 s1, s9, 0
	s_add_i32 s77, s78, s2
	global_load_lds_dwordx4 v202, s[8:9]
	s_mov_b32 m0, s77
	v_lshl_add_u64 v[216:217], s[66:67], 0, v[204:205]
	global_load_lds_dwordx4 v196, s[0:1]
	s_add_i32 m0, s77, 0x2000
	s_nop 0
	global_load_lds_dwordx4 v202, s[0:1]
	v_lshl_add_u64 v[214:215], s[66:67], 0, v[206:207]
	s_mov_b32 m0, s3
	s_nop 0
	global_load_lds_dwordx4 v206, s[66:67]
	s_mov_b32 m0, s10
	s_nop 0
	global_load_lds_dwordx4 v204, s[66:67]
	s_waitcnt vmcnt(8)
	s_waitcnt lgkmcnt(0)
	s_setprio 1
	s_barrier
	v_mfma_f32_16x16x32_bf16 v[62:65], v[130:133], v[162:165], 0
	v_mfma_f32_16x16x32_bf16 v[58:61], v[138:141], v[162:165], 0
	v_mfma_f32_16x16x32_bf16 v[46:49], v[130:133], v[170:173], 0
	v_mfma_f32_16x16x32_bf16 v[42:45], v[138:141], v[170:173], 0
	v_mfma_f32_16x16x32_bf16 v[30:33], v[130:133], v[178:181], 0
	v_mfma_f32_16x16x32_bf16 v[26:29], v[138:141], v[178:181], 0
	v_mfma_f32_16x16x32_bf16 v[14:17], v[130:133], v[186:189], 0
	v_mfma_f32_16x16x32_bf16 v[10:13], v[138:141], v[186:189], 0
	v_mfma_f32_16x16x32_bf16 v[62:65], v[134:137], v[166:169], v[62:65]
	v_mfma_f32_16x16x32_bf16 v[58:61], v[142:145], v[166:169], v[58:61]
	v_mfma_f32_16x16x32_bf16 v[46:49], v[134:137], v[174:177], v[46:49]
	v_mfma_f32_16x16x32_bf16 v[42:45], v[142:145], v[174:177], v[42:45]
	v_mfma_f32_16x16x32_bf16 v[30:33], v[134:137], v[182:185], v[30:33]
	v_mfma_f32_16x16x32_bf16 v[26:29], v[142:145], v[182:185], v[26:29]
	v_mfma_f32_16x16x32_bf16 v[14:17], v[134:137], v[190:193], v[14:17]
	v_mfma_f32_16x16x32_bf16 v[10:13], v[142:145], v[190:193], v[10:13]
	v_mfma_f32_16x16x32_bf16 v[54:57], v[146:149], v[162:165], 0
	v_mfma_f32_16x16x32_bf16 v[50:53], v[154:157], v[162:165], 0
	v_mfma_f32_16x16x32_bf16 v[38:41], v[146:149], v[170:173], 0
	v_mfma_f32_16x16x32_bf16 v[34:37], v[154:157], v[170:173], 0
	v_mfma_f32_16x16x32_bf16 v[22:25], v[146:149], v[178:181], 0
	v_mfma_f32_16x16x32_bf16 v[18:21], v[154:157], v[178:181], 0
	v_mfma_f32_16x16x32_bf16 v[6:9], v[146:149], v[186:189], 0
	v_mfma_f32_16x16x32_bf16 v[2:5], v[154:157], v[186:189], 0
	v_mfma_f32_16x16x32_bf16 v[54:57], v[150:153], v[166:169], v[54:57]
	v_mfma_f32_16x16x32_bf16 v[50:53], v[158:161], v[166:169], v[50:53]
	v_mfma_f32_16x16x32_bf16 v[38:41], v[150:153], v[174:177], v[38:41]
	v_mfma_f32_16x16x32_bf16 v[34:37], v[158:161], v[174:177], v[34:37]
	v_mfma_f32_16x16x32_bf16 v[22:25], v[150:153], v[182:185], v[22:25]
	v_mfma_f32_16x16x32_bf16 v[18:21], v[158:161], v[182:185], v[18:21]
	v_mfma_f32_16x16x32_bf16 v[6:9], v[150:153], v[190:193], v[6:9]
	v_mfma_f32_16x16x32_bf16 v[2:5], v[158:161], v[190:193], v[2:5]
	s_barrier
	s_setprio 0
	s_branch .Lkmid_3
.LBB0_2239:
	s_add_i32 s73, s8, 2
	s_add_u32 s0, s44, 0xfff00080
	s_addc_u32 s1, s45, -1
	s_add_i32 s77, 0, 0x10000
	s_cmp_eq_u32 s70, s8
	s_cselect_b32 s67, s51, s1
	s_cselect_b32 s66, s53, s0
	s_cselect_b32 s9, s49, s72
	s_cselect_b32 s8, s69, s71
	s_add_i32 s78, 0, 0x14000
	ds_read_b128 v[130:133], v250
	ds_read_b128 v[134:137], v250 offset:1024
	ds_read_b128 v[138:141], v250 offset:2048
	ds_read_b128 v[142:145], v250 offset:3072
	ds_read_b128 v[146:149], v250 offset:16384
	ds_read_b128 v[150:153], v250 offset:17408
	ds_read_b128 v[154:157], v250 offset:18432
	ds_read_b128 v[158:161], v250 offset:19456
	s_add_i32 m0, s3, 0xc000
	ds_read_b128 v[162:165], v246
	ds_read_b128 v[166:169], v246 offset:1024
	ds_read_b128 v[170:173], v246 offset:2048
	ds_read_b128 v[174:177], v246 offset:3072
	ds_read_b128 v[178:181], v246 offset:4096
	ds_read_b128 v[182:185], v246 offset:5120
	ds_read_b128 v[186:189], v246 offset:6144
	ds_read_b128 v[190:193], v246 offset:7168
	global_load_lds_dwordx4 v210, s[44:45]
	s_add_i32 m0, s3, 0xe000
	s_nop 0
	global_load_lds_dwordx4 v208, s[44:45]
	s_waitcnt vmcnt(8)
	s_waitcnt lgkmcnt(0)
	s_setprio 1
	s_barrier
	v_mfma_f32_16x16x32_bf16 v[126:129], v[130:133], v[162:165], v[126:129]
	v_mfma_f32_16x16x32_bf16 v[122:125], v[138:141], v[162:165], v[122:125]
	v_mfma_f32_16x16x32_bf16 v[110:113], v[130:133], v[170:173], v[110:113]
	v_mfma_f32_16x16x32_bf16 v[106:109], v[138:141], v[170:173], v[106:109]
	v_mfma_f32_16x16x32_bf16 v[94:97], v[130:133], v[178:181], v[94:97]
	v_mfma_f32_16x16x32_bf16 v[90:93], v[138:141], v[178:181], v[90:93]
	v_mfma_f32_16x16x32_bf16 v[78:81], v[130:133], v[186:189], v[78:81]
	v_mfma_f32_16x16x32_bf16 v[74:77], v[138:141], v[186:189], v[74:77]
	v_mfma_f32_16x16x32_bf16 v[126:129], v[134:137], v[166:169], v[126:129]
	v_mfma_f32_16x16x32_bf16 v[122:125], v[142:145], v[166:169], v[122:125]
	v_mfma_f32_16x16x32_bf16 v[110:113], v[134:137], v[174:177], v[110:113]
	v_mfma_f32_16x16x32_bf16 v[106:109], v[142:145], v[174:177], v[106:109]
	v_mfma_f32_16x16x32_bf16 v[94:97], v[134:137], v[182:185], v[94:97]
	v_mfma_f32_16x16x32_bf16 v[90:93], v[142:145], v[182:185], v[90:93]
	v_mfma_f32_16x16x32_bf16 v[78:81], v[134:137], v[190:193], v[78:81]
	v_mfma_f32_16x16x32_bf16 v[74:77], v[142:145], v[190:193], v[74:77]
	v_mfma_f32_16x16x32_bf16 v[118:121], v[146:149], v[162:165], v[118:121]
	v_mfma_f32_16x16x32_bf16 v[114:117], v[154:157], v[162:165], v[114:117]
	v_mfma_f32_16x16x32_bf16 v[102:105], v[146:149], v[170:173], v[102:105]
	v_mfma_f32_16x16x32_bf16 v[98:101], v[154:157], v[170:173], v[98:101]
	v_mfma_f32_16x16x32_bf16 v[86:89], v[146:149], v[178:181], v[86:89]
	v_mfma_f32_16x16x32_bf16 v[82:85], v[154:157], v[178:181], v[82:85]
	v_mfma_f32_16x16x32_bf16 v[70:73], v[146:149], v[186:189], v[70:73]
	v_mfma_f32_16x16x32_bf16 v[66:69], v[154:157], v[186:189], v[66:69]
	v_mfma_f32_16x16x32_bf16 v[118:121], v[150:153], v[166:169], v[118:121]
	v_mfma_f32_16x16x32_bf16 v[114:117], v[158:161], v[166:169], v[114:117]
	v_mfma_f32_16x16x32_bf16 v[102:105], v[150:153], v[174:177], v[102:105]
	v_mfma_f32_16x16x32_bf16 v[98:101], v[158:161], v[174:177], v[98:101]
	v_mfma_f32_16x16x32_bf16 v[86:89], v[150:153], v[182:185], v[86:89]
	v_mfma_f32_16x16x32_bf16 v[82:85], v[158:161], v[182:185], v[82:85]
	v_mfma_f32_16x16x32_bf16 v[70:73], v[150:153], v[190:193], v[70:73]
	v_mfma_f32_16x16x32_bf16 v[66:69], v[158:161], v[190:193], v[66:69]
	s_barrier
	s_setprio 0
	s_add_i32 s0, s77, s2
	s_add_u32 s98, s8, s16
	s_addc_u32 s99, s9, s17
	s_mov_b32 m0, s0
	ds_read_b128 v[162:165], v246 offset:16384
	ds_read_b128 v[166:169], v246 offset:17408
	ds_read_b128 v[170:173], v246 offset:18432
	ds_read_b128 v[174:177], v246 offset:19456
	ds_read_b128 v[178:181], v246 offset:20480
	ds_read_b128 v[182:185], v246 offset:21504
	ds_read_b128 v[186:189], v246 offset:22528
	ds_read_b128 v[190:193], v246 offset:23552
	global_load_lds_dwordx4 v196, s[8:9]
	s_add_i32 m0, s0, 0x2000
	s_add_u32 s0, s8, 0x100000
	s_addc_u32 s1, s9, 0
	s_add_i32 s77, s78, s2
	global_load_lds_dwordx4 v202, s[8:9]
	s_mov_b32 m0, s77
	v_lshl_add_u64 v[216:217], s[66:67], 0, v[204:205]
	global_load_lds_dwordx4 v196, s[0:1]
	s_add_i32 m0, s77, 0x2000
	s_nop 0
	global_load_lds_dwordx4 v202, s[0:1]
	v_lshl_add_u64 v[214:215], s[66:67], 0, v[206:207]
	s_mov_b32 m0, s3
	s_nop 0
	global_load_lds_dwordx4 v206, s[66:67]
	s_mov_b32 m0, s10
	s_nop 0
	global_load_lds_dwordx4 v204, s[66:67]
	s_waitcnt vmcnt(8)
	s_waitcnt lgkmcnt(0)
	s_setprio 1
	s_barrier
	v_mfma_f32_16x16x32_bf16 v[62:65], v[130:133], v[162:165], v[62:65]
	v_mfma_f32_16x16x32_bf16 v[58:61], v[138:141], v[162:165], v[58:61]
	v_mfma_f32_16x16x32_bf16 v[46:49], v[130:133], v[170:173], v[46:49]
	v_mfma_f32_16x16x32_bf16 v[42:45], v[138:141], v[170:173], v[42:45]
	v_mfma_f32_16x16x32_bf16 v[30:33], v[130:133], v[178:181], v[30:33]
	v_mfma_f32_16x16x32_bf16 v[26:29], v[138:141], v[178:181], v[26:29]
	v_mfma_f32_16x16x32_bf16 v[14:17], v[130:133], v[186:189], v[14:17]
	v_mfma_f32_16x16x32_bf16 v[10:13], v[138:141], v[186:189], v[10:13]
	v_mfma_f32_16x16x32_bf16 v[62:65], v[134:137], v[166:169], v[62:65]
	v_mfma_f32_16x16x32_bf16 v[58:61], v[142:145], v[166:169], v[58:61]
	v_mfma_f32_16x16x32_bf16 v[46:49], v[134:137], v[174:177], v[46:49]
	v_mfma_f32_16x16x32_bf16 v[42:45], v[142:145], v[174:177], v[42:45]
	v_mfma_f32_16x16x32_bf16 v[30:33], v[134:137], v[182:185], v[30:33]
	v_mfma_f32_16x16x32_bf16 v[26:29], v[142:145], v[182:185], v[26:29]
	v_mfma_f32_16x16x32_bf16 v[14:17], v[134:137], v[190:193], v[14:17]
	v_mfma_f32_16x16x32_bf16 v[10:13], v[142:145], v[190:193], v[10:13]
	v_mfma_f32_16x16x32_bf16 v[54:57], v[146:149], v[162:165], v[54:57]
	v_mfma_f32_16x16x32_bf16 v[50:53], v[154:157], v[162:165], v[50:53]
	v_mfma_f32_16x16x32_bf16 v[38:41], v[146:149], v[170:173], v[38:41]
	v_mfma_f32_16x16x32_bf16 v[34:37], v[154:157], v[170:173], v[34:37]
	v_mfma_f32_16x16x32_bf16 v[22:25], v[146:149], v[178:181], v[22:25]
	v_mfma_f32_16x16x32_bf16 v[18:21], v[154:157], v[178:181], v[18:21]
	v_mfma_f32_16x16x32_bf16 v[6:9], v[146:149], v[186:189], v[6:9]
	v_mfma_f32_16x16x32_bf16 v[2:5], v[154:157], v[186:189], v[2:5]
	v_mfma_f32_16x16x32_bf16 v[54:57], v[150:153], v[166:169], v[54:57]
	v_mfma_f32_16x16x32_bf16 v[50:53], v[158:161], v[166:169], v[50:53]
	v_mfma_f32_16x16x32_bf16 v[38:41], v[150:153], v[174:177], v[38:41]
	v_mfma_f32_16x16x32_bf16 v[34:37], v[158:161], v[174:177], v[34:37]
	v_mfma_f32_16x16x32_bf16 v[22:25], v[150:153], v[182:185], v[22:25]
	v_mfma_f32_16x16x32_bf16 v[18:21], v[158:161], v[182:185], v[18:21]
	v_mfma_f32_16x16x32_bf16 v[6:9], v[150:153], v[190:193], v[6:9]
	v_mfma_f32_16x16x32_bf16 v[2:5], v[158:161], v[190:193], v[2:5]
	s_barrier
	s_setprio 0
.Lkmid_3:
	s_add_i32 s77, 0, 0x18000
	s_add_i32 s78, 0, 0x1c000
	ds_read_b128 v[130:133], v250 offset:32768
	ds_read_b128 v[134:137], v250 offset:33792
	ds_read_b128 v[138:141], v250 offset:34816
	ds_read_b128 v[142:145], v250 offset:35840
	ds_read_b128 v[146:149], v250 offset:49152
	ds_read_b128 v[150:153], v250 offset:50176
	ds_read_b128 v[154:157], v250 offset:51200
	ds_read_b128 v[158:161], v250 offset:52224
	s_add_u32 s0, s66, 0x100000
	s_addc_u32 s1, s67, 0
	s_mov_b32 m0, s11
	ds_read_b128 v[162:165], v246 offset:32768
	ds_read_b128 v[166:169], v246 offset:33792
	ds_read_b128 v[170:173], v246 offset:34816
	ds_read_b128 v[174:177], v246 offset:35840
	ds_read_b128 v[178:181], v246 offset:36864
	ds_read_b128 v[182:185], v246 offset:37888
	ds_read_b128 v[186:189], v246 offset:38912
	ds_read_b128 v[190:193], v246 offset:39936
	global_load_lds_dwordx4 v206, s[0:1]
	s_mov_b32 m0, s26
	s_nop 0
	global_load_lds_dwordx4 v204, s[0:1]
	s_waitcnt vmcnt(8)
	s_waitcnt lgkmcnt(0)
	s_setprio 1
	s_barrier
	v_mfma_f32_16x16x32_bf16 v[126:129], v[130:133], v[162:165], v[126:129]
	v_mfma_f32_16x16x32_bf16 v[122:125], v[138:141], v[162:165], v[122:125]
	v_mfma_f32_16x16x32_bf16 v[110:113], v[130:133], v[170:173], v[110:113]
	v_mfma_f32_16x16x32_bf16 v[106:109], v[138:141], v[170:173], v[106:109]
	v_mfma_f32_16x16x32_bf16 v[94:97], v[130:133], v[178:181], v[94:97]
	v_mfma_f32_16x16x32_bf16 v[90:93], v[138:141], v[178:181], v[90:93]
	v_mfma_f32_16x16x32_bf16 v[78:81], v[130:133], v[186:189], v[78:81]
	v_mfma_f32_16x16x32_bf16 v[74:77], v[138:141], v[186:189], v[74:77]
	v_mfma_f32_16x16x32_bf16 v[126:129], v[134:137], v[166:169], v[126:129]
	v_mfma_f32_16x16x32_bf16 v[122:125], v[142:145], v[166:169], v[122:125]
	v_mfma_f32_16x16x32_bf16 v[110:113], v[134:137], v[174:177], v[110:113]
	v_mfma_f32_16x16x32_bf16 v[106:109], v[142:145], v[174:177], v[106:109]
	v_mfma_f32_16x16x32_bf16 v[94:97], v[134:137], v[182:185], v[94:97]
	v_mfma_f32_16x16x32_bf16 v[90:93], v[142:145], v[182:185], v[90:93]
	v_mfma_f32_16x16x32_bf16 v[78:81], v[134:137], v[190:193], v[78:81]
	v_mfma_f32_16x16x32_bf16 v[74:77], v[142:145], v[190:193], v[74:77]
	v_mfma_f32_16x16x32_bf16 v[118:121], v[146:149], v[162:165], v[118:121]
	v_mfma_f32_16x16x32_bf16 v[114:117], v[154:157], v[162:165], v[114:117]
	v_mfma_f32_16x16x32_bf16 v[102:105], v[146:149], v[170:173], v[102:105]
	v_mfma_f32_16x16x32_bf16 v[98:101], v[154:157], v[170:173], v[98:101]
	v_mfma_f32_16x16x32_bf16 v[86:89], v[146:149], v[178:181], v[86:89]
	v_mfma_f32_16x16x32_bf16 v[82:85], v[154:157], v[178:181], v[82:85]
	v_mfma_f32_16x16x32_bf16 v[70:73], v[146:149], v[186:189], v[70:73]
	v_mfma_f32_16x16x32_bf16 v[66:69], v[154:157], v[186:189], v[66:69]
	v_mfma_f32_16x16x32_bf16 v[118:121], v[150:153], v[166:169], v[118:121]
	v_mfma_f32_16x16x32_bf16 v[114:117], v[158:161], v[166:169], v[114:117]
	v_mfma_f32_16x16x32_bf16 v[102:105], v[150:153], v[174:177], v[102:105]
	v_mfma_f32_16x16x32_bf16 v[98:101], v[158:161], v[174:177], v[98:101]
	v_mfma_f32_16x16x32_bf16 v[86:89], v[150:153], v[182:185], v[86:89]
	v_mfma_f32_16x16x32_bf16 v[82:85], v[158:161], v[182:185], v[82:85]
	v_mfma_f32_16x16x32_bf16 v[70:73], v[150:153], v[190:193], v[70:73]
	v_mfma_f32_16x16x32_bf16 v[66:69], v[158:161], v[190:193], v[66:69]
	s_barrier
	s_setprio 0
	s_add_i32 s0, s77, s2
	s_mov_b32 m0, s0
	ds_read_b128 v[162:165], v246 offset:49152
	ds_read_b128 v[166:169], v246 offset:50176
	ds_read_b128 v[170:173], v246 offset:51200
	ds_read_b128 v[174:177], v246 offset:52224
	ds_read_b128 v[178:181], v246 offset:53248
	ds_read_b128 v[182:185], v246 offset:54272
	ds_read_b128 v[186:189], v246 offset:55296
	ds_read_b128 v[190:193], v246 offset:56320
	global_load_lds_dwordx4 v196, s[98:99]
	s_add_i32 m0, s0, 0x2000
	s_add_u32 s0, s8, 0x100080
	s_addc_u32 s1, s9, 0
	s_add_i32 s8, s78, s2
	global_load_lds_dwordx4 v202, s[98:99]
	s_mov_b32 m0, s8
	s_nop 0
	global_load_lds_dwordx4 v196, s[0:1]
	s_add_i32 m0, s8, 0x2000
	s_nop 0
	global_load_lds_dwordx4 v202, s[0:1]
	v_lshl_add_u64 v[194:195], v[214:215], 0, s[16:17]
	s_mov_b32 m0, s27
	s_nop 0
	global_load_lds_dwordx4 v[194:195], off
	v_lshl_add_u64 v[194:195], v[216:217], 0, s[16:17]
	s_mov_b32 m0, s28
	s_nop 0
	global_load_lds_dwordx4 v[194:195], off
	s_waitcnt vmcnt(8)
	s_waitcnt lgkmcnt(0)
	s_setprio 1
	s_barrier
	v_mfma_f32_16x16x32_bf16 v[62:65], v[130:133], v[162:165], v[62:65]
	v_mfma_f32_16x16x32_bf16 v[58:61], v[138:141], v[162:165], v[58:61]
	v_mfma_f32_16x16x32_bf16 v[46:49], v[130:133], v[170:173], v[46:49]
	v_mfma_f32_16x16x32_bf16 v[42:45], v[138:141], v[170:173], v[42:45]
	v_mfma_f32_16x16x32_bf16 v[30:33], v[130:133], v[178:181], v[30:33]
	v_mfma_f32_16x16x32_bf16 v[26:29], v[138:141], v[178:181], v[26:29]
	v_mfma_f32_16x16x32_bf16 v[14:17], v[130:133], v[186:189], v[14:17]
	v_mfma_f32_16x16x32_bf16 v[10:13], v[138:141], v[186:189], v[10:13]
	v_mfma_f32_16x16x32_bf16 v[62:65], v[134:137], v[166:169], v[62:65]
	v_mfma_f32_16x16x32_bf16 v[58:61], v[142:145], v[166:169], v[58:61]
	v_mfma_f32_16x16x32_bf16 v[46:49], v[134:137], v[174:177], v[46:49]
	v_mfma_f32_16x16x32_bf16 v[42:45], v[142:145], v[174:177], v[42:45]
	v_mfma_f32_16x16x32_bf16 v[30:33], v[134:137], v[182:185], v[30:33]
	v_mfma_f32_16x16x32_bf16 v[26:29], v[142:145], v[182:185], v[26:29]
	v_mfma_f32_16x16x32_bf16 v[14:17], v[134:137], v[190:193], v[14:17]
	v_mfma_f32_16x16x32_bf16 v[10:13], v[142:145], v[190:193], v[10:13]
	v_mfma_f32_16x16x32_bf16 v[54:57], v[146:149], v[162:165], v[54:57]
	v_mfma_f32_16x16x32_bf16 v[50:53], v[154:157], v[162:165], v[50:53]
	v_mfma_f32_16x16x32_bf16 v[38:41], v[146:149], v[170:173], v[38:41]
	v_mfma_f32_16x16x32_bf16 v[34:37], v[154:157], v[170:173], v[34:37]
	v_mfma_f32_16x16x32_bf16 v[22:25], v[146:149], v[178:181], v[22:25]
	v_mfma_f32_16x16x32_bf16 v[18:21], v[154:157], v[178:181], v[18:21]
	v_mfma_f32_16x16x32_bf16 v[6:9], v[146:149], v[186:189], v[6:9]
	v_mfma_f32_16x16x32_bf16 v[2:5], v[154:157], v[186:189], v[2:5]
	v_mfma_f32_16x16x32_bf16 v[54:57], v[150:153], v[166:169], v[54:57]
	v_mfma_f32_16x16x32_bf16 v[50:53], v[158:161], v[166:169], v[50:53]
	v_mfma_f32_16x16x32_bf16 v[38:41], v[150:153], v[174:177], v[38:41]
	v_mfma_f32_16x16x32_bf16 v[34:37], v[158:161], v[174:177], v[34:37]
	v_mfma_f32_16x16x32_bf16 v[22:25], v[150:153], v[182:185], v[22:25]
	v_mfma_f32_16x16x32_bf16 v[18:21], v[158:161], v[182:185], v[18:21]
	v_mfma_f32_16x16x32_bf16 v[6:9], v[150:153], v[190:193], v[6:9]
	v_mfma_f32_16x16x32_bf16 v[2:5], v[158:161], v[190:193], v[2:5]
	s_barrier
	s_setprio 0
	s_add_u32 s71, s71, 0x100
	s_addc_u32 s72, s72, 0
	s_add_u32 s44, s44, 0x100
	s_addc_u32 s45, s45, 0
	s_cmp_ge_i32 s73, s35
	s_mov_b32 s8, s73
	s_cbranch_scc0 .LBB0_2239
	s_and_b64 vcc, exec, s[46:47]
	s_cbranch_vccz .LBB0_2242
	s_barrier

.Ldefbar_skip_4:
	v_add_u32_e32 v250, 0x10000, v188
	s_add_i32 s77, s8, 2
	s_add_u32 s0, s62, 0xfff80080
	s_addc_u32 s1, s63, -1
	s_add_i32 s78, 0, 0x10000
	s_cmp_eq_u32 s71, s8
	s_cselect_b32 s65, s41, s1
	s_cselect_b32 s64, s45, s0
	s_cselect_b32 s9, s43, s73
	s_cselect_b32 s8, s70, s72
	s_add_i32 s79, 0, 0x14000
	ds_read_b128 v[130:133], v250
	ds_read_b128 v[134:137], v250 offset:1024
	ds_read_b128 v[138:141], v250 offset:2048
	ds_read_b128 v[142:145], v250 offset:3072
	ds_read_b128 v[146:149], v250 offset:16384
	ds_read_b128 v[150:153], v250 offset:17408
	ds_read_b128 v[154:157], v250 offset:18432
	ds_read_b128 v[158:161], v250 offset:19456
	s_add_i32 m0, s27, 0xc000
	ds_read_b128 v[162:165], v189
	ds_read_b128 v[180:183], v189 offset:1024
	ds_read_b128 v[184:187], v189 offset:2048
	ds_read_b128 v[190:193], v189 offset:3072
	ds_read_b128 v[202:205], v189 offset:4096
	ds_read_b128 v[206:209], v189 offset:5120
	ds_read_b128 v[210:213], v189 offset:6144
	ds_read_b128 v[214:217], v189 offset:7168
	global_load_lds_dwordx4 v178, s[62:63]
	s_add_i32 m0, s27, 0xe000
	s_nop 0
	global_load_lds_dwordx4 v176, s[62:63]
	s_waitcnt vmcnt(8)
	s_waitcnt lgkmcnt(0)
	s_setprio 1
	s_barrier
	v_mfma_f32_16x16x32_bf16 v[126:129], v[130:133], v[162:165], 0
	v_mfma_f32_16x16x32_bf16 v[122:125], v[138:141], v[162:165], 0
	v_mfma_f32_16x16x32_bf16 v[110:113], v[130:133], v[184:187], 0
	v_mfma_f32_16x16x32_bf16 v[106:109], v[138:141], v[184:187], 0
	v_mfma_f32_16x16x32_bf16 v[98:101], v[130:133], v[202:205], 0
	v_mfma_f32_16x16x32_bf16 v[90:93], v[138:141], v[202:205], 0
	v_mfma_f32_16x16x32_bf16 v[82:85], v[130:133], v[210:213], 0
	v_mfma_f32_16x16x32_bf16 v[74:77], v[138:141], v[210:213], 0
	v_mfma_f32_16x16x32_bf16 v[126:129], v[134:137], v[180:183], v[126:129]
	v_mfma_f32_16x16x32_bf16 v[122:125], v[142:145], v[180:183], v[122:125]
	v_mfma_f32_16x16x32_bf16 v[110:113], v[134:137], v[190:193], v[110:113]
	v_mfma_f32_16x16x32_bf16 v[106:109], v[142:145], v[190:193], v[106:109]
	v_mfma_f32_16x16x32_bf16 v[98:101], v[134:137], v[206:209], v[98:101]
	v_mfma_f32_16x16x32_bf16 v[90:93], v[142:145], v[206:209], v[90:93]
	v_mfma_f32_16x16x32_bf16 v[82:85], v[134:137], v[214:217], v[82:85]
	v_mfma_f32_16x16x32_bf16 v[74:77], v[142:145], v[214:217], v[74:77]
	v_mfma_f32_16x16x32_bf16 v[118:121], v[146:149], v[162:165], 0
	v_mfma_f32_16x16x32_bf16 v[114:117], v[154:157], v[162:165], 0
	v_mfma_f32_16x16x32_bf16 v[102:105], v[146:149], v[184:187], 0
	v_mfma_f32_16x16x32_bf16 v[94:97], v[154:157], v[184:187], 0
	v_mfma_f32_16x16x32_bf16 v[86:89], v[146:149], v[202:205], 0
	v_mfma_f32_16x16x32_bf16 v[78:81], v[154:157], v[202:205], 0
	v_mfma_f32_16x16x32_bf16 v[70:73], v[146:149], v[210:213], 0
	v_mfma_f32_16x16x32_bf16 v[66:69], v[154:157], v[210:213], 0
	v_mfma_f32_16x16x32_bf16 v[118:121], v[150:153], v[180:183], v[118:121]
	v_mfma_f32_16x16x32_bf16 v[114:117], v[158:161], v[180:183], v[114:117]
	v_mfma_f32_16x16x32_bf16 v[102:105], v[150:153], v[190:193], v[102:105]
	v_mfma_f32_16x16x32_bf16 v[94:97], v[158:161], v[190:193], v[94:97]
	v_mfma_f32_16x16x32_bf16 v[86:89], v[150:153], v[206:209], v[86:89]
	v_mfma_f32_16x16x32_bf16 v[78:81], v[158:161], v[206:209], v[78:81]
	v_mfma_f32_16x16x32_bf16 v[70:73], v[150:153], v[214:217], v[70:73]
	v_mfma_f32_16x16x32_bf16 v[66:69], v[158:161], v[214:217], v[66:69]
	s_barrier
	s_setprio 0
	s_add_i32 s0, s78, s26
	s_add_u32 s98, s8, s16
	s_addc_u32 s99, s9, s17
	s_mov_b32 m0, s0
	ds_read_b128 v[162:165], v189 offset:16384
	ds_read_b128 v[180:183], v189 offset:17408
	ds_read_b128 v[184:187], v189 offset:18432
	ds_read_b128 v[190:193], v189 offset:19456
	ds_read_b128 v[202:205], v189 offset:20480
	ds_read_b128 v[206:209], v189 offset:21504
	ds_read_b128 v[210:213], v189 offset:22528
	ds_read_b128 v[214:217], v189 offset:23552
	global_load_lds_dwordx4 v196, s[8:9]
	s_add_i32 m0, s0, 0x2000
	s_add_u32 s0, s8, 0x80000
	s_addc_u32 s1, s9, 0
	s_add_i32 s78, s79, s26
	global_load_lds_dwordx4 v170, s[8:9]
	s_mov_b32 m0, s78
	v_lshl_add_u64 v[222:223], s[64:65], 0, v[168:169]
	global_load_lds_dwordx4 v196, s[0:1]
	s_add_i32 m0, s78, 0x2000
	s_nop 0
	global_load_lds_dwordx4 v170, s[0:1]
	v_lshl_add_u64 v[220:221], s[64:65], 0, v[166:167]
	s_mov_b32 m0, s27
	s_nop 0
	global_load_lds_dwordx4 v166, s[64:65]
	s_mov_b32 m0, s28
	s_nop 0
	global_load_lds_dwordx4 v168, s[64:65]
	s_waitcnt vmcnt(8)
	s_waitcnt lgkmcnt(0)
	s_setprio 1
	s_barrier
	v_mfma_f32_16x16x32_bf16 v[62:65], v[130:133], v[162:165], 0
	v_mfma_f32_16x16x32_bf16 v[58:61], v[138:141], v[162:165], 0
	v_mfma_f32_16x16x32_bf16 v[50:53], v[130:133], v[184:187], 0
	v_mfma_f32_16x16x32_bf16 v[42:45], v[138:141], v[184:187], 0
	v_mfma_f32_16x16x32_bf16 v[34:37], v[130:133], v[202:205], 0
	v_mfma_f32_16x16x32_bf16 v[26:29], v[138:141], v[202:205], 0
	v_mfma_f32_16x16x32_bf16 v[18:21], v[130:133], v[210:213], 0
	v_mfma_f32_16x16x32_bf16 v[10:13], v[138:141], v[210:213], 0
	v_mfma_f32_16x16x32_bf16 v[62:65], v[134:137], v[180:183], v[62:65]
	v_mfma_f32_16x16x32_bf16 v[58:61], v[142:145], v[180:183], v[58:61]
	v_mfma_f32_16x16x32_bf16 v[50:53], v[134:137], v[190:193], v[50:53]
	v_mfma_f32_16x16x32_bf16 v[42:45], v[142:145], v[190:193], v[42:45]
	v_mfma_f32_16x16x32_bf16 v[34:37], v[134:137], v[206:209], v[34:37]
	v_mfma_f32_16x16x32_bf16 v[26:29], v[142:145], v[206:209], v[26:29]
	v_mfma_f32_16x16x32_bf16 v[18:21], v[134:137], v[214:217], v[18:21]
	v_mfma_f32_16x16x32_bf16 v[10:13], v[142:145], v[214:217], v[10:13]
	v_mfma_f32_16x16x32_bf16 v[54:57], v[146:149], v[162:165], 0
	v_mfma_f32_16x16x32_bf16 v[46:49], v[154:157], v[162:165], 0
	v_mfma_f32_16x16x32_bf16 v[38:41], v[146:149], v[184:187], 0
	v_mfma_f32_16x16x32_bf16 v[30:33], v[154:157], v[184:187], 0
	v_mfma_f32_16x16x32_bf16 v[22:25], v[146:149], v[202:205], 0
	v_mfma_f32_16x16x32_bf16 v[14:17], v[154:157], v[202:205], 0
	v_mfma_f32_16x16x32_bf16 v[6:9], v[146:149], v[210:213], 0
	v_mfma_f32_16x16x32_bf16 v[2:5], v[154:157], v[210:213], 0
	v_mfma_f32_16x16x32_bf16 v[54:57], v[150:153], v[180:183], v[54:57]
	v_mfma_f32_16x16x32_bf16 v[46:49], v[158:161], v[180:183], v[46:49]
	v_mfma_f32_16x16x32_bf16 v[38:41], v[150:153], v[190:193], v[38:41]
	v_mfma_f32_16x16x32_bf16 v[30:33], v[158:161], v[190:193], v[30:33]
	v_mfma_f32_16x16x32_bf16 v[22:25], v[150:153], v[206:209], v[22:25]
	v_mfma_f32_16x16x32_bf16 v[14:17], v[158:161], v[206:209], v[14:17]
	v_mfma_f32_16x16x32_bf16 v[6:9], v[150:153], v[214:217], v[6:9]
	v_mfma_f32_16x16x32_bf16 v[2:5], v[158:161], v[214:217], v[2:5]
	s_barrier
	s_setprio 0
	s_branch .Lkmid_4
.LBB0_2357:
	s_add_i32 s77, s8, 2
	s_add_u32 s0, s62, 0xfff80080
	s_addc_u32 s1, s63, -1
	s_add_i32 s78, 0, 0x10000
	s_cmp_eq_u32 s71, s8
	s_cselect_b32 s65, s41, s1
	s_cselect_b32 s64, s45, s0
	s_cselect_b32 s9, s43, s73
	s_cselect_b32 s8, s70, s72
	s_add_i32 s79, 0, 0x14000
	ds_read_b128 v[130:133], v250
	ds_read_b128 v[134:137], v250 offset:1024
	ds_read_b128 v[138:141], v250 offset:2048
	ds_read_b128 v[142:145], v250 offset:3072
	ds_read_b128 v[146:149], v250 offset:16384
	ds_read_b128 v[150:153], v250 offset:17408
	ds_read_b128 v[154:157], v250 offset:18432
	ds_read_b128 v[158:161], v250 offset:19456
	s_add_i32 m0, s27, 0xc000
	ds_read_b128 v[162:165], v189
	ds_read_b128 v[180:183], v189 offset:1024
	ds_read_b128 v[184:187], v189 offset:2048
	ds_read_b128 v[190:193], v189 offset:3072
	ds_read_b128 v[202:205], v189 offset:4096
	ds_read_b128 v[206:209], v189 offset:5120
	ds_read_b128 v[210:213], v189 offset:6144
	ds_read_b128 v[214:217], v189 offset:7168
	global_load_lds_dwordx4 v178, s[62:63]
	s_add_i32 m0, s27, 0xe000
	s_nop 0
	global_load_lds_dwordx4 v176, s[62:63]
	s_waitcnt vmcnt(8)
	s_waitcnt lgkmcnt(0)
	s_setprio 1
	s_barrier
	v_mfma_f32_16x16x32_bf16 v[126:129], v[130:133], v[162:165], v[126:129]
	v_mfma_f32_16x16x32_bf16 v[122:125], v[138:141], v[162:165], v[122:125]
	v_mfma_f32_16x16x32_bf16 v[110:113], v[130:133], v[184:187], v[110:113]
	v_mfma_f32_16x16x32_bf16 v[106:109], v[138:141], v[184:187], v[106:109]
	v_mfma_f32_16x16x32_bf16 v[98:101], v[130:133], v[202:205], v[98:101]
	v_mfma_f32_16x16x32_bf16 v[90:93], v[138:141], v[202:205], v[90:93]
	v_mfma_f32_16x16x32_bf16 v[82:85], v[130:133], v[210:213], v[82:85]
	v_mfma_f32_16x16x32_bf16 v[74:77], v[138:141], v[210:213], v[74:77]
	v_mfma_f32_16x16x32_bf16 v[126:129], v[134:137], v[180:183], v[126:129]
	v_mfma_f32_16x16x32_bf16 v[122:125], v[142:145], v[180:183], v[122:125]
	v_mfma_f32_16x16x32_bf16 v[110:113], v[134:137], v[190:193], v[110:113]
	v_mfma_f32_16x16x32_bf16 v[106:109], v[142:145], v[190:193], v[106:109]
	v_mfma_f32_16x16x32_bf16 v[98:101], v[134:137], v[206:209], v[98:101]
	v_mfma_f32_16x16x32_bf16 v[90:93], v[142:145], v[206:209], v[90:93]
	v_mfma_f32_16x16x32_bf16 v[82:85], v[134:137], v[214:217], v[82:85]
	v_mfma_f32_16x16x32_bf16 v[74:77], v[142:145], v[214:217], v[74:77]
	v_mfma_f32_16x16x32_bf16 v[118:121], v[146:149], v[162:165], v[118:121]
	v_mfma_f32_16x16x32_bf16 v[114:117], v[154:157], v[162:165], v[114:117]
	v_mfma_f32_16x16x32_bf16 v[102:105], v[146:149], v[184:187], v[102:105]
	v_mfma_f32_16x16x32_bf16 v[94:97], v[154:157], v[184:187], v[94:97]
	v_mfma_f32_16x16x32_bf16 v[86:89], v[146:149], v[202:205], v[86:89]
	v_mfma_f32_16x16x32_bf16 v[78:81], v[154:157], v[202:205], v[78:81]
	v_mfma_f32_16x16x32_bf16 v[70:73], v[146:149], v[210:213], v[70:73]
	v_mfma_f32_16x16x32_bf16 v[66:69], v[154:157], v[210:213], v[66:69]
	v_mfma_f32_16x16x32_bf16 v[118:121], v[150:153], v[180:183], v[118:121]
	v_mfma_f32_16x16x32_bf16 v[114:117], v[158:161], v[180:183], v[114:117]
	v_mfma_f32_16x16x32_bf16 v[102:105], v[150:153], v[190:193], v[102:105]
	v_mfma_f32_16x16x32_bf16 v[94:97], v[158:161], v[190:193], v[94:97]
	v_mfma_f32_16x16x32_bf16 v[86:89], v[150:153], v[206:209], v[86:89]
	v_mfma_f32_16x16x32_bf16 v[78:81], v[158:161], v[206:209], v[78:81]
	v_mfma_f32_16x16x32_bf16 v[70:73], v[150:153], v[214:217], v[70:73]
	v_mfma_f32_16x16x32_bf16 v[66:69], v[158:161], v[214:217], v[66:69]
	s_barrier
	s_setprio 0
	s_add_i32 s0, s78, s26
	s_add_u32 s98, s8, s16
	s_addc_u32 s99, s9, s17
	s_mov_b32 m0, s0
	ds_read_b128 v[162:165], v189 offset:16384
	ds_read_b128 v[180:183], v189 offset:17408
	ds_read_b128 v[184:187], v189 offset:18432
	ds_read_b128 v[190:193], v189 offset:19456
	ds_read_b128 v[202:205], v189 offset:20480
	ds_read_b128 v[206:209], v189 offset:21504
	ds_read_b128 v[210:213], v189 offset:22528
	ds_read_b128 v[214:217], v189 offset:23552
	global_load_lds_dwordx4 v196, s[8:9]
	s_add_i32 m0, s0, 0x2000
	s_add_u32 s0, s8, 0x80000
	s_addc_u32 s1, s9, 0
	s_add_i32 s78, s79, s26
	global_load_lds_dwordx4 v170, s[8:9]
	s_mov_b32 m0, s78
	v_lshl_add_u64 v[222:223], s[64:65], 0, v[168:169]
	global_load_lds_dwordx4 v196, s[0:1]
	s_add_i32 m0, s78, 0x2000
	s_nop 0
	global_load_lds_dwordx4 v170, s[0:1]
	v_lshl_add_u64 v[220:221], s[64:65], 0, v[166:167]
	s_mov_b32 m0, s27
	s_nop 0
	global_load_lds_dwordx4 v166, s[64:65]
	s_mov_b32 m0, s28
	s_nop 0
	global_load_lds_dwordx4 v168, s[64:65]
	s_waitcnt vmcnt(8)
	s_waitcnt lgkmcnt(0)
	s_setprio 1
	s_barrier
	v_mfma_f32_16x16x32_bf16 v[62:65], v[130:133], v[162:165], v[62:65]
	v_mfma_f32_16x16x32_bf16 v[58:61], v[138:141], v[162:165], v[58:61]
	v_mfma_f32_16x16x32_bf16 v[50:53], v[130:133], v[184:187], v[50:53]
	v_mfma_f32_16x16x32_bf16 v[42:45], v[138:141], v[184:187], v[42:45]
	v_mfma_f32_16x16x32_bf16 v[34:37], v[130:133], v[202:205], v[34:37]
	v_mfma_f32_16x16x32_bf16 v[26:29], v[138:141], v[202:205], v[26:29]
	v_mfma_f32_16x16x32_bf16 v[18:21], v[130:133], v[210:213], v[18:21]
	v_mfma_f32_16x16x32_bf16 v[10:13], v[138:141], v[210:213], v[10:13]
	v_mfma_f32_16x16x32_bf16 v[62:65], v[134:137], v[180:183], v[62:65]
	v_mfma_f32_16x16x32_bf16 v[58:61], v[142:145], v[180:183], v[58:61]
	v_mfma_f32_16x16x32_bf16 v[50:53], v[134:137], v[190:193], v[50:53]
	v_mfma_f32_16x16x32_bf16 v[42:45], v[142:145], v[190:193], v[42:45]
	v_mfma_f32_16x16x32_bf16 v[34:37], v[134:137], v[206:209], v[34:37]
	v_mfma_f32_16x16x32_bf16 v[26:29], v[142:145], v[206:209], v[26:29]
	v_mfma_f32_16x16x32_bf16 v[18:21], v[134:137], v[214:217], v[18:21]
	v_mfma_f32_16x16x32_bf16 v[10:13], v[142:145], v[214:217], v[10:13]
	v_mfma_f32_16x16x32_bf16 v[54:57], v[146:149], v[162:165], v[54:57]
	v_mfma_f32_16x16x32_bf16 v[46:49], v[154:157], v[162:165], v[46:49]
	v_mfma_f32_16x16x32_bf16 v[38:41], v[146:149], v[184:187], v[38:41]
	v_mfma_f32_16x16x32_bf16 v[30:33], v[154:157], v[184:187], v[30:33]
	v_mfma_f32_16x16x32_bf16 v[22:25], v[146:149], v[202:205], v[22:25]
	v_mfma_f32_16x16x32_bf16 v[14:17], v[154:157], v[202:205], v[14:17]
	v_mfma_f32_16x16x32_bf16 v[6:9], v[146:149], v[210:213], v[6:9]
	v_mfma_f32_16x16x32_bf16 v[2:5], v[154:157], v[210:213], v[2:5]
	v_mfma_f32_16x16x32_bf16 v[54:57], v[150:153], v[180:183], v[54:57]
	v_mfma_f32_16x16x32_bf16 v[46:49], v[158:161], v[180:183], v[46:49]
	v_mfma_f32_16x16x32_bf16 v[38:41], v[150:153], v[190:193], v[38:41]
	v_mfma_f32_16x16x32_bf16 v[30:33], v[158:161], v[190:193], v[30:33]
	v_mfma_f32_16x16x32_bf16 v[22:25], v[150:153], v[206:209], v[22:25]
	v_mfma_f32_16x16x32_bf16 v[14:17], v[158:161], v[206:209], v[14:17]
	v_mfma_f32_16x16x32_bf16 v[6:9], v[150:153], v[214:217], v[6:9]
	v_mfma_f32_16x16x32_bf16 v[2:5], v[158:161], v[214:217], v[2:5]
	s_barrier
	s_setprio 0
.Lkmid_4:
	s_add_i32 s78, 0, 0x18000
	s_add_i32 s79, 0, 0x1c000
	ds_read_b128 v[130:133], v250 offset:32768
	ds_read_b128 v[134:137], v250 offset:33792
	ds_read_b128 v[138:141], v250 offset:34816
	ds_read_b128 v[142:145], v250 offset:35840
	ds_read_b128 v[146:149], v250 offset:49152
	ds_read_b128 v[150:153], v250 offset:50176
	ds_read_b128 v[154:157], v250 offset:51200
	ds_read_b128 v[158:161], v250 offset:52224
	s_add_u32 s0, s64, 0x80000
	s_addc_u32 s1, s65, 0
	s_mov_b32 m0, s29
	ds_read_b128 v[162:165], v189 offset:32768
	ds_read_b128 v[180:183], v189 offset:33792
	ds_read_b128 v[184:187], v189 offset:34816
	ds_read_b128 v[190:193], v189 offset:35840
	ds_read_b128 v[202:205], v189 offset:36864
	ds_read_b128 v[206:209], v189 offset:37888
	ds_read_b128 v[210:213], v189 offset:38912
	ds_read_b128 v[214:217], v189 offset:39936
	global_load_lds_dwordx4 v166, s[0:1]
	s_mov_b32 m0, s30
	s_nop 0
	global_load_lds_dwordx4 v168, s[0:1]
	s_waitcnt vmcnt(8)
	s_waitcnt lgkmcnt(0)
	s_setprio 1
	s_barrier
	v_mfma_f32_16x16x32_bf16 v[126:129], v[130:133], v[162:165], v[126:129]
	v_mfma_f32_16x16x32_bf16 v[122:125], v[138:141], v[162:165], v[122:125]
	v_mfma_f32_16x16x32_bf16 v[110:113], v[130:133], v[184:187], v[110:113]
	v_mfma_f32_16x16x32_bf16 v[106:109], v[138:141], v[184:187], v[106:109]
	v_mfma_f32_16x16x32_bf16 v[98:101], v[130:133], v[202:205], v[98:101]
	v_mfma_f32_16x16x32_bf16 v[90:93], v[138:141], v[202:205], v[90:93]
	v_mfma_f32_16x16x32_bf16 v[82:85], v[130:133], v[210:213], v[82:85]
	v_mfma_f32_16x16x32_bf16 v[74:77], v[138:141], v[210:213], v[74:77]
	v_mfma_f32_16x16x32_bf16 v[126:129], v[134:137], v[180:183], v[126:129]
	v_mfma_f32_16x16x32_bf16 v[122:125], v[142:145], v[180:183], v[122:125]
	v_mfma_f32_16x16x32_bf16 v[110:113], v[134:137], v[190:193], v[110:113]
	v_mfma_f32_16x16x32_bf16 v[106:109], v[142:145], v[190:193], v[106:109]
	v_mfma_f32_16x16x32_bf16 v[98:101], v[134:137], v[206:209], v[98:101]
	v_mfma_f32_16x16x32_bf16 v[90:93], v[142:145], v[206:209], v[90:93]
	v_mfma_f32_16x16x32_bf16 v[82:85], v[134:137], v[214:217], v[82:85]
	v_mfma_f32_16x16x32_bf16 v[74:77], v[142:145], v[214:217], v[74:77]
	v_mfma_f32_16x16x32_bf16 v[118:121], v[146:149], v[162:165], v[118:121]
	v_mfma_f32_16x16x32_bf16 v[114:117], v[154:157], v[162:165], v[114:117]
	v_mfma_f32_16x16x32_bf16 v[102:105], v[146:149], v[184:187], v[102:105]
	v_mfma_f32_16x16x32_bf16 v[94:97], v[154:157], v[184:187], v[94:97]
	v_mfma_f32_16x16x32_bf16 v[86:89], v[146:149], v[202:205], v[86:89]
	v_mfma_f32_16x16x32_bf16 v[78:81], v[154:157], v[202:205], v[78:81]
	v_mfma_f32_16x16x32_bf16 v[70:73], v[146:149], v[210:213], v[70:73]
	v_mfma_f32_16x16x32_bf16 v[66:69], v[154:157], v[210:213], v[66:69]
	v_mfma_f32_16x16x32_bf16 v[118:121], v[150:153], v[180:183], v[118:121]
	v_mfma_f32_16x16x32_bf16 v[114:117], v[158:161], v[180:183], v[114:117]
	v_mfma_f32_16x16x32_bf16 v[102:105], v[150:153], v[190:193], v[102:105]
	v_mfma_f32_16x16x32_bf16 v[94:97], v[158:161], v[190:193], v[94:97]
	v_mfma_f32_16x16x32_bf16 v[86:89], v[150:153], v[206:209], v[86:89]
	v_mfma_f32_16x16x32_bf16 v[78:81], v[158:161], v[206:209], v[78:81]
	v_mfma_f32_16x16x32_bf16 v[70:73], v[150:153], v[214:217], v[70:73]
	v_mfma_f32_16x16x32_bf16 v[66:69], v[158:161], v[214:217], v[66:69]
	s_barrier
	s_setprio 0
	s_add_i32 s0, s78, s26
	s_mov_b32 m0, s0
	ds_read_b128 v[162:165], v189 offset:49152
	ds_read_b128 v[180:183], v189 offset:50176
	ds_read_b128 v[184:187], v189 offset:51200
	ds_read_b128 v[190:193], v189 offset:52224
	ds_read_b128 v[202:205], v189 offset:53248
	ds_read_b128 v[206:209], v189 offset:54272
	ds_read_b128 v[210:213], v189 offset:55296
	ds_read_b128 v[214:217], v189 offset:56320
	global_load_lds_dwordx4 v196, s[98:99]
	s_add_i32 m0, s0, 0x2000
	s_add_u32 s0, s8, 0x80080
	s_addc_u32 s1, s9, 0
	s_add_i32 s8, s79, s26
	global_load_lds_dwordx4 v170, s[98:99]
	s_mov_b32 m0, s8
	s_nop 0
	global_load_lds_dwordx4 v196, s[0:1]
	s_add_i32 m0, s8, 0x2000
	s_nop 0
	global_load_lds_dwordx4 v170, s[0:1]
	v_lshl_add_u64 v[194:195], v[220:221], 0, s[16:17]
	s_mov_b32 m0, s35
	s_nop 0
	global_load_lds_dwordx4 v[194:195], off
	v_lshl_add_u64 v[194:195], v[222:223], 0, s[16:17]
	s_mov_b32 m0, s53
	s_nop 0
	global_load_lds_dwordx4 v[194:195], off
	s_waitcnt vmcnt(8)
	s_waitcnt lgkmcnt(0)
	s_setprio 1
	s_barrier
	v_mfma_f32_16x16x32_bf16 v[62:65], v[130:133], v[162:165], v[62:65]
	v_mfma_f32_16x16x32_bf16 v[58:61], v[138:141], v[162:165], v[58:61]
	v_mfma_f32_16x16x32_bf16 v[50:53], v[130:133], v[184:187], v[50:53]
	v_mfma_f32_16x16x32_bf16 v[42:45], v[138:141], v[184:187], v[42:45]
	v_mfma_f32_16x16x32_bf16 v[34:37], v[130:133], v[202:205], v[34:37]
	v_mfma_f32_16x16x32_bf16 v[26:29], v[138:141], v[202:205], v[26:29]
	v_mfma_f32_16x16x32_bf16 v[18:21], v[130:133], v[210:213], v[18:21]
	v_mfma_f32_16x16x32_bf16 v[10:13], v[138:141], v[210:213], v[10:13]
	v_mfma_f32_16x16x32_bf16 v[62:65], v[134:137], v[180:183], v[62:65]
	v_mfma_f32_16x16x32_bf16 v[58:61], v[142:145], v[180:183], v[58:61]
	v_mfma_f32_16x16x32_bf16 v[50:53], v[134:137], v[190:193], v[50:53]
	v_mfma_f32_16x16x32_bf16 v[42:45], v[142:145], v[190:193], v[42:45]
	v_mfma_f32_16x16x32_bf16 v[34:37], v[134:137], v[206:209], v[34:37]
	v_mfma_f32_16x16x32_bf16 v[26:29], v[142:145], v[206:209], v[26:29]
	v_mfma_f32_16x16x32_bf16 v[18:21], v[134:137], v[214:217], v[18:21]
	v_mfma_f32_16x16x32_bf16 v[10:13], v[142:145], v[214:217], v[10:13]
	v_mfma_f32_16x16x32_bf16 v[54:57], v[146:149], v[162:165], v[54:57]
	v_mfma_f32_16x16x32_bf16 v[46:49], v[154:157], v[162:165], v[46:49]
	v_mfma_f32_16x16x32_bf16 v[38:41], v[146:149], v[184:187], v[38:41]
	v_mfma_f32_16x16x32_bf16 v[30:33], v[154:157], v[184:187], v[30:33]
	v_mfma_f32_16x16x32_bf16 v[22:25], v[146:149], v[202:205], v[22:25]
	v_mfma_f32_16x16x32_bf16 v[14:17], v[154:157], v[202:205], v[14:17]
	v_mfma_f32_16x16x32_bf16 v[6:9], v[146:149], v[210:213], v[6:9]
	v_mfma_f32_16x16x32_bf16 v[2:5], v[154:157], v[210:213], v[2:5]
	v_mfma_f32_16x16x32_bf16 v[54:57], v[150:153], v[180:183], v[54:57]
	v_mfma_f32_16x16x32_bf16 v[46:49], v[158:161], v[180:183], v[46:49]
	v_mfma_f32_16x16x32_bf16 v[38:41], v[150:153], v[190:193], v[38:41]
	v_mfma_f32_16x16x32_bf16 v[30:33], v[158:161], v[190:193], v[30:33]
	v_mfma_f32_16x16x32_bf16 v[22:25], v[150:153], v[206:209], v[22:25]
	v_mfma_f32_16x16x32_bf16 v[14:17], v[158:161], v[206:209], v[14:17]
	v_mfma_f32_16x16x32_bf16 v[6:9], v[150:153], v[214:217], v[6:9]
	v_mfma_f32_16x16x32_bf16 v[2:5], v[158:161], v[214:217], v[2:5]
	s_barrier
	s_setprio 0
	s_add_u32 s72, s72, 0x100
	s_addc_u32 s73, s73, 0
	s_add_u32 s62, s62, 0x100
	s_addc_u32 s63, s63, 0
	s_cmp_ge_i32 s77, s69
	s_mov_b32 s8, s77
	s_cbranch_scc0 .LBB0_2357
	s_and_b64 vcc, exec, s[38:39]
	s_cbranch_vccz .LBB0_2360
	s_barrier

.Ldefbar_skip_5:
	v_add_u32_e32 v250, 0x10000, v141
	s_add_i32 s69, s8, 2
	s_add_u32 s0, s52, 0xfff80080
	s_addc_u32 s1, s53, -1
	s_add_i32 s70, 0, 0x10000
	s_cmp_eq_u32 s66, s8
	s_cselect_b32 s59, s41, s1
	s_cselect_b32 s58, s45, s0
	s_cselect_b32 s9, s43, s68
	s_cselect_b32 s8, s65, s67
	s_add_i32 s71, 0, 0x14000
	ds_read_b128 v[144:147], v250
	ds_read_b128 v[148:151], v250 offset:1024
	ds_read_b128 v[152:155], v250 offset:2048
	ds_read_b128 v[156:159], v250 offset:3072
	ds_read_b128 v[160:163], v250 offset:16384
	ds_read_b128 v[164:167], v250 offset:17408
	ds_read_b128 v[168:171], v250 offset:18432
	ds_read_b128 v[172:175], v250 offset:19456
	s_add_i32 m0, s27, 0xc000
	ds_read_b128 v[176:179], v143
	ds_read_b128 v[180:183], v143 offset:1024
	ds_read_b128 v[184:187], v143 offset:2048
	ds_read_b128 v[188:191], v143 offset:3072
	ds_read_b128 v[192:195], v143 offset:4096
	ds_read_b128 v[202:205], v143 offset:5120
	ds_read_b128 v[206:209], v143 offset:6144
	ds_read_b128 v[210:213], v143 offset:7168
	global_load_lds_dwordx4 v138, s[52:53]
	s_add_i32 m0, s27, 0xe000
	s_nop 0
	global_load_lds_dwordx4 v136, s[52:53]
	s_waitcnt vmcnt(8)
	s_waitcnt lgkmcnt(0)
	s_setprio 1
	s_barrier
	v_mfma_f32_16x16x32_bf16 v[126:129], v[144:147], v[176:179], 0
	v_mfma_f32_16x16x32_bf16 v[118:121], v[152:155], v[176:179], 0
	v_mfma_f32_16x16x32_bf16 v[110:113], v[144:147], v[184:187], 0
	v_mfma_f32_16x16x32_bf16 v[102:105], v[152:155], v[184:187], 0
	v_mfma_f32_16x16x32_bf16 v[94:97], v[144:147], v[192:195], 0
	v_mfma_f32_16x16x32_bf16 v[86:89], v[152:155], v[192:195], 0
	v_mfma_f32_16x16x32_bf16 v[78:81], v[144:147], v[206:209], 0
	v_mfma_f32_16x16x32_bf16 v[70:73], v[152:155], v[206:209], 0
	v_mfma_f32_16x16x32_bf16 v[126:129], v[148:151], v[180:183], v[126:129]
	v_mfma_f32_16x16x32_bf16 v[118:121], v[156:159], v[180:183], v[118:121]
	v_mfma_f32_16x16x32_bf16 v[110:113], v[148:151], v[188:191], v[110:113]
	v_mfma_f32_16x16x32_bf16 v[102:105], v[156:159], v[188:191], v[102:105]
	v_mfma_f32_16x16x32_bf16 v[94:97], v[148:151], v[202:205], v[94:97]
	v_mfma_f32_16x16x32_bf16 v[86:89], v[156:159], v[202:205], v[86:89]
	v_mfma_f32_16x16x32_bf16 v[78:81], v[148:151], v[210:213], v[78:81]
	v_mfma_f32_16x16x32_bf16 v[70:73], v[156:159], v[210:213], v[70:73]
	v_mfma_f32_16x16x32_bf16 v[122:125], v[160:163], v[176:179], 0
	v_mfma_f32_16x16x32_bf16 v[114:117], v[168:171], v[176:179], 0
	v_mfma_f32_16x16x32_bf16 v[106:109], v[160:163], v[184:187], 0
	v_mfma_f32_16x16x32_bf16 v[98:101], v[168:171], v[184:187], 0
	v_mfma_f32_16x16x32_bf16 v[90:93], v[160:163], v[192:195], 0
	v_mfma_f32_16x16x32_bf16 v[82:85], v[168:171], v[192:195], 0
	v_mfma_f32_16x16x32_bf16 v[74:77], v[160:163], v[206:209], 0
	v_mfma_f32_16x16x32_bf16 v[66:69], v[168:171], v[206:209], 0
	v_mfma_f32_16x16x32_bf16 v[122:125], v[164:167], v[180:183], v[122:125]
	v_mfma_f32_16x16x32_bf16 v[114:117], v[172:175], v[180:183], v[114:117]
	v_mfma_f32_16x16x32_bf16 v[106:109], v[164:167], v[188:191], v[106:109]
	v_mfma_f32_16x16x32_bf16 v[98:101], v[172:175], v[188:191], v[98:101]
	v_mfma_f32_16x16x32_bf16 v[90:93], v[164:167], v[202:205], v[90:93]
	v_mfma_f32_16x16x32_bf16 v[82:85], v[172:175], v[202:205], v[82:85]
	v_mfma_f32_16x16x32_bf16 v[74:77], v[164:167], v[210:213], v[74:77]
	v_mfma_f32_16x16x32_bf16 v[66:69], v[172:175], v[210:213], v[66:69]
	s_barrier
	s_setprio 0
	s_add_i32 s0, s70, s26
	s_add_u32 s98, s8, s16
	s_addc_u32 s99, s9, s17
	s_mov_b32 m0, s0
	ds_read_b128 v[176:179], v143 offset:16384
	ds_read_b128 v[180:183], v143 offset:17408
	ds_read_b128 v[184:187], v143 offset:18432
	ds_read_b128 v[188:191], v143 offset:19456
	ds_read_b128 v[192:195], v143 offset:20480
	ds_read_b128 v[202:205], v143 offset:21504
	ds_read_b128 v[206:209], v143 offset:22528
	ds_read_b128 v[210:213], v143 offset:23552
	global_load_lds_dwordx4 v196, s[8:9]
	s_add_i32 m0, s0, 0x2000
	s_add_u32 s0, s8, 0x80000
	s_addc_u32 s1, s9, 0
	s_add_i32 s70, s71, s26
	global_load_lds_dwordx4 v130, s[8:9]
	s_mov_b32 m0, s70
	s_nop 0
	global_load_lds_dwordx4 v196, s[0:1]
	s_add_i32 m0, s70, 0x2000
	s_nop 0
	global_load_lds_dwordx4 v130, s[0:1]
	s_add_u32 s78, s58, s16
	s_addc_u32 s79, s59, s17
	s_mov_b32 m0, s27
	s_nop 0
	global_load_lds_dwordx4 v134, s[58:59]
	s_mov_b32 m0, s28
	s_nop 0
	global_load_lds_dwordx4 v132, s[58:59]
	s_waitcnt vmcnt(8)
	s_waitcnt lgkmcnt(0)
	s_setprio 1
	s_barrier
	v_mfma_f32_16x16x32_bf16 v[62:65], v[144:147], v[176:179], 0
	v_mfma_f32_16x16x32_bf16 v[54:57], v[152:155], v[176:179], 0
	v_mfma_f32_16x16x32_bf16 v[46:49], v[144:147], v[184:187], 0
	v_mfma_f32_16x16x32_bf16 v[38:41], v[152:155], v[184:187], 0
	v_mfma_f32_16x16x32_bf16 v[30:33], v[144:147], v[192:195], 0
	v_mfma_f32_16x16x32_bf16 v[22:25], v[152:155], v[192:195], 0
	v_mfma_f32_16x16x32_bf16 v[14:17], v[144:147], v[206:209], 0
	v_mfma_f32_16x16x32_bf16 v[6:9], v[152:155], v[206:209], 0
	v_mfma_f32_16x16x32_bf16 v[62:65], v[148:151], v[180:183], v[62:65]
	v_mfma_f32_16x16x32_bf16 v[54:57], v[156:159], v[180:183], v[54:57]
	v_mfma_f32_16x16x32_bf16 v[46:49], v[148:151], v[188:191], v[46:49]
	v_mfma_f32_16x16x32_bf16 v[38:41], v[156:159], v[188:191], v[38:41]
	v_mfma_f32_16x16x32_bf16 v[30:33], v[148:151], v[202:205], v[30:33]
	v_mfma_f32_16x16x32_bf16 v[22:25], v[156:159], v[202:205], v[22:25]
	v_mfma_f32_16x16x32_bf16 v[14:17], v[148:151], v[210:213], v[14:17]
	v_mfma_f32_16x16x32_bf16 v[6:9], v[156:159], v[210:213], v[6:9]
	v_mfma_f32_16x16x32_bf16 v[58:61], v[160:163], v[176:179], 0
	v_mfma_f32_16x16x32_bf16 v[50:53], v[168:171], v[176:179], 0
	v_mfma_f32_16x16x32_bf16 v[42:45], v[160:163], v[184:187], 0
	v_mfma_f32_16x16x32_bf16 v[34:37], v[168:171], v[184:187], 0
	v_mfma_f32_16x16x32_bf16 v[26:29], v[160:163], v[192:195], 0
	v_mfma_f32_16x16x32_bf16 v[18:21], v[168:171], v[192:195], 0
	v_mfma_f32_16x16x32_bf16 v[10:13], v[160:163], v[206:209], 0
	v_mfma_f32_16x16x32_bf16 v[2:5], v[168:171], v[206:209], 0
	v_mfma_f32_16x16x32_bf16 v[58:61], v[164:167], v[180:183], v[58:61]
	v_mfma_f32_16x16x32_bf16 v[50:53], v[172:175], v[180:183], v[50:53]
	v_mfma_f32_16x16x32_bf16 v[42:45], v[164:167], v[188:191], v[42:45]
	v_mfma_f32_16x16x32_bf16 v[34:37], v[172:175], v[188:191], v[34:37]
	v_mfma_f32_16x16x32_bf16 v[26:29], v[164:167], v[202:205], v[26:29]
	v_mfma_f32_16x16x32_bf16 v[18:21], v[172:175], v[202:205], v[18:21]
	v_mfma_f32_16x16x32_bf16 v[10:13], v[164:167], v[210:213], v[10:13]
	v_mfma_f32_16x16x32_bf16 v[2:5], v[172:175], v[210:213], v[2:5]
	s_barrier
	s_setprio 0
	s_branch .Lkmid_5
.LBB0_2507:
	s_add_i32 s69, s8, 2
	s_add_u32 s0, s52, 0xfff80080
	s_addc_u32 s1, s53, -1
	s_add_i32 s70, 0, 0x10000
	s_cmp_eq_u32 s66, s8
	s_cselect_b32 s59, s41, s1
	s_cselect_b32 s58, s45, s0
	s_cselect_b32 s9, s43, s68
	s_cselect_b32 s8, s65, s67
	s_add_i32 s71, 0, 0x14000
	ds_read_b128 v[144:147], v250
	ds_read_b128 v[148:151], v250 offset:1024
	ds_read_b128 v[152:155], v250 offset:2048
	ds_read_b128 v[156:159], v250 offset:3072
	ds_read_b128 v[160:163], v250 offset:16384
	ds_read_b128 v[164:167], v250 offset:17408
	ds_read_b128 v[168:171], v250 offset:18432
	ds_read_b128 v[172:175], v250 offset:19456
	s_add_i32 m0, s27, 0xc000
	ds_read_b128 v[176:179], v143
	ds_read_b128 v[180:183], v143 offset:1024
	ds_read_b128 v[184:187], v143 offset:2048
	ds_read_b128 v[188:191], v143 offset:3072
	ds_read_b128 v[192:195], v143 offset:4096
	ds_read_b128 v[202:205], v143 offset:5120
	ds_read_b128 v[206:209], v143 offset:6144
	ds_read_b128 v[210:213], v143 offset:7168
	global_load_lds_dwordx4 v138, s[52:53]
	s_add_i32 m0, s27, 0xe000
	s_nop 0
	global_load_lds_dwordx4 v136, s[52:53]
	s_waitcnt vmcnt(8)
	s_waitcnt lgkmcnt(0)
	s_setprio 1
	s_barrier
	v_mfma_f32_16x16x32_bf16 v[126:129], v[144:147], v[176:179], v[126:129]
	v_mfma_f32_16x16x32_bf16 v[118:121], v[152:155], v[176:179], v[118:121]
	v_mfma_f32_16x16x32_bf16 v[110:113], v[144:147], v[184:187], v[110:113]
	v_mfma_f32_16x16x32_bf16 v[102:105], v[152:155], v[184:187], v[102:105]
	v_mfma_f32_16x16x32_bf16 v[94:97], v[144:147], v[192:195], v[94:97]
	v_mfma_f32_16x16x32_bf16 v[86:89], v[152:155], v[192:195], v[86:89]
	v_mfma_f32_16x16x32_bf16 v[78:81], v[144:147], v[206:209], v[78:81]
	v_mfma_f32_16x16x32_bf16 v[70:73], v[152:155], v[206:209], v[70:73]
	v_mfma_f32_16x16x32_bf16 v[126:129], v[148:151], v[180:183], v[126:129]
	v_mfma_f32_16x16x32_bf16 v[118:121], v[156:159], v[180:183], v[118:121]
	v_mfma_f32_16x16x32_bf16 v[110:113], v[148:151], v[188:191], v[110:113]
	v_mfma_f32_16x16x32_bf16 v[102:105], v[156:159], v[188:191], v[102:105]
	v_mfma_f32_16x16x32_bf16 v[94:97], v[148:151], v[202:205], v[94:97]
	v_mfma_f32_16x16x32_bf16 v[86:89], v[156:159], v[202:205], v[86:89]
	v_mfma_f32_16x16x32_bf16 v[78:81], v[148:151], v[210:213], v[78:81]
	v_mfma_f32_16x16x32_bf16 v[70:73], v[156:159], v[210:213], v[70:73]
	v_mfma_f32_16x16x32_bf16 v[122:125], v[160:163], v[176:179], v[122:125]
	v_mfma_f32_16x16x32_bf16 v[114:117], v[168:171], v[176:179], v[114:117]
	v_mfma_f32_16x16x32_bf16 v[106:109], v[160:163], v[184:187], v[106:109]
	v_mfma_f32_16x16x32_bf16 v[98:101], v[168:171], v[184:187], v[98:101]
	v_mfma_f32_16x16x32_bf16 v[90:93], v[160:163], v[192:195], v[90:93]
	v_mfma_f32_16x16x32_bf16 v[82:85], v[168:171], v[192:195], v[82:85]
	v_mfma_f32_16x16x32_bf16 v[74:77], v[160:163], v[206:209], v[74:77]
	v_mfma_f32_16x16x32_bf16 v[66:69], v[168:171], v[206:209], v[66:69]
	v_mfma_f32_16x16x32_bf16 v[122:125], v[164:167], v[180:183], v[122:125]
	v_mfma_f32_16x16x32_bf16 v[114:117], v[172:175], v[180:183], v[114:117]
	v_mfma_f32_16x16x32_bf16 v[106:109], v[164:167], v[188:191], v[106:109]
	v_mfma_f32_16x16x32_bf16 v[98:101], v[172:175], v[188:191], v[98:101]
	v_mfma_f32_16x16x32_bf16 v[90:93], v[164:167], v[202:205], v[90:93]
	v_mfma_f32_16x16x32_bf16 v[82:85], v[172:175], v[202:205], v[82:85]
	v_mfma_f32_16x16x32_bf16 v[74:77], v[164:167], v[210:213], v[74:77]
	v_mfma_f32_16x16x32_bf16 v[66:69], v[172:175], v[210:213], v[66:69]
	s_barrier
	s_setprio 0
	s_add_i32 s0, s70, s26
	s_add_u32 s98, s8, s16
	s_addc_u32 s99, s9, s17
	s_mov_b32 m0, s0
	ds_read_b128 v[176:179], v143 offset:16384
	ds_read_b128 v[180:183], v143 offset:17408
	ds_read_b128 v[184:187], v143 offset:18432
	ds_read_b128 v[188:191], v143 offset:19456
	ds_read_b128 v[192:195], v143 offset:20480
	ds_read_b128 v[202:205], v143 offset:21504
	ds_read_b128 v[206:209], v143 offset:22528
	ds_read_b128 v[210:213], v143 offset:23552
	global_load_lds_dwordx4 v196, s[8:9]
	s_add_i32 m0, s0, 0x2000
	s_add_u32 s0, s8, 0x80000
	s_addc_u32 s1, s9, 0
	s_add_i32 s70, s71, s26
	global_load_lds_dwordx4 v130, s[8:9]
	s_mov_b32 m0, s70
	s_nop 0
	global_load_lds_dwordx4 v196, s[0:1]
	s_add_i32 m0, s70, 0x2000
	s_nop 0
	global_load_lds_dwordx4 v130, s[0:1]
	s_add_u32 s78, s58, s16
	s_addc_u32 s79, s59, s17
	s_mov_b32 m0, s27
	s_nop 0
	global_load_lds_dwordx4 v134, s[58:59]
	s_mov_b32 m0, s28
	s_nop 0
	global_load_lds_dwordx4 v132, s[58:59]
	s_waitcnt vmcnt(8)
	s_waitcnt lgkmcnt(0)
	s_setprio 1
	s_barrier
	v_mfma_f32_16x16x32_bf16 v[62:65], v[144:147], v[176:179], v[62:65]
	v_mfma_f32_16x16x32_bf16 v[54:57], v[152:155], v[176:179], v[54:57]
	v_mfma_f32_16x16x32_bf16 v[46:49], v[144:147], v[184:187], v[46:49]
	v_mfma_f32_16x16x32_bf16 v[38:41], v[152:155], v[184:187], v[38:41]
	v_mfma_f32_16x16x32_bf16 v[30:33], v[144:147], v[192:195], v[30:33]
	v_mfma_f32_16x16x32_bf16 v[22:25], v[152:155], v[192:195], v[22:25]
	v_mfma_f32_16x16x32_bf16 v[14:17], v[144:147], v[206:209], v[14:17]
	v_mfma_f32_16x16x32_bf16 v[6:9], v[152:155], v[206:209], v[6:9]
	v_mfma_f32_16x16x32_bf16 v[62:65], v[148:151], v[180:183], v[62:65]
	v_mfma_f32_16x16x32_bf16 v[54:57], v[156:159], v[180:183], v[54:57]
	v_mfma_f32_16x16x32_bf16 v[46:49], v[148:151], v[188:191], v[46:49]
	v_mfma_f32_16x16x32_bf16 v[38:41], v[156:159], v[188:191], v[38:41]
	v_mfma_f32_16x16x32_bf16 v[30:33], v[148:151], v[202:205], v[30:33]
	v_mfma_f32_16x16x32_bf16 v[22:25], v[156:159], v[202:205], v[22:25]
	v_mfma_f32_16x16x32_bf16 v[14:17], v[148:151], v[210:213], v[14:17]
	v_mfma_f32_16x16x32_bf16 v[6:9], v[156:159], v[210:213], v[6:9]
	v_mfma_f32_16x16x32_bf16 v[58:61], v[160:163], v[176:179], v[58:61]
	v_mfma_f32_16x16x32_bf16 v[50:53], v[168:171], v[176:179], v[50:53]
	v_mfma_f32_16x16x32_bf16 v[42:45], v[160:163], v[184:187], v[42:45]
	v_mfma_f32_16x16x32_bf16 v[34:37], v[168:171], v[184:187], v[34:37]
	v_mfma_f32_16x16x32_bf16 v[26:29], v[160:163], v[192:195], v[26:29]
	v_mfma_f32_16x16x32_bf16 v[18:21], v[168:171], v[192:195], v[18:21]
	v_mfma_f32_16x16x32_bf16 v[10:13], v[160:163], v[206:209], v[10:13]
	v_mfma_f32_16x16x32_bf16 v[2:5], v[168:171], v[206:209], v[2:5]
	v_mfma_f32_16x16x32_bf16 v[58:61], v[164:167], v[180:183], v[58:61]
	v_mfma_f32_16x16x32_bf16 v[50:53], v[172:175], v[180:183], v[50:53]
	v_mfma_f32_16x16x32_bf16 v[42:45], v[164:167], v[188:191], v[42:45]
	v_mfma_f32_16x16x32_bf16 v[34:37], v[172:175], v[188:191], v[34:37]
	v_mfma_f32_16x16x32_bf16 v[26:29], v[164:167], v[202:205], v[26:29]
	v_mfma_f32_16x16x32_bf16 v[18:21], v[172:175], v[202:205], v[18:21]
	v_mfma_f32_16x16x32_bf16 v[10:13], v[164:167], v[210:213], v[10:13]
	v_mfma_f32_16x16x32_bf16 v[2:5], v[172:175], v[210:213], v[2:5]
	s_barrier
	s_setprio 0
.Lkmid_5:
	s_add_i32 s70, 0, 0x18000
	s_add_i32 s71, 0, 0x1c000
	ds_read_b128 v[144:147], v250 offset:32768
	ds_read_b128 v[148:151], v250 offset:33792
	ds_read_b128 v[152:155], v250 offset:34816
	ds_read_b128 v[156:159], v250 offset:35840
	ds_read_b128 v[160:163], v250 offset:49152
	ds_read_b128 v[164:167], v250 offset:50176
	ds_read_b128 v[168:171], v250 offset:51200
	ds_read_b128 v[172:175], v250 offset:52224
	s_add_u32 s0, s58, 0x80000
	s_addc_u32 s1, s59, 0
	s_mov_b32 m0, s29
	ds_read_b128 v[176:179], v143 offset:32768
	ds_read_b128 v[180:183], v143 offset:33792
	ds_read_b128 v[184:187], v143 offset:34816
	ds_read_b128 v[188:191], v143 offset:35840
	ds_read_b128 v[192:195], v143 offset:36864
	ds_read_b128 v[202:205], v143 offset:37888
	ds_read_b128 v[206:209], v143 offset:38912
	ds_read_b128 v[210:213], v143 offset:39936
	global_load_lds_dwordx4 v134, s[0:1]
	s_mov_b32 m0, s30
	s_nop 0
	global_load_lds_dwordx4 v132, s[0:1]
	s_waitcnt vmcnt(8)
	s_waitcnt lgkmcnt(0)
	s_setprio 1
	s_barrier
	v_mfma_f32_16x16x32_bf16 v[126:129], v[144:147], v[176:179], v[126:129]
	v_mfma_f32_16x16x32_bf16 v[118:121], v[152:155], v[176:179], v[118:121]
	v_mfma_f32_16x16x32_bf16 v[110:113], v[144:147], v[184:187], v[110:113]
	v_mfma_f32_16x16x32_bf16 v[102:105], v[152:155], v[184:187], v[102:105]
	v_mfma_f32_16x16x32_bf16 v[94:97], v[144:147], v[192:195], v[94:97]
	v_mfma_f32_16x16x32_bf16 v[86:89], v[152:155], v[192:195], v[86:89]
	v_mfma_f32_16x16x32_bf16 v[78:81], v[144:147], v[206:209], v[78:81]
	v_mfma_f32_16x16x32_bf16 v[70:73], v[152:155], v[206:209], v[70:73]
	v_mfma_f32_16x16x32_bf16 v[126:129], v[148:151], v[180:183], v[126:129]
	v_mfma_f32_16x16x32_bf16 v[118:121], v[156:159], v[180:183], v[118:121]
	v_mfma_f32_16x16x32_bf16 v[110:113], v[148:151], v[188:191], v[110:113]
	v_mfma_f32_16x16x32_bf16 v[102:105], v[156:159], v[188:191], v[102:105]
	v_mfma_f32_16x16x32_bf16 v[94:97], v[148:151], v[202:205], v[94:97]
	v_mfma_f32_16x16x32_bf16 v[86:89], v[156:159], v[202:205], v[86:89]
	v_mfma_f32_16x16x32_bf16 v[78:81], v[148:151], v[210:213], v[78:81]
	v_mfma_f32_16x16x32_bf16 v[70:73], v[156:159], v[210:213], v[70:73]
	v_mfma_f32_16x16x32_bf16 v[122:125], v[160:163], v[176:179], v[122:125]
	v_mfma_f32_16x16x32_bf16 v[114:117], v[168:171], v[176:179], v[114:117]
	v_mfma_f32_16x16x32_bf16 v[106:109], v[160:163], v[184:187], v[106:109]
	v_mfma_f32_16x16x32_bf16 v[98:101], v[168:171], v[184:187], v[98:101]
	v_mfma_f32_16x16x32_bf16 v[90:93], v[160:163], v[192:195], v[90:93]
	v_mfma_f32_16x16x32_bf16 v[82:85], v[168:171], v[192:195], v[82:85]
	v_mfma_f32_16x16x32_bf16 v[74:77], v[160:163], v[206:209], v[74:77]
	v_mfma_f32_16x16x32_bf16 v[66:69], v[168:171], v[206:209], v[66:69]
	v_mfma_f32_16x16x32_bf16 v[122:125], v[164:167], v[180:183], v[122:125]
	v_mfma_f32_16x16x32_bf16 v[114:117], v[172:175], v[180:183], v[114:117]
	v_mfma_f32_16x16x32_bf16 v[106:109], v[164:167], v[188:191], v[106:109]
	v_mfma_f32_16x16x32_bf16 v[98:101], v[172:175], v[188:191], v[98:101]
	v_mfma_f32_16x16x32_bf16 v[90:93], v[164:167], v[202:205], v[90:93]
	v_mfma_f32_16x16x32_bf16 v[82:85], v[172:175], v[202:205], v[82:85]
	v_mfma_f32_16x16x32_bf16 v[74:77], v[164:167], v[210:213], v[74:77]
	v_mfma_f32_16x16x32_bf16 v[66:69], v[172:175], v[210:213], v[66:69]
	s_barrier
	s_setprio 0
	s_add_i32 s0, s70, s26
	s_mov_b32 m0, s0
	ds_read_b128 v[176:179], v143 offset:49152
	ds_read_b128 v[180:183], v143 offset:50176
	ds_read_b128 v[184:187], v143 offset:51200
	ds_read_b128 v[188:191], v143 offset:52224
	ds_read_b128 v[192:195], v143 offset:53248
	ds_read_b128 v[202:205], v143 offset:54272
	ds_read_b128 v[206:209], v143 offset:55296
	ds_read_b128 v[210:213], v143 offset:56320
	global_load_lds_dwordx4 v196, s[98:99]
	s_add_i32 m0, s0, 0x2000
	s_add_u32 s0, s8, 0x80080
	s_addc_u32 s1, s9, 0
	s_add_i32 s8, s71, s26
	global_load_lds_dwordx4 v130, s[98:99]
	s_mov_b32 m0, s8
	s_nop 0
	global_load_lds_dwordx4 v196, s[0:1]
	s_add_i32 m0, s8, 0x2000
	s_nop 0
	global_load_lds_dwordx4 v130, s[0:1]
	s_mov_b32 m0, s31
	s_nop 0
	global_load_lds_dwordx4 v134, s[78:79]
	s_mov_b32 m0, s34
	s_nop 0
	global_load_lds_dwordx4 v132, s[78:79]
	s_waitcnt vmcnt(8)
	s_waitcnt lgkmcnt(0)
	s_setprio 1
	s_barrier
	v_mfma_f32_16x16x32_bf16 v[62:65], v[144:147], v[176:179], v[62:65]
	v_mfma_f32_16x16x32_bf16 v[54:57], v[152:155], v[176:179], v[54:57]
	v_mfma_f32_16x16x32_bf16 v[46:49], v[144:147], v[184:187], v[46:49]
	v_mfma_f32_16x16x32_bf16 v[38:41], v[152:155], v[184:187], v[38:41]
	v_mfma_f32_16x16x32_bf16 v[30:33], v[144:147], v[192:195], v[30:33]
	v_mfma_f32_16x16x32_bf16 v[22:25], v[152:155], v[192:195], v[22:25]
	v_mfma_f32_16x16x32_bf16 v[14:17], v[144:147], v[206:209], v[14:17]
	v_mfma_f32_16x16x32_bf16 v[6:9], v[152:155], v[206:209], v[6:9]
	v_mfma_f32_16x16x32_bf16 v[62:65], v[148:151], v[180:183], v[62:65]
	v_mfma_f32_16x16x32_bf16 v[54:57], v[156:159], v[180:183], v[54:57]
	v_mfma_f32_16x16x32_bf16 v[46:49], v[148:151], v[188:191], v[46:49]
	v_mfma_f32_16x16x32_bf16 v[38:41], v[156:159], v[188:191], v[38:41]
	v_mfma_f32_16x16x32_bf16 v[30:33], v[148:151], v[202:205], v[30:33]
	v_mfma_f32_16x16x32_bf16 v[22:25], v[156:159], v[202:205], v[22:25]
	v_mfma_f32_16x16x32_bf16 v[14:17], v[148:151], v[210:213], v[14:17]
	v_mfma_f32_16x16x32_bf16 v[6:9], v[156:159], v[210:213], v[6:9]
	v_mfma_f32_16x16x32_bf16 v[58:61], v[160:163], v[176:179], v[58:61]
	v_mfma_f32_16x16x32_bf16 v[50:53], v[168:171], v[176:179], v[50:53]
	v_mfma_f32_16x16x32_bf16 v[42:45], v[160:163], v[184:187], v[42:45]
	v_mfma_f32_16x16x32_bf16 v[34:37], v[168:171], v[184:187], v[34:37]
	v_mfma_f32_16x16x32_bf16 v[26:29], v[160:163], v[192:195], v[26:29]
	v_mfma_f32_16x16x32_bf16 v[18:21], v[168:171], v[192:195], v[18:21]
	v_mfma_f32_16x16x32_bf16 v[10:13], v[160:163], v[206:209], v[10:13]
	v_mfma_f32_16x16x32_bf16 v[2:5], v[168:171], v[206:209], v[2:5]
	v_mfma_f32_16x16x32_bf16 v[58:61], v[164:167], v[180:183], v[58:61]
	v_mfma_f32_16x16x32_bf16 v[50:53], v[172:175], v[180:183], v[50:53]
	v_mfma_f32_16x16x32_bf16 v[42:45], v[164:167], v[188:191], v[42:45]
	v_mfma_f32_16x16x32_bf16 v[34:37], v[172:175], v[188:191], v[34:37]
	v_mfma_f32_16x16x32_bf16 v[26:29], v[164:167], v[202:205], v[26:29]
	v_mfma_f32_16x16x32_bf16 v[18:21], v[172:175], v[202:205], v[18:21]
	v_mfma_f32_16x16x32_bf16 v[10:13], v[164:167], v[210:213], v[10:13]
	v_mfma_f32_16x16x32_bf16 v[2:5], v[172:175], v[210:213], v[2:5]
	s_barrier
	s_setprio 0
	s_add_u32 s67, s67, 0x100
	s_addc_u32 s68, s68, 0
	s_add_u32 s52, s52, 0x100
	s_addc_u32 s53, s53, 0
	s_cmp_ge_i32 s69, s62
	s_mov_b32 s8, s69
	s_cbranch_scc0 .LBB0_2507
	s_and_b64 vcc, exec, s[38:39]
	s_cbranch_vccz .LBB0_2510
	s_barrier

.Ldefbar_skip_6:
	v_add_u32_e32 v250, 0x10000, v188
	s_add_i32 s72, s48, 2
	s_add_u32 s8, s46, 0x100
	s_addc_u32 s9, s47, 0
	s_add_i32 s0, 0, 0x10000
	s_cmp_eq_u32 s41, s48
	s_cselect_b32 s51, s43, s9
	s_cselect_b32 s50, s42, s8
	s_cselect_b32 s49, s45, s71
	s_cselect_b32 s48, s44, s70
	s_add_i32 s73, 0, 0x14000
	ds_read_b128 v[130:133], v250
	ds_read_b128 v[134:137], v250 offset:1024
	ds_read_b128 v[138:141], v250 offset:2048
	ds_read_b128 v[142:145], v250 offset:3072
	ds_read_b128 v[146:149], v250 offset:16384
	ds_read_b128 v[164:167], v250 offset:17408
	ds_read_b128 v[168:171], v250 offset:18432
	ds_read_b128 v[172:175], v250 offset:19456
	v_lshl_add_u64 v[194:195], s[46:47], 0, v[162:163]
	s_add_i32 m0, s27, 0xc000
	ds_read_b128 v[176:179], v189
	ds_read_b128 v[180:183], v189 offset:1024
	ds_read_b128 v[184:187], v189 offset:2048
	ds_read_b128 v[190:193], v189 offset:3072
	ds_read_b128 v[202:205], v189 offset:4096
	ds_read_b128 v[206:209], v189 offset:5120
	ds_read_b128 v[210:213], v189 offset:6144
	ds_read_b128 v[214:217], v189 offset:7168
	global_load_lds_dwordx4 v[194:195], off
	v_lshl_add_u64 v[194:195], s[46:47], 0, v[160:161]
	s_add_i32 m0, s27, 0xe000
	s_nop 0
	global_load_lds_dwordx4 v[194:195], off
	s_waitcnt vmcnt(8)
	s_waitcnt lgkmcnt(0)
	s_setprio 1
	s_barrier
	v_mfma_f32_16x16x32_bf16 v[126:129], v[130:133], v[176:179], 0
	v_mfma_f32_16x16x32_bf16 v[122:125], v[138:141], v[176:179], 0
	v_mfma_f32_16x16x32_bf16 v[110:113], v[130:133], v[184:187], 0
	v_mfma_f32_16x16x32_bf16 v[106:109], v[138:141], v[184:187], 0
	v_mfma_f32_16x16x32_bf16 v[98:101], v[130:133], v[202:205], 0
	v_mfma_f32_16x16x32_bf16 v[90:93], v[138:141], v[202:205], 0
	v_mfma_f32_16x16x32_bf16 v[82:85], v[130:133], v[210:213], 0
	v_mfma_f32_16x16x32_bf16 v[74:77], v[138:141], v[210:213], 0
	v_mfma_f32_16x16x32_bf16 v[126:129], v[134:137], v[180:183], v[126:129]
	v_mfma_f32_16x16x32_bf16 v[122:125], v[142:145], v[180:183], v[122:125]
	v_mfma_f32_16x16x32_bf16 v[110:113], v[134:137], v[190:193], v[110:113]
	v_mfma_f32_16x16x32_bf16 v[106:109], v[142:145], v[190:193], v[106:109]
	v_mfma_f32_16x16x32_bf16 v[98:101], v[134:137], v[206:209], v[98:101]
	v_mfma_f32_16x16x32_bf16 v[90:93], v[142:145], v[206:209], v[90:93]
	v_mfma_f32_16x16x32_bf16 v[82:85], v[134:137], v[214:217], v[82:85]
	v_mfma_f32_16x16x32_bf16 v[74:77], v[142:145], v[214:217], v[74:77]
	v_mfma_f32_16x16x32_bf16 v[118:121], v[146:149], v[176:179], 0
	v_mfma_f32_16x16x32_bf16 v[114:117], v[168:171], v[176:179], 0
	v_mfma_f32_16x16x32_bf16 v[102:105], v[146:149], v[184:187], 0
	v_mfma_f32_16x16x32_bf16 v[94:97], v[168:171], v[184:187], 0
	v_mfma_f32_16x16x32_bf16 v[86:89], v[146:149], v[202:205], 0
	v_mfma_f32_16x16x32_bf16 v[78:81], v[168:171], v[202:205], 0
	v_mfma_f32_16x16x32_bf16 v[70:73], v[146:149], v[210:213], 0
	v_mfma_f32_16x16x32_bf16 v[66:69], v[168:171], v[210:213], 0
	v_mfma_f32_16x16x32_bf16 v[118:121], v[164:167], v[180:183], v[118:121]
	v_mfma_f32_16x16x32_bf16 v[114:117], v[172:175], v[180:183], v[114:117]
	v_mfma_f32_16x16x32_bf16 v[102:105], v[164:167], v[190:193], v[102:105]
	v_mfma_f32_16x16x32_bf16 v[94:97], v[172:175], v[190:193], v[94:97]
	v_mfma_f32_16x16x32_bf16 v[86:89], v[164:167], v[206:209], v[86:89]
	v_mfma_f32_16x16x32_bf16 v[78:81], v[172:175], v[206:209], v[78:81]
	v_mfma_f32_16x16x32_bf16 v[70:73], v[164:167], v[214:217], v[70:73]
	v_mfma_f32_16x16x32_bf16 v[66:69], v[172:175], v[214:217], v[66:69]
	s_barrier
	s_setprio 0
	s_add_i32 s0, s0, s26
	s_add_u32 s98, s48, s16
	s_addc_u32 s99, s49, s17
	s_mov_b32 m0, s0
	ds_read_b128 v[176:179], v189 offset:16384
	ds_read_b128 v[180:183], v189 offset:17408
	ds_read_b128 v[184:187], v189 offset:18432
	ds_read_b128 v[190:193], v189 offset:19456
	ds_read_b128 v[202:205], v189 offset:20480
	ds_read_b128 v[206:209], v189 offset:21504
	ds_read_b128 v[210:213], v189 offset:22528
	ds_read_b128 v[214:217], v189 offset:23552
	global_load_lds_dwordx4 v196, s[48:49]
	s_add_i32 m0, s0, 0x2000
	s_add_u32 s0, s48, 0x158000
	s_addc_u32 s1, s49, 0
	s_add_i32 s46, s73, s26
	global_load_lds_dwordx4 v154, s[48:49]
	s_mov_b32 m0, s46
	s_nop 0
	global_load_lds_dwordx4 v196, s[0:1]
	s_add_i32 m0, s46, 0x2000
	s_nop 0
	global_load_lds_dwordx4 v154, s[0:1]
	s_add_u32 s78, s50, s16
	s_addc_u32 s79, s51, s17
	s_mov_b32 m0, s27
	s_nop 0
	global_load_lds_dwordx4 v150, s[50:51]
	s_mov_b32 m0, s30
	s_nop 0
	global_load_lds_dwordx4 v152, s[50:51]
	s_waitcnt vmcnt(8)
	s_waitcnt lgkmcnt(0)
	s_setprio 1
	s_barrier
	v_mfma_f32_16x16x32_bf16 v[62:65], v[130:133], v[176:179], 0
	v_mfma_f32_16x16x32_bf16 v[58:61], v[138:141], v[176:179], 0
	v_mfma_f32_16x16x32_bf16 v[50:53], v[130:133], v[184:187], 0
	v_mfma_f32_16x16x32_bf16 v[42:45], v[138:141], v[184:187], 0
	v_mfma_f32_16x16x32_bf16 v[34:37], v[130:133], v[202:205], 0
	v_mfma_f32_16x16x32_bf16 v[26:29], v[138:141], v[202:205], 0
	v_mfma_f32_16x16x32_bf16 v[18:21], v[130:133], v[210:213], 0
	v_mfma_f32_16x16x32_bf16 v[10:13], v[138:141], v[210:213], 0
	v_mfma_f32_16x16x32_bf16 v[62:65], v[134:137], v[180:183], v[62:65]
	v_mfma_f32_16x16x32_bf16 v[58:61], v[142:145], v[180:183], v[58:61]
	v_mfma_f32_16x16x32_bf16 v[50:53], v[134:137], v[190:193], v[50:53]
	v_mfma_f32_16x16x32_bf16 v[42:45], v[142:145], v[190:193], v[42:45]
	v_mfma_f32_16x16x32_bf16 v[34:37], v[134:137], v[206:209], v[34:37]
	v_mfma_f32_16x16x32_bf16 v[26:29], v[142:145], v[206:209], v[26:29]
	v_mfma_f32_16x16x32_bf16 v[18:21], v[134:137], v[214:217], v[18:21]
	v_mfma_f32_16x16x32_bf16 v[10:13], v[142:145], v[214:217], v[10:13]
	v_mfma_f32_16x16x32_bf16 v[54:57], v[146:149], v[176:179], 0
	v_mfma_f32_16x16x32_bf16 v[46:49], v[168:171], v[176:179], 0
	v_mfma_f32_16x16x32_bf16 v[38:41], v[146:149], v[184:187], 0
	v_mfma_f32_16x16x32_bf16 v[30:33], v[168:171], v[184:187], 0
	v_mfma_f32_16x16x32_bf16 v[22:25], v[146:149], v[202:205], 0
	v_mfma_f32_16x16x32_bf16 v[14:17], v[168:171], v[202:205], 0
	v_mfma_f32_16x16x32_bf16 v[6:9], v[146:149], v[210:213], 0
	v_mfma_f32_16x16x32_bf16 v[2:5], v[168:171], v[210:213], 0
	v_mfma_f32_16x16x32_bf16 v[54:57], v[164:167], v[180:183], v[54:57]
	v_mfma_f32_16x16x32_bf16 v[46:49], v[172:175], v[180:183], v[46:49]
	v_mfma_f32_16x16x32_bf16 v[38:41], v[164:167], v[190:193], v[38:41]
	v_mfma_f32_16x16x32_bf16 v[30:33], v[172:175], v[190:193], v[30:33]
	v_mfma_f32_16x16x32_bf16 v[22:25], v[164:167], v[206:209], v[22:25]
	v_mfma_f32_16x16x32_bf16 v[14:17], v[172:175], v[206:209], v[14:17]
	v_mfma_f32_16x16x32_bf16 v[6:9], v[164:167], v[214:217], v[6:9]
	v_mfma_f32_16x16x32_bf16 v[2:5], v[172:175], v[214:217], v[2:5]
	s_barrier
	s_setprio 0
	s_branch .Lkmid_6
.LBB0_2588:
	s_add_i32 s72, s48, 2
	s_add_u32 s8, s46, 0x100
	s_addc_u32 s9, s47, 0
	s_add_i32 s0, 0, 0x10000
	s_cmp_eq_u32 s41, s48
	s_cselect_b32 s51, s43, s9
	s_cselect_b32 s50, s42, s8
	s_cselect_b32 s49, s45, s71
	s_cselect_b32 s48, s44, s70
	s_add_i32 s73, 0, 0x14000
	ds_read_b128 v[130:133], v250
	ds_read_b128 v[134:137], v250 offset:1024
	ds_read_b128 v[138:141], v250 offset:2048
	ds_read_b128 v[142:145], v250 offset:3072
	ds_read_b128 v[146:149], v250 offset:16384
	ds_read_b128 v[164:167], v250 offset:17408
	ds_read_b128 v[168:171], v250 offset:18432
	ds_read_b128 v[172:175], v250 offset:19456
	v_lshl_add_u64 v[194:195], s[46:47], 0, v[162:163]
	s_add_i32 m0, s27, 0xc000
	ds_read_b128 v[176:179], v189
	ds_read_b128 v[180:183], v189 offset:1024
	ds_read_b128 v[184:187], v189 offset:2048
	ds_read_b128 v[190:193], v189 offset:3072
	ds_read_b128 v[202:205], v189 offset:4096
	ds_read_b128 v[206:209], v189 offset:5120
	ds_read_b128 v[210:213], v189 offset:6144
	ds_read_b128 v[214:217], v189 offset:7168
	global_load_lds_dwordx4 v[194:195], off
	v_lshl_add_u64 v[194:195], s[46:47], 0, v[160:161]
	s_add_i32 m0, s27, 0xe000
	s_nop 0
	global_load_lds_dwordx4 v[194:195], off
	s_waitcnt vmcnt(8)
	s_waitcnt lgkmcnt(0)
	s_setprio 1
	s_barrier
	v_mfma_f32_16x16x32_bf16 v[126:129], v[130:133], v[176:179], v[126:129]
	v_mfma_f32_16x16x32_bf16 v[122:125], v[138:141], v[176:179], v[122:125]
	v_mfma_f32_16x16x32_bf16 v[110:113], v[130:133], v[184:187], v[110:113]
	v_mfma_f32_16x16x32_bf16 v[106:109], v[138:141], v[184:187], v[106:109]
	v_mfma_f32_16x16x32_bf16 v[98:101], v[130:133], v[202:205], v[98:101]
	v_mfma_f32_16x16x32_bf16 v[90:93], v[138:141], v[202:205], v[90:93]
	v_mfma_f32_16x16x32_bf16 v[82:85], v[130:133], v[210:213], v[82:85]
	v_mfma_f32_16x16x32_bf16 v[74:77], v[138:141], v[210:213], v[74:77]
	v_mfma_f32_16x16x32_bf16 v[126:129], v[134:137], v[180:183], v[126:129]
	v_mfma_f32_16x16x32_bf16 v[122:125], v[142:145], v[180:183], v[122:125]
	v_mfma_f32_16x16x32_bf16 v[110:113], v[134:137], v[190:193], v[110:113]
	v_mfma_f32_16x16x32_bf16 v[106:109], v[142:145], v[190:193], v[106:109]
	v_mfma_f32_16x16x32_bf16 v[98:101], v[134:137], v[206:209], v[98:101]
	v_mfma_f32_16x16x32_bf16 v[90:93], v[142:145], v[206:209], v[90:93]
	v_mfma_f32_16x16x32_bf16 v[82:85], v[134:137], v[214:217], v[82:85]
	v_mfma_f32_16x16x32_bf16 v[74:77], v[142:145], v[214:217], v[74:77]
	v_mfma_f32_16x16x32_bf16 v[118:121], v[146:149], v[176:179], v[118:121]
	v_mfma_f32_16x16x32_bf16 v[114:117], v[168:171], v[176:179], v[114:117]
	v_mfma_f32_16x16x32_bf16 v[102:105], v[146:149], v[184:187], v[102:105]
	v_mfma_f32_16x16x32_bf16 v[94:97], v[168:171], v[184:187], v[94:97]
	v_mfma_f32_16x16x32_bf16 v[86:89], v[146:149], v[202:205], v[86:89]
	v_mfma_f32_16x16x32_bf16 v[78:81], v[168:171], v[202:205], v[78:81]
	v_mfma_f32_16x16x32_bf16 v[70:73], v[146:149], v[210:213], v[70:73]
	v_mfma_f32_16x16x32_bf16 v[66:69], v[168:171], v[210:213], v[66:69]
	v_mfma_f32_16x16x32_bf16 v[118:121], v[164:167], v[180:183], v[118:121]
	v_mfma_f32_16x16x32_bf16 v[114:117], v[172:175], v[180:183], v[114:117]
	v_mfma_f32_16x16x32_bf16 v[102:105], v[164:167], v[190:193], v[102:105]
	v_mfma_f32_16x16x32_bf16 v[94:97], v[172:175], v[190:193], v[94:97]
	v_mfma_f32_16x16x32_bf16 v[86:89], v[164:167], v[206:209], v[86:89]
	v_mfma_f32_16x16x32_bf16 v[78:81], v[172:175], v[206:209], v[78:81]
	v_mfma_f32_16x16x32_bf16 v[70:73], v[164:167], v[214:217], v[70:73]
	v_mfma_f32_16x16x32_bf16 v[66:69], v[172:175], v[214:217], v[66:69]
	s_barrier
	s_setprio 0
	s_add_i32 s0, s0, s26
	s_add_u32 s98, s48, s16
	s_addc_u32 s99, s49, s17
	s_mov_b32 m0, s0
	ds_read_b128 v[176:179], v189 offset:16384
	ds_read_b128 v[180:183], v189 offset:17408
	ds_read_b128 v[184:187], v189 offset:18432
	ds_read_b128 v[190:193], v189 offset:19456
	ds_read_b128 v[202:205], v189 offset:20480
	ds_read_b128 v[206:209], v189 offset:21504
	ds_read_b128 v[210:213], v189 offset:22528
	ds_read_b128 v[214:217], v189 offset:23552
	global_load_lds_dwordx4 v196, s[48:49]
	s_add_i32 m0, s0, 0x2000
	s_add_u32 s0, s48, 0x158000
	s_addc_u32 s1, s49, 0
	s_add_i32 s46, s73, s26
	global_load_lds_dwordx4 v154, s[48:49]
	s_mov_b32 m0, s46
	s_nop 0
	global_load_lds_dwordx4 v196, s[0:1]
	s_add_i32 m0, s46, 0x2000
	s_nop 0
	global_load_lds_dwordx4 v154, s[0:1]
	s_add_u32 s78, s50, s16
	s_addc_u32 s79, s51, s17
	s_mov_b32 m0, s27
	s_nop 0
	global_load_lds_dwordx4 v150, s[50:51]
	s_mov_b32 m0, s30
	s_nop 0
	global_load_lds_dwordx4 v152, s[50:51]
	s_waitcnt vmcnt(8)
	s_waitcnt lgkmcnt(0)
	s_setprio 1
	s_barrier
	v_mfma_f32_16x16x32_bf16 v[62:65], v[130:133], v[176:179], v[62:65]
	v_mfma_f32_16x16x32_bf16 v[58:61], v[138:141], v[176:179], v[58:61]
	v_mfma_f32_16x16x32_bf16 v[50:53], v[130:133], v[184:187], v[50:53]
	v_mfma_f32_16x16x32_bf16 v[42:45], v[138:141], v[184:187], v[42:45]
	v_mfma_f32_16x16x32_bf16 v[34:37], v[130:133], v[202:205], v[34:37]
	v_mfma_f32_16x16x32_bf16 v[26:29], v[138:141], v[202:205], v[26:29]
	v_mfma_f32_16x16x32_bf16 v[18:21], v[130:133], v[210:213], v[18:21]
	v_mfma_f32_16x16x32_bf16 v[10:13], v[138:141], v[210:213], v[10:13]
	v_mfma_f32_16x16x32_bf16 v[62:65], v[134:137], v[180:183], v[62:65]
	v_mfma_f32_16x16x32_bf16 v[58:61], v[142:145], v[180:183], v[58:61]
	v_mfma_f32_16x16x32_bf16 v[50:53], v[134:137], v[190:193], v[50:53]
	v_mfma_f32_16x16x32_bf16 v[42:45], v[142:145], v[190:193], v[42:45]
	v_mfma_f32_16x16x32_bf16 v[34:37], v[134:137], v[206:209], v[34:37]
	v_mfma_f32_16x16x32_bf16 v[26:29], v[142:145], v[206:209], v[26:29]
	v_mfma_f32_16x16x32_bf16 v[18:21], v[134:137], v[214:217], v[18:21]
	v_mfma_f32_16x16x32_bf16 v[10:13], v[142:145], v[214:217], v[10:13]
	v_mfma_f32_16x16x32_bf16 v[54:57], v[146:149], v[176:179], v[54:57]
	v_mfma_f32_16x16x32_bf16 v[46:49], v[168:171], v[176:179], v[46:49]
	v_mfma_f32_16x16x32_bf16 v[38:41], v[146:149], v[184:187], v[38:41]
	v_mfma_f32_16x16x32_bf16 v[30:33], v[168:171], v[184:187], v[30:33]
	v_mfma_f32_16x16x32_bf16 v[22:25], v[146:149], v[202:205], v[22:25]
	v_mfma_f32_16x16x32_bf16 v[14:17], v[168:171], v[202:205], v[14:17]
	v_mfma_f32_16x16x32_bf16 v[6:9], v[146:149], v[210:213], v[6:9]
	v_mfma_f32_16x16x32_bf16 v[2:5], v[168:171], v[210:213], v[2:5]
	v_mfma_f32_16x16x32_bf16 v[54:57], v[164:167], v[180:183], v[54:57]
	v_mfma_f32_16x16x32_bf16 v[46:49], v[172:175], v[180:183], v[46:49]
	v_mfma_f32_16x16x32_bf16 v[38:41], v[164:167], v[190:193], v[38:41]
	v_mfma_f32_16x16x32_bf16 v[30:33], v[172:175], v[190:193], v[30:33]
	v_mfma_f32_16x16x32_bf16 v[22:25], v[164:167], v[206:209], v[22:25]
	v_mfma_f32_16x16x32_bf16 v[14:17], v[172:175], v[206:209], v[14:17]
	v_mfma_f32_16x16x32_bf16 v[6:9], v[164:167], v[214:217], v[6:9]
	v_mfma_f32_16x16x32_bf16 v[2:5], v[172:175], v[214:217], v[2:5]
	s_barrier
	s_setprio 0
.Lkmid_6:
	s_add_i32 s46, 0, 0x18000
	s_add_i32 s47, 0, 0x1c000
	ds_read_b128 v[130:133], v250 offset:32768
	ds_read_b128 v[134:137], v250 offset:33792
	ds_read_b128 v[138:141], v250 offset:34816
	ds_read_b128 v[142:145], v250 offset:35840
	ds_read_b128 v[146:149], v250 offset:49152
	ds_read_b128 v[164:167], v250 offset:50176
	ds_read_b128 v[168:171], v250 offset:51200
	ds_read_b128 v[172:175], v250 offset:52224
	s_add_u32 s0, s50, 0x158000
	s_addc_u32 s1, s51, 0
	s_mov_b32 m0, s31
	ds_read_b128 v[176:179], v189 offset:32768
	ds_read_b128 v[180:183], v189 offset:33792
	ds_read_b128 v[184:187], v189 offset:34816
	ds_read_b128 v[190:193], v189 offset:35840
	ds_read_b128 v[202:205], v189 offset:36864
	ds_read_b128 v[206:209], v189 offset:37888
	ds_read_b128 v[210:213], v189 offset:38912
	ds_read_b128 v[214:217], v189 offset:39936
	global_load_lds_dwordx4 v150, s[0:1]
	s_mov_b32 m0, s34
	s_nop 0
	global_load_lds_dwordx4 v152, s[0:1]
	s_waitcnt vmcnt(8)
	s_waitcnt lgkmcnt(0)
	s_setprio 1
	s_barrier
	v_mfma_f32_16x16x32_bf16 v[126:129], v[130:133], v[176:179], v[126:129]
	v_mfma_f32_16x16x32_bf16 v[122:125], v[138:141], v[176:179], v[122:125]
	v_mfma_f32_16x16x32_bf16 v[110:113], v[130:133], v[184:187], v[110:113]
	v_mfma_f32_16x16x32_bf16 v[106:109], v[138:141], v[184:187], v[106:109]
	v_mfma_f32_16x16x32_bf16 v[98:101], v[130:133], v[202:205], v[98:101]
	v_mfma_f32_16x16x32_bf16 v[90:93], v[138:141], v[202:205], v[90:93]
	v_mfma_f32_16x16x32_bf16 v[82:85], v[130:133], v[210:213], v[82:85]
	v_mfma_f32_16x16x32_bf16 v[74:77], v[138:141], v[210:213], v[74:77]
	v_mfma_f32_16x16x32_bf16 v[126:129], v[134:137], v[180:183], v[126:129]
	v_mfma_f32_16x16x32_bf16 v[122:125], v[142:145], v[180:183], v[122:125]
	v_mfma_f32_16x16x32_bf16 v[110:113], v[134:137], v[190:193], v[110:113]
	v_mfma_f32_16x16x32_bf16 v[106:109], v[142:145], v[190:193], v[106:109]
	v_mfma_f32_16x16x32_bf16 v[98:101], v[134:137], v[206:209], v[98:101]
	v_mfma_f32_16x16x32_bf16 v[90:93], v[142:145], v[206:209], v[90:93]
	v_mfma_f32_16x16x32_bf16 v[82:85], v[134:137], v[214:217], v[82:85]
	v_mfma_f32_16x16x32_bf16 v[74:77], v[142:145], v[214:217], v[74:77]
	v_mfma_f32_16x16x32_bf16 v[118:121], v[146:149], v[176:179], v[118:121]
	v_mfma_f32_16x16x32_bf16 v[114:117], v[168:171], v[176:179], v[114:117]
	v_mfma_f32_16x16x32_bf16 v[102:105], v[146:149], v[184:187], v[102:105]
	v_mfma_f32_16x16x32_bf16 v[94:97], v[168:171], v[184:187], v[94:97]
	v_mfma_f32_16x16x32_bf16 v[86:89], v[146:149], v[202:205], v[86:89]
	v_mfma_f32_16x16x32_bf16 v[78:81], v[168:171], v[202:205], v[78:81]
	v_mfma_f32_16x16x32_bf16 v[70:73], v[146:149], v[210:213], v[70:73]
	v_mfma_f32_16x16x32_bf16 v[66:69], v[168:171], v[210:213], v[66:69]
	v_mfma_f32_16x16x32_bf16 v[118:121], v[164:167], v[180:183], v[118:121]
	v_mfma_f32_16x16x32_bf16 v[114:117], v[172:175], v[180:183], v[114:117]
	v_mfma_f32_16x16x32_bf16 v[102:105], v[164:167], v[190:193], v[102:105]
	v_mfma_f32_16x16x32_bf16 v[94:97], v[172:175], v[190:193], v[94:97]
	v_mfma_f32_16x16x32_bf16 v[86:89], v[164:167], v[206:209], v[86:89]
	v_mfma_f32_16x16x32_bf16 v[78:81], v[172:175], v[206:209], v[78:81]
	v_mfma_f32_16x16x32_bf16 v[70:73], v[164:167], v[214:217], v[70:73]
	v_mfma_f32_16x16x32_bf16 v[66:69], v[172:175], v[214:217], v[66:69]
	s_barrier
	s_setprio 0
	s_add_i32 s0, s46, s26
	s_mov_b32 m0, s0
	ds_read_b128 v[176:179], v189 offset:49152
	ds_read_b128 v[180:183], v189 offset:50176
	ds_read_b128 v[184:187], v189 offset:51200
	ds_read_b128 v[190:193], v189 offset:52224
	ds_read_b128 v[202:205], v189 offset:53248
	ds_read_b128 v[206:209], v189 offset:54272
	ds_read_b128 v[210:213], v189 offset:55296
	ds_read_b128 v[214:217], v189 offset:56320
	global_load_lds_dwordx4 v196, s[98:99]
	s_add_i32 m0, s0, 0x2000
	s_add_u32 s0, s48, 0x158080
	s_addc_u32 s1, s49, 0
	s_add_i32 s46, s47, s26
	global_load_lds_dwordx4 v154, s[98:99]
	s_mov_b32 m0, s46
	s_nop 0
	global_load_lds_dwordx4 v196, s[0:1]
	s_add_i32 m0, s46, 0x2000
	s_nop 0
	global_load_lds_dwordx4 v154, s[0:1]
	s_mov_b32 m0, s53
	s_nop 0
	global_load_lds_dwordx4 v150, s[78:79]
	s_mov_b32 m0, s58
	s_nop 0
	global_load_lds_dwordx4 v152, s[78:79]
	s_waitcnt vmcnt(8)
	s_waitcnt lgkmcnt(0)
	s_setprio 1
	s_barrier
	v_mfma_f32_16x16x32_bf16 v[62:65], v[130:133], v[176:179], v[62:65]
	v_mfma_f32_16x16x32_bf16 v[58:61], v[138:141], v[176:179], v[58:61]
	v_mfma_f32_16x16x32_bf16 v[50:53], v[130:133], v[184:187], v[50:53]
	v_mfma_f32_16x16x32_bf16 v[42:45], v[138:141], v[184:187], v[42:45]
	v_mfma_f32_16x16x32_bf16 v[34:37], v[130:133], v[202:205], v[34:37]
	v_mfma_f32_16x16x32_bf16 v[26:29], v[138:141], v[202:205], v[26:29]
	v_mfma_f32_16x16x32_bf16 v[18:21], v[130:133], v[210:213], v[18:21]
	v_mfma_f32_16x16x32_bf16 v[10:13], v[138:141], v[210:213], v[10:13]
	v_mfma_f32_16x16x32_bf16 v[62:65], v[134:137], v[180:183], v[62:65]
	v_mfma_f32_16x16x32_bf16 v[58:61], v[142:145], v[180:183], v[58:61]
	v_mfma_f32_16x16x32_bf16 v[50:53], v[134:137], v[190:193], v[50:53]
	v_mfma_f32_16x16x32_bf16 v[42:45], v[142:145], v[190:193], v[42:45]
	v_mfma_f32_16x16x32_bf16 v[34:37], v[134:137], v[206:209], v[34:37]
	v_mfma_f32_16x16x32_bf16 v[26:29], v[142:145], v[206:209], v[26:29]
	v_mfma_f32_16x16x32_bf16 v[18:21], v[134:137], v[214:217], v[18:21]
	v_mfma_f32_16x16x32_bf16 v[10:13], v[142:145], v[214:217], v[10:13]
	v_mfma_f32_16x16x32_bf16 v[54:57], v[146:149], v[176:179], v[54:57]
	v_mfma_f32_16x16x32_bf16 v[46:49], v[168:171], v[176:179], v[46:49]
	v_mfma_f32_16x16x32_bf16 v[38:41], v[146:149], v[184:187], v[38:41]
	v_mfma_f32_16x16x32_bf16 v[30:33], v[168:171], v[184:187], v[30:33]
	v_mfma_f32_16x16x32_bf16 v[22:25], v[146:149], v[202:205], v[22:25]
	v_mfma_f32_16x16x32_bf16 v[14:17], v[168:171], v[202:205], v[14:17]
	v_mfma_f32_16x16x32_bf16 v[6:9], v[146:149], v[210:213], v[6:9]
	v_mfma_f32_16x16x32_bf16 v[2:5], v[168:171], v[210:213], v[2:5]
	v_mfma_f32_16x16x32_bf16 v[54:57], v[164:167], v[180:183], v[54:57]
	v_mfma_f32_16x16x32_bf16 v[46:49], v[172:175], v[180:183], v[46:49]
	v_mfma_f32_16x16x32_bf16 v[38:41], v[164:167], v[190:193], v[38:41]
	v_mfma_f32_16x16x32_bf16 v[30:33], v[172:175], v[190:193], v[30:33]
	v_mfma_f32_16x16x32_bf16 v[22:25], v[164:167], v[206:209], v[22:25]
	v_mfma_f32_16x16x32_bf16 v[14:17], v[172:175], v[206:209], v[14:17]
	v_mfma_f32_16x16x32_bf16 v[6:9], v[164:167], v[214:217], v[6:9]
	v_mfma_f32_16x16x32_bf16 v[2:5], v[172:175], v[214:217], v[2:5]
	s_barrier
	s_setprio 0
	s_add_u32 s70, s70, 0x100
	s_addc_u32 s71, s71, 0
	s_cmp_ge_i32 s72, s69
	s_mov_b64 s[46:47], s[8:9]
	s_mov_b32 s48, s72
	s_cbranch_scc0 .LBB0_2588
	s_and_b64 vcc, exec, s[28:29]
	s_cbranch_vccz .LBB0_2591
	s_barrier
